# P5 row loads software-pipelined one token group ahead; counted waits never leave a younger store outstanding; on top of v19
# baseline (speedup 1.0000x reference)
.LBB0_1066:
	v_lshl_add_u64 v[44:45], v[22:23], 1, s[6:7]
	s_movk_i32 s2, 0xfc00
	v_add_co_u32_e32 v30, vcc, s2, v44
	s_movk_i32 s4, 0x1000
	s_nop 0
	v_addc_co_u32_e32 v31, vcc, -1, v45, vcc
	global_load_ushort v17, v[30:31], off
	v_add_co_u32_e32 v30, vcc, s4, v44
	s_waitcnt vmcnt(0)
	v_mul_f32_e32 v16, v5, v16
	v_addc_co_u32_e32 v31, vcc, 0, v45, vcc
	v_add_co_u32_e32 v48, vcc, s14, v44
	v_fmac_f32_e32 v16, v9, v70
	s_nop 0
	v_addc_co_u32_e32 v49, vcc, 0, v45, vcc
	global_load_ushort v54, v[30:31], off offset:3072
	global_load_ushort v71, v[30:31], off
	global_load_ushort v47, v[48:49], off
	global_load_ushort v50, v[30:31], off offset:1024
	global_load_ushort v52, v[44:45], off offset:3072
	global_load_ushort v55, v[48:49], off offset:3072
	global_load_ushort v72, v[44:45], off
	v_fmac_f32_e32 v16, v7, v46
	v_mov_b32_e32 v57, 0
	v_mul_f32_e32 v32, 0xbfb8aa3b, v14
	v_exp_f32_e32 v62, v32
	v_mov_b32_e32 v60, 0
	v_add_co_u32_e32 v58, vcc, s12, v44
	s_mov_b64 s[2:3], 0x4000
	s_nop 0
	v_addc_co_u32_e32 v59, vcc, 0, v45, vcc
	global_load_ushort v56, v[44:45], off offset:1024
	global_load_ushort v69, v[58:59], off
	global_load_ushort v53, v[58:59], off offset:1024
	global_load_ushort v51, v[48:49], off offset:1024
	v_add_f32_e32 v48, 1.0, v62
	v_mov_b32_e32 v61, 0
	v_lshl_add_u64 v[32:33], v[44:45], 0, s[2:3]
	v_add_co_u32_e32 v36, vcc, s13, v44
	v_div_scale_f32 v49, s[2:3], v48, v48, 1.0
	s_movk_i32 s4, 0x5000
	v_addc_co_u32_e32 v37, vcc, 0, v45, vcc
	v_rcp_f32_e32 v62, v49
	v_add_co_u32_e32 v42, vcc, s4, v44
	s_movk_i32 s18, 0x6000
	s_nop 0
	v_addc_co_u32_e32 v43, vcc, 0, v45, vcc
	v_add_co_u32_e32 v38, vcc, s18, v44
	v_fma_f32 v67, -v49, v62, 1.0
	s_nop 0
	v_addc_co_u32_e32 v39, vcc, 0, v45, vcc
	v_div_scale_f32 v66, vcc, 1.0, v48, 1.0
	v_fmac_f32_e32 v62, v67, v62
	v_mul_f32_e32 v67, v66, v62
	v_fma_f32 v73, -v49, v67, v66
	v_lshrrev_b32_e32 v21, 3, v22
	v_lshlrev_b32_e32 v87, 1, v22
	v_fmac_f32_e32 v67, v73, v62
	s_mov_b64 s[6:7], 0x5000
	v_and_b32_e32 v64, 14, v87
	v_lshlrev_b32_e32 v65, 4, v21
	v_fma_f32 v49, -v49, v67, v66
	s_mov_b64 s[8:9], 0x6000
	s_mov_b64 s[16:17], 0x7000
	v_lshl_add_u64 v[34:35], v[44:45], 0, s[6:7]
	v_or_b32_e32 v63, v65, v64
	v_div_fmas_f32 v49, v49, v62, v67
	v_mov_b32_e32 v14, v28
	v_lshl_add_u64 v[40:41], v[44:45], 0, s[8:9]
	v_lshl_add_u64 v[30:31], v[44:45], 0, s[16:17]
	v_div_fixup_f32 v102, v49, v48, 1.0
	v_add_u32_e32 v114, s51, v63
	v_pk_mul_f32 v[14:15], v[12:13], v[14:15]
	v_readlane_b32 s6, v102, 0
	v_add_f32_e32 v14, v14, v15
	v_mov_b32_e32 v15, v12
	v_readlane_b32 s7, v102, 1
	v_readlane_b32 s8, v102, 2
	v_readlane_b32 s9, v102, 3
	v_pk_mul_f32 v[26:27], v[2:3], v[26:27] op_sel_hi:[0,1]
	v_pk_fma_f32 v[26:27], v[4:5], v[24:25], v[26:27] op_sel_hi:[0,1,1]
	v_ashrrev_i32_e32 v109, 5, v22
	v_lshlrev_b32_e32 v108, 4, v96
	s_waitcnt lgkmcnt(0)
	v_lshlrev_b32_e32 v68, 16, v17
	v_fmac_f32_e32 v16, v105, v68
	v_mul_f32_e32 v17, 0xbfb8aa3b, v16
	v_exp_f32_e32 v17, v17
	s_mov_b64 s[98:99], 0x4000
	v_lshl_add_u64 v[150:151], v[44:45], 0, s[98:99]
	global_load_ushort v156, v[150:151], off offset:-1024
	global_load_ushort v159, v[150:151], off
	global_load_ushort v160, v[150:151], off offset:1024
	s_mov_b64 s[98:99], 0x5000
	v_lshl_add_u64 v[150:151], v[44:45], 0, s[98:99]
	global_load_ushort v157, v[150:151], off offset:-1024
	global_load_ushort v158, v[150:151], off
	global_load_ushort v154, v[150:151], off offset:1024
	s_mov_b64 s[98:99], 0x6000
	v_lshl_add_u64 v[150:151], v[44:45], 0, s[98:99]
	global_load_ushort v152, v[150:151], off offset:-1024
	global_load_ushort v162, v[150:151], off offset:1024
	global_load_ushort v161, v[150:151], off
	s_mov_b64 s[98:99], 0x7000
	v_lshl_add_u64 v[150:151], v[44:45], 0, s[98:99]
	global_load_ushort v153, v[150:151], off offset:-1024
	global_load_ushort v155, v[150:151], off
	global_load_ushort v163, v[150:151], off offset:1024
	s_waitcnt vmcnt(15)
	v_lshlrev_b32_e32 v54, 16, v54
	v_add_f32_e32 v17, 1.0, v17
	v_rcp_f32_e32 v17, v17
	v_lshlrev_b32_e32 v52, 16, v52
	v_mul_f32_e32 v16, v16, v17
	v_mul_f32_e32 v17, v16, v16
	v_lshlrev_b32_e32 v56, 16, v56
	s_nop 0
	v_mov_b32_dpp v57, v17 quad_perm:[1,0,3,2] row_mask:0xf bank_mask:0xf
	v_fmac_f32_e32 v57, v16, v16
	s_nop 1
	v_add_f32_dpp v17, v57, v57 quad_perm:[2,3,0,1] row_mask:0xf bank_mask:0xf bound_ctrl:1
	s_nop 1
	v_add_f32_dpp v17, v17, v17 row_half_mirror row_mask:0xf bank_mask:0xf bound_ctrl:1
	s_nop 1
	v_add_f32_dpp v17, v17, v17 row_mirror row_mask:0xf bank_mask:0xf bound_ctrl:1
	s_nop 1
	v_mov_b32_dpp v60, v17 row_bcast:15 row_mask:0xa bank_mask:0xf
	v_add_f32_e32 v17, v17, v60
	v_lshlrev_b32_e32 v60, 16, v55
	s_nop 0
	v_mov_b32_dpp v61, v17 row_bcast:31 row_mask:0xc bank_mask:0xf
	v_add_f32_e32 v17, v17, v61
	s_nop 0
	v_readlane_b32 s2, v17, 63
	s_nop 1
	v_add_f32_e32 v17, s2, v86
	v_rsq_f32_e32 v17, v17
	s_movk_i32 s2, 0x7000
	v_mul_f32_e32 v16, v16, v17
	v_mul_f32_e32 v16, 0x3e000000, v16
	v_cvt_pk_bf16_f32 v73, v16, s0
	v_add_co_u32_e32 v16, vcc, s2, v44
	v_readlane_b32 s2, v3, 0
	s_nop 0
	v_addc_co_u32_e32 v17, vcc, 0, v45, vcc
	s_nop 0
	s_nop 0
	v_lshlrev_b32_e32 v33, 16, v71
	v_lshlrev_b32_e32 v32, 16, v72
	v_pk_mov_b32 v[30:31], v[28:29], v[32:33] op_sel:[1,0]
	v_mov_b32_e32 v38, 0
	v_pk_mul_f32 v[36:37], v[10:11], v[30:31]
	v_mul_f32_e32 v35, v5, v70
	v_add_f32_e32 v14, v36, v14
	v_add_f32_e32 v36, v14, v37
	v_mul_f32_e32 v14, 0xbfb8aa3b, v36
	v_exp_f32_e32 v14, v14
	v_fmac_f32_e32 v35, v9, v46
	v_fmac_f32_e32 v35, v7, v68
	v_pk_mul_f32 v[40:41], v[10:11], v[32:33]
	v_add_f32_e32 v14, 1.0, v14
	v_rcp_f32_e32 v37, v14
	v_mov_b32_e32 v14, v13
	v_pk_mul_f32 v[28:29], v[14:15], v[28:29]
	v_fmac_f32_e32 v35, v105, v52
	v_mul_f32_e32 v36, v36, v37
	v_mul_f32_e32 v37, v36, v36
	v_add_f32_e32 v28, v29, v28
	v_add_f32_e32 v28, v28, v40
	v_mov_b32_dpp v38, v37 quad_perm:[1,0,3,2] row_mask:0xf bank_mask:0xf
	v_fmac_f32_e32 v38, v36, v36
	v_add_f32_e32 v28, v28, v41
	v_mul_f32_e32 v29, 0xbfb8aa3b, v35
	v_add_f32_dpp v37, v38, v38 quad_perm:[2,3,0,1] row_mask:0xf bank_mask:0xf bound_ctrl:1
	v_mov_b32_e32 v38, 0
	v_exp_f32_e32 v29, v29
	v_add_f32_dpp v37, v37, v37 row_half_mirror row_mask:0xf bank_mask:0xf bound_ctrl:1
	v_mul_f32_e32 v40, 0xbfb8aa3b, v28
	v_exp_f32_e32 v40, v40
	v_add_f32_dpp v37, v37, v37 row_mirror row_mask:0xf bank_mask:0xf bound_ctrl:1
	v_mov_b32_e32 v39, s2
	v_add_f32_e32 v29, 1.0, v29
	v_mov_b32_dpp v38, v37 row_bcast:15 row_mask:0xa bank_mask:0xf
	v_add_f32_e32 v37, v37, v38
	v_mov_b32_e32 v38, 0
	v_rcp_f32_e32 v29, v29
	ds_write_b16 v114, v73
	v_mov_b32_dpp v38, v37 row_bcast:31 row_mask:0xc bank_mask:0xf
	v_add_f32_e32 v37, v37, v38
	v_mul_f32_e32 v29, v35, v29
	v_readlane_b32 s3, v37, 63
	v_mul_f32_e32 v35, v29, v29
	s_mov_b64 s[98:99], 0x8000
	v_lshl_add_u64 v[150:151], v[44:45], 0, s[98:99]
	global_load_ushort v164, v[150:151], off offset:-1024
	global_load_ushort v165, v[150:151], off
	global_load_ushort v176, v[150:151], off offset:1024
	s_mov_b64 s[98:99], 0x9000
	v_lshl_add_u64 v[150:151], v[44:45], 0, s[98:99]
	global_load_ushort v166, v[150:151], off offset:-1024
	global_load_ushort v175, v[150:151], off offset:1024
	global_load_ushort v173, v[150:151], off
	s_mov_b64 s[98:99], 0xa000
	v_lshl_add_u64 v[150:151], v[44:45], 0, s[98:99]
	global_load_ushort v167, v[150:151], off offset:-1024
	global_load_ushort v174, v[150:151], off
	s_mov_b64 s[98:99], 0xb000
	v_lshl_add_u64 v[150:151], v[44:45], 0, s[98:99]
	global_load_ushort v172, v[150:151], off offset:-1024
	s_waitcnt vmcnt(10) lgkmcnt(0)
	v_lshlrev_b32_e32 v103, 16, v152
	v_add_f32_e32 v37, s3, v86
	v_rsq_f32_e32 v38, v37
	v_mov_b32_e32 v37, s6
	v_lshlrev_b32_e32 v57, 16, v50
	v_pk_mov_b32 v[24:25], v[24:25], v[56:57] op_sel:[1,0]
	v_pk_mul_f32 v[36:37], v[36:37], v[38:39]
	v_add_f32_e32 v38, 1.0, v40
	v_rcp_f32_e32 v38, v38
	v_cvt_pk_bf16_f32 v39, v36, s0
	ds_write_b16 v114, v39 offset:4096
	v_pk_fma_f32 v[26:27], v[6:7], v[24:25], v[26:27] op_sel_hi:[0,1,1]
	v_mul_f32_e32 v28, v28, v38
	v_mov_b32_e32 v38, 0
	v_pk_fma_f32 v[26:27], v[8:9], v[56:57], v[26:27] op_sel_hi:[0,1,1]
	v_lshlrev_b32_e32 v98, 16, v153
	v_mov_b32_dpp v38, v35 quad_perm:[1,0,3,2] row_mask:0xf bank_mask:0xf
	v_fmac_f32_e32 v38, v29, v29
	v_mul_f32_e32 v34, 0xbfb8aa3b, v26
	v_exp_f32_e32 v34, v34
	v_add_f32_dpp v35, v38, v38 quad_perm:[2,3,0,1] row_mask:0xf bank_mask:0xf bound_ctrl:1
	v_mov_b32_e32 v38, 0
	v_mul_f32_e32 v88, v36, v37
	v_add_f32_dpp v35, v35, v35 row_half_mirror row_mask:0xf bank_mask:0xf bound_ctrl:1
	v_add_f32_e32 v34, 1.0, v34
	v_rcp_f32_e32 v74, v34
	v_add_f32_dpp v35, v35, v35 row_mirror row_mask:0xf bank_mask:0xf bound_ctrl:1
	v_lshlrev_b32_e32 v55, 16, v154
	v_lshlrev_b32_e32 v61, 16, v155
	v_mov_b32_dpp v38, v35 row_bcast:15 row_mask:0xa bank_mask:0xf
	v_add_f32_e32 v35, v35, v38
	v_mov_b32_e32 v38, 0
	v_mul_f32_e32 v123, v9, v98
	v_fmac_f32_e32 v123, v5, v103
	v_mov_b32_dpp v38, v35 row_bcast:31 row_mask:0xc bank_mask:0xf
	v_add_f32_e32 v35, v35, v38
	v_mov_b32_e32 v38, 0
	v_readlane_b32 s2, v35, 63
	v_mul_f32_e32 v35, v28, v28
	s_nop 0
	v_add_f32_e32 v39, s2, v86
	v_mov_b32_dpp v38, v35 quad_perm:[1,0,3,2] row_mask:0xf bank_mask:0xf
	v_fmac_f32_e32 v38, v28, v28
	v_rsq_f32_e32 v39, v39
	s_nop 0
	v_add_f32_dpp v35, v38, v38 quad_perm:[2,3,0,1] row_mask:0xf bank_mask:0xf bound_ctrl:1
	v_mov_b32_e32 v38, 0
	v_mul_f32_e32 v29, v29, v39
	v_add_f32_dpp v35, v35, v35 row_half_mirror row_mask:0xf bank_mask:0xf bound_ctrl:1
	v_mul_f32_e32 v29, 0x3e000000, v29
	v_cvt_pk_bf16_f32 v29, v29, s0
	v_add_f32_dpp v35, v35, v35 row_mirror row_mask:0xf bank_mask:0xf bound_ctrl:1
	s_nop 1
	v_mov_b32_dpp v38, v35 row_bcast:15 row_mask:0xa bank_mask:0xf
	v_add_f32_e32 v35, v35, v38
	v_mov_b32_e32 v38, 0
	s_nop 1
	v_mov_b32_dpp v38, v35 row_bcast:31 row_mask:0xc bank_mask:0xf
	v_add_f32_e32 v35, v35, v38
	s_nop 0
	v_readlane_b32 s2, v35, 63
	s_nop 1
	v_add_f32_e32 v35, s2, v86
	v_rsq_f32_e32 v38, v35
	v_xor_b32_e32 v35, 16, v65
	v_or_b32_e32 v35, v35, v64
	v_add_u32_e32 v116, s51, v35
	v_mul_f32_e32 v35, v9, v68
	v_fmac_f32_e32 v35, v5, v46
	v_fmac_f32_e32 v35, v7, v52
	v_fmac_f32_e32 v35, v105, v54
	v_mul_f32_e32 v39, 0xbfb8aa3b, v35
	v_exp_f32_e32 v39, v39
	ds_write_b16 v116, v29 offset:128
	v_readlane_b32 s2, v3, 1
	v_add_f32_e32 v29, 1.0, v39
	v_rcp_f32_e32 v40, v29
	v_mov_b32_e32 v29, s7
	v_mov_b32_e32 v39, s2
	v_pk_mul_f32 v[38:39], v[28:29], v[38:39]
	v_mul_f32_e32 v28, v35, v40
	v_mul_f32_e32 v29, v28, v28
	v_mov_b32_e32 v35, 0
	v_pk_mul_f32 v[40:41], v[14:15], v[30:31]
	v_mul_f32_e32 v90, v38, v39
	v_mov_b32_dpp v35, v29 quad_perm:[1,0,3,2] row_mask:0xf bank_mask:0xf
	v_fmac_f32_e32 v35, v28, v28
	v_cvt_pk_bf16_f32 v36, v36, v38
	s_nop 0
	v_add_f32_dpp v29, v35, v35 quad_perm:[2,3,0,1] row_mask:0xf bank_mask:0xf bound_ctrl:1
	v_mov_b32_e32 v35, 0
	s_nop 0
	v_add_f32_dpp v29, v29, v29 row_half_mirror row_mask:0xf bank_mask:0xf bound_ctrl:1
	s_nop 1
	v_add_f32_dpp v29, v29, v29 row_mirror row_mask:0xf bank_mask:0xf bound_ctrl:1
	s_nop 1
	v_mov_b32_dpp v35, v29 row_bcast:15 row_mask:0xa bank_mask:0xf
	v_add_f32_e32 v29, v29, v35
	v_mov_b32_e32 v35, 0
	s_nop 1
	v_mov_b32_dpp v35, v29 row_bcast:31 row_mask:0xc bank_mask:0xf
	v_add_f32_e32 v29, v29, v35
	v_cvt_pk_bf16_f32 v35, v38, s0
	v_readlane_b32 s2, v29, 63
	ds_write_b16 v116, v35 offset:4224
	v_add_f32_e32 v35, v40, v41
	v_add_f32_e32 v29, s2, v86
	v_rsq_f32_e32 v29, v29
	v_mov_b32_e32 v41, 0
	v_readlane_b32 s2, v3, 2
	v_mul_f32_e32 v28, v28, v29
	v_xor_b32_e32 v29, 32, v65
	v_mul_f32_e32 v28, 0x3e000000, v28
	v_or_b32_e32 v29, v29, v64
	v_cvt_pk_bf16_f32 v28, v28, s0
	v_add_u32_e32 v115, s51, v29
	ds_write_b16 v115, v28 offset:256
	v_lshlrev_b32_e32 v29, 16, v69
	v_lshlrev_b32_e32 v28, 16, v47
	v_pk_mov_b32 v[30:31], v[32:33], v[28:29] op_sel:[1,0]
	v_mul_f32_e32 v69, v9, v52
	v_pk_mul_f32 v[42:43], v[10:11], v[30:31]
	v_fmac_f32_e32 v69, v5, v68
	v_add_f32_e32 v35, v35, v42
	v_add_f32_e32 v35, v35, v43
	v_mul_f32_e32 v40, 0xbfb8aa3b, v35
	v_exp_f32_e32 v40, v40
	v_pk_mul_f32 v[32:33], v[14:15], v[32:33]
	v_fmac_f32_e32 v69, v7, v54
	v_pk_mul_f32 v[46:47], v[10:11], v[28:29]
	v_add_f32_e32 v40, 1.0, v40
	v_rcp_f32_e32 v40, v40
	v_add_f32_e32 v32, v32, v33
	v_fmac_f32_e32 v69, v105, v60
	v_add_f32_e32 v32, v32, v46
	v_mul_f32_e32 v40, v35, v40
	v_mul_f32_e32 v35, v40, v40
	v_add_f32_e32 v32, v32, v47
	v_mul_f32_e32 v33, 0xbfb8aa3b, v69
	v_mov_b32_dpp v41, v35 quad_perm:[1,0,3,2] row_mask:0xf bank_mask:0xf
	v_fmac_f32_e32 v41, v40, v40
	v_exp_f32_e32 v33, v33
	v_mov_b32_e32 v43, s2
	v_add_f32_dpp v35, v41, v41 quad_perm:[2,3,0,1] row_mask:0xf bank_mask:0xf bound_ctrl:1
	v_mov_b32_e32 v41, 0
	v_add_f32_e32 v33, 1.0, v33
	v_add_f32_dpp v35, v35, v35 row_half_mirror row_mask:0xf bank_mask:0xf bound_ctrl:1
	v_rcp_f32_e32 v33, v33
	v_lshlrev_b32_e32 v68, 16, v156
	v_add_f32_dpp v35, v35, v35 row_mirror row_mask:0xf bank_mask:0xf bound_ctrl:1
	v_mul_f32_e32 v33, v69, v33
	s_nop 0
	v_mov_b32_dpp v41, v35 row_bcast:15 row_mask:0xa bank_mask:0xf
	v_add_f32_e32 v35, v35, v41
	v_mov_b32_e32 v41, 0
	s_nop 1
	v_mov_b32_dpp v41, v35 row_bcast:31 row_mask:0xc bank_mask:0xf
	v_add_f32_e32 v35, v35, v41
	v_mov_b32_e32 v41, s8
	v_readlane_b32 s3, v35, 63
	s_nop 1
	v_add_f32_e32 v35, s3, v86
	v_rsq_f32_e32 v42, v35
	v_mul_f32_e32 v35, 0xbfb8aa3b, v32
	v_exp_f32_e32 v35, v35
	v_pk_mul_f32 v[40:41], v[40:41], v[42:43]
	s_nop 0
	v_cvt_pk_bf16_f32 v42, v40, s0
	v_add_f32_e32 v35, 1.0, v35
	v_rcp_f32_e32 v35, v35
	ds_write_b16 v115, v42 offset:4352
	v_mov_b32_e32 v42, 0
	v_mul_f32_e32 v89, v40, v41
	v_mul_f32_e32 v32, v32, v35
	v_mul_f32_e32 v35, v33, v33
	s_nop 1
	v_mov_b32_dpp v42, v35 quad_perm:[1,0,3,2] row_mask:0xf bank_mask:0xf
	v_fmac_f32_e32 v42, v33, v33
	s_nop 1
	v_add_f32_dpp v35, v42, v42 quad_perm:[2,3,0,1] row_mask:0xf bank_mask:0xf bound_ctrl:1
	v_mov_b32_e32 v42, 0
	s_nop 0
	v_add_f32_dpp v35, v35, v35 row_half_mirror row_mask:0xf bank_mask:0xf bound_ctrl:1
	s_nop 1
	v_add_f32_dpp v35, v35, v35 row_mirror row_mask:0xf bank_mask:0xf bound_ctrl:1
	s_nop 1
	v_mov_b32_dpp v42, v35 row_bcast:15 row_mask:0xa bank_mask:0xf
	v_add_f32_e32 v35, v35, v42
	v_mov_b32_e32 v42, 0
	s_nop 1
	v_mov_b32_dpp v42, v35 row_bcast:31 row_mask:0xc bank_mask:0xf
	v_add_f32_e32 v35, v35, v42
	v_mov_b32_e32 v42, 0
	v_readlane_b32 s2, v35, 63
	v_mul_f32_e32 v35, v32, v32
	s_nop 0
	v_add_f32_e32 v43, s2, v86
	v_mov_b32_dpp v42, v35 quad_perm:[1,0,3,2] row_mask:0xf bank_mask:0xf
	v_fmac_f32_e32 v42, v32, v32
	v_rsq_f32_e32 v43, v43
	s_nop 0
	v_add_f32_dpp v35, v42, v42 quad_perm:[2,3,0,1] row_mask:0xf bank_mask:0xf bound_ctrl:1
	v_mov_b32_e32 v42, 0
	v_mul_f32_e32 v33, v33, v43
	v_add_f32_dpp v35, v35, v35 row_half_mirror row_mask:0xf bank_mask:0xf bound_ctrl:1
	v_mul_f32_e32 v33, 0x3e000000, v33
	v_cvt_pk_bf16_f32 v33, v33, s0
	v_add_f32_dpp v35, v35, v35 row_mirror row_mask:0xf bank_mask:0xf bound_ctrl:1
	s_nop 1
	v_mov_b32_dpp v42, v35 row_bcast:15 row_mask:0xa bank_mask:0xf
	v_add_f32_e32 v35, v35, v42
	v_mov_b32_e32 v42, 0
	s_nop 1
	v_mov_b32_dpp v42, v35 row_bcast:31 row_mask:0xc bank_mask:0xf
	v_add_f32_e32 v35, v35, v42
	s_nop 0
	v_readlane_b32 s2, v35, 63
	s_nop 1
	v_add_f32_e32 v35, s2, v86
	v_rsq_f32_e32 v42, v35
	v_xor_b32_e32 v35, 48, v65
	v_or_b32_e32 v35, v35, v64
	v_add_u32_e32 v117, s51, v35
	v_readlane_b32 s2, v3, 3
	ds_write_b16 v117, v33 offset:384
	v_mov_b32_e32 v33, s9
	v_mov_b32_e32 v43, s2
	v_pk_mul_f32 v[46:47], v[32:33], v[42:43]
	v_mul_f32_e32 v35, 0xbfb8aa3b, v27
	v_cvt_pk_bf16_f32 v32, v46, s0
	ds_write_b16 v117, v32 offset:4480
	v_exp_f32_e32 v35, v35
	s_mov_b32 s2, 0x8000
	v_add_co_u32_e32 v70, vcc, s2, v44
	v_add_f32_e32 v34, 1.0, v35
	v_rcp_f32_e32 v75, v34
	v_lshlrev_b32_e32 v35, 16, v53
	v_lshlrev_b32_e32 v34, 16, v51
	v_pk_mul_f32 v[50:51], v[4:5], v[56:57] op_sel_hi:[0,1]
	v_pk_fma_f32 v[24:25], v[2:3], v[24:25], v[50:51] op_sel_hi:[0,1,1]
	v_pk_mov_b32 v[50:51], v[56:57], v[34:35] op_sel:[1,0]
	v_lshl_or_b32 v16, v109, 11, v108
	v_pk_fma_f32 v[24:25], v[6:7], v[50:51], v[24:25] op_sel_hi:[0,1,1]
	v_addc_co_u32_e32 v71, vcc, 0, v45, vcc
	s_mov_b32 s2, 0x9000
	v_ashrrev_i32_e32 v17, 31, v16
	v_pk_fma_f32 v[56:57], v[8:9], v[34:35], v[24:25] op_sel_hi:[0,1,1]
	v_add_co_u32_e32 v72, vcc, s2, v44
	v_lshl_add_u64 v[42:43], s[0:1], 0, v[16:17]
	s_mov_b64 s[2:3], 0x2800
	v_mul_f32_e32 v24, 0xbfb8aa3b, v56
	v_addc_co_u32_e32 v73, vcc, 0, v45, vcc
	v_lshl_add_u64 v[16:17], v[42:43], 0, s[2:3]
	s_mov_b32 s2, 0xa000
	v_exp_f32_e32 v37, v24
	v_add_co_u32_e32 v48, vcc, s2, v44
	v_lshlrev_b32_e32 v32, 16, v157
	s_nop 0
	v_addc_co_u32_e32 v49, vcc, 0, v45, vcc
	v_mul_f32_e32 v24, 0xbfb8aa3b, v57
	v_exp_f32_e32 v53, v24
	v_pk_mul_f32 v[24:25], v[26:27], v[74:75]
	v_add_f32_e32 v26, 1.0, v37
	v_mul_f32_e32 v37, v9, v54
	v_fmac_f32_e32 v37, v5, v52
	v_fmac_f32_e32 v37, v7, v60
	v_fmac_f32_e32 v37, v105, v68
	v_mul_f32_e32 v39, 0xbfb8aa3b, v37
	v_exp_f32_e32 v39, v39
	v_add_f32_e32 v27, 1.0, v53
	v_mov_b32_e32 v53, 0
	v_rcp_f32_e32 v26, v26
	v_rcp_f32_e32 v27, v27
	v_mul_f32_e32 v91, v46, v47
	v_pk_mul_f32 v[24:25], v[24:25], s[6:7]
	v_pk_mul_f32 v[26:27], v[56:57], v[26:27]
	v_readlane_b32 s6, v102, 4
	v_readlane_b32 s7, v102, 5
	v_pk_mul_f32 v[26:27], v[26:27], s[8:9]
	s_mov_b64 s[98:99], 0xa000
	v_lshl_add_u64 v[150:151], v[44:45], 0, s[98:99]
	global_load_ushort v183, v[150:151], off offset:1024
	s_mov_b64 s[98:99], 0xb000
	v_lshl_add_u64 v[150:151], v[44:45], 0, s[98:99]
	global_load_ushort v182, v[150:151], off offset:1024
	global_load_ushort v181, v[150:151], off
	s_mov_b64 s[98:99], 0xc000
	v_lshl_add_u64 v[150:151], v[44:45], 0, s[98:99]
	global_load_ushort v179, v[150:151], off offset:-1024
	global_load_ushort v184, v[150:151], off
	global_load_ushort v186, v[150:151], off offset:1024
	s_mov_b64 s[98:99], 0xd000
	v_lshl_add_u64 v[150:151], v[44:45], 0, s[98:99]
	global_load_ushort v177, v[150:151], off offset:-1024
	global_load_ushort v187, v[150:151], off
	global_load_ushort v185, v[150:151], off offset:1024
	s_mov_b64 s[98:99], 0xe000
	v_lshl_add_u64 v[150:151], v[44:45], 0, s[98:99]
	global_load_ushort v178, v[150:151], off offset:-1024
	global_load_ushort v191, v[150:151], off offset:1024
	global_load_ushort v188, v[150:151], off
	s_mov_b64 s[98:99], 0xf000
	v_lshl_add_u64 v[150:151], v[44:45], 0, s[98:99]
	global_load_ushort v180, v[150:151], off offset:-1024
	global_load_ushort v189, v[150:151], off
	global_load_ushort v190, v[150:151], off offset:1024
	s_waitcnt vmcnt(15) lgkmcnt(0)
	v_lshlrev_b32_e32 v100, 16, v164
	v_add_f32_e32 v33, 1.0, v39
	v_rcp_f32_e32 v52, v33
	v_fmac_f32_e32 v123, v7, v100
	v_mul_f32_e32 v52, v37, v52
	v_mul_f32_e32 v37, v52, v52
	v_lshlrev_b32_e32 v33, 16, v165
	s_nop 0
	v_mov_b32_dpp v53, v37 quad_perm:[1,0,3,2] row_mask:0xf bank_mask:0xf
	v_fmac_f32_e32 v53, v52, v52
	v_lshlrev_b32_e32 v41, 16, v166
	v_fmac_f32_e32 v123, v105, v41
	v_add_f32_dpp v37, v53, v53 quad_perm:[2,3,0,1] row_mask:0xf bank_mask:0xf bound_ctrl:1
	v_mov_b32_e32 v53, 0
	v_lshlrev_b32_e32 v39, 16, v167
	v_add_f32_dpp v37, v37, v37 row_half_mirror row_mask:0xf bank_mask:0xf bound_ctrl:1
	v_mul_f32_e32 v132, v9, v39
	v_fmac_f32_e32 v132, v5, v41
	v_add_f32_dpp v37, v37, v37 row_mirror row_mask:0xf bank_mask:0xf bound_ctrl:1
	s_nop 1
	v_mov_b32_dpp v53, v37 row_bcast:15 row_mask:0xa bank_mask:0xf
	v_add_f32_e32 v37, v37, v53
	v_mov_b32_e32 v53, 0
	s_nop 1
	v_mov_b32_dpp v53, v37 row_bcast:31 row_mask:0xc bank_mask:0xf
	v_add_f32_e32 v37, v37, v53
	s_nop 0
	v_readlane_b32 s2, v37, 63
	s_nop 1
	v_add_f32_e32 v37, s2, v86
	v_rsq_f32_e32 v53, v37
	s_mov_b32 s2, 0xb000
	v_add_co_u32_e32 v56, vcc, s2, v44
	v_readlane_b32 s2, v3, 4
	s_nop 0
	v_addc_co_u32_e32 v57, vcc, 0, v45, vcc
	v_pk_mul_f32 v[48:49], v[14:15], v[30:31]
	v_mul_f32_e32 v30, v52, v53
	v_xor_b32_e32 v31, 64, v65
	v_mul_f32_e32 v30, 0x3e000000, v30
	v_or_b32_e32 v31, v31, v64
	v_cvt_pk_bf16_f32 v30, v30, s0
	v_add_u32_e32 v118, s51, v31
	ds_write_b16 v118, v30 offset:512
	v_lshlrev_b32_e32 v31, 16, v158
	v_lshlrev_b32_e32 v30, 16, v159
	v_pk_mov_b32 v[52:53], v[28:29], v[30:31] op_sel:[1,0]
	v_add_f32_e32 v48, v48, v49
	v_pk_mul_f32 v[70:71], v[10:11], v[52:53]
	v_mul_f32_e32 v59, v9, v60
	v_add_f32_e32 v48, v48, v70
	v_add_f32_e32 v48, v48, v71
	v_mul_f32_e32 v49, 0xbfb8aa3b, v48
	v_exp_f32_e32 v49, v49
	v_fmac_f32_e32 v59, v5, v54
	v_mov_b32_e32 v54, 0
	v_pk_mul_f32 v[28:29], v[14:15], v[28:29]
	v_add_f32_e32 v49, 1.0, v49
	v_rcp_f32_e32 v49, v49
	v_mov_b32_e32 v71, s2
	v_fmac_f32_e32 v59, v7, v68
	v_add_f32_e32 v28, v28, v29
	v_mul_f32_e32 v48, v48, v49
	v_mul_f32_e32 v49, v48, v48
	v_fmac_f32_e32 v59, v105, v32
	v_mul_f32_e32 v29, 0xbfb8aa3b, v59
	v_mov_b32_dpp v54, v49 quad_perm:[1,0,3,2] row_mask:0xf bank_mask:0xf
	v_fmac_f32_e32 v54, v48, v48
	v_exp_f32_e32 v29, v29
	v_lshlrev_b32_e32 v37, 16, v172
	v_add_f32_dpp v49, v54, v54 quad_perm:[2,3,0,1] row_mask:0xf bank_mask:0xf bound_ctrl:1
	v_mov_b32_e32 v54, 0
	v_add_f32_e32 v29, 1.0, v29
	v_add_f32_dpp v49, v49, v49 row_half_mirror row_mask:0xf bank_mask:0xf bound_ctrl:1
	v_rcp_f32_e32 v29, v29
	v_fmac_f32_e32 v132, v7, v37
	v_add_f32_dpp v49, v49, v49 row_mirror row_mask:0xf bank_mask:0xf bound_ctrl:1
	v_mul_f32_e32 v29, v59, v29
	s_nop 0
	v_mov_b32_dpp v54, v49 row_bcast:15 row_mask:0xa bank_mask:0xf
	v_add_f32_e32 v49, v49, v54
	v_mov_b32_e32 v54, 0
	s_nop 1
	v_mov_b32_dpp v54, v49 row_bcast:31 row_mask:0xc bank_mask:0xf
	v_add_f32_e32 v49, v49, v54
	s_nop 0
	v_readlane_b32 s3, v49, 63
	s_nop 1
	v_add_f32_e32 v49, s3, v86
	v_rsq_f32_e32 v70, v49
	v_mov_b32_e32 v49, s6
	v_readlane_b32 s3, v3, 6
	v_pk_mul_f32 v[48:49], v[48:49], v[70:71]
	v_pk_mul_f32 v[70:71], v[10:11], v[30:31]
	v_mul_f32_e32 v92, v48, v49
	v_add_f32_e32 v28, v28, v70
	v_add_f32_e32 v28, v28, v71
	v_mul_f32_e32 v54, 0xbfb8aa3b, v28
	v_exp_f32_e32 v54, v54
	v_mov_b32_e32 v49, 0
	v_cvt_pk_bf16_f32 v63, v48, s0
	ds_write_b16 v118, v63 offset:4608
	v_add_f32_e32 v54, 1.0, v54
	v_rcp_f32_e32 v54, v54
	v_mov_b32_e32 v71, s7
	v_mul_f32_e32 v70, v28, v54
	v_mul_f32_e32 v28, v29, v29
	s_nop 1
	v_mov_b32_dpp v49, v28 quad_perm:[1,0,3,2] row_mask:0xf bank_mask:0xf
	v_fmac_f32_e32 v49, v29, v29
	s_nop 1
	v_add_f32_dpp v28, v49, v49 quad_perm:[2,3,0,1] row_mask:0xf bank_mask:0xf bound_ctrl:1
	v_mov_b32_e32 v49, 0
	s_nop 0
	v_add_f32_dpp v28, v28, v28 row_half_mirror row_mask:0xf bank_mask:0xf bound_ctrl:1
	s_nop 1
	v_add_f32_dpp v28, v28, v28 row_mirror row_mask:0xf bank_mask:0xf bound_ctrl:1
	s_nop 1
	v_mov_b32_dpp v49, v28 row_bcast:15 row_mask:0xa bank_mask:0xf
	v_add_f32_e32 v28, v28, v49
	v_mov_b32_e32 v49, 0
	s_nop 1
	v_mov_b32_dpp v49, v28 row_bcast:31 row_mask:0xc bank_mask:0xf
	v_add_f32_e32 v28, v28, v49
	v_mov_b32_e32 v49, 0
	v_readlane_b32 s2, v28, 63
	v_mul_f32_e32 v28, v70, v70
	s_nop 0
	v_add_f32_e32 v54, s2, v86
	v_mov_b32_dpp v49, v28 quad_perm:[1,0,3,2] row_mask:0xf bank_mask:0xf
	v_fmac_f32_e32 v49, v70, v70
	v_rsq_f32_e32 v54, v54
	s_nop 0
	v_add_f32_dpp v28, v49, v49 quad_perm:[2,3,0,1] row_mask:0xf bank_mask:0xf bound_ctrl:1
	v_mov_b32_e32 v49, 0
	s_nop 0
	v_add_f32_dpp v28, v28, v28 row_half_mirror row_mask:0xf bank_mask:0xf bound_ctrl:1
	s_nop 1
	v_add_f32_dpp v28, v28, v28 row_mirror row_mask:0xf bank_mask:0xf bound_ctrl:1
	s_nop 1
	v_mov_b32_dpp v49, v28 row_bcast:15 row_mask:0xa bank_mask:0xf
	v_add_f32_e32 v28, v28, v49
	v_mov_b32_e32 v49, 0
	s_nop 1
	v_mov_b32_dpp v49, v28 row_bcast:31 row_mask:0xc bank_mask:0xf
	v_add_f32_e32 v28, v28, v49
	v_mul_f32_e32 v49, v9, v68
	v_readlane_b32 s2, v28, 63
	v_mul_f32_e32 v28, v29, v54
	v_mul_f32_e32 v28, 0x3e000000, v28
	v_add_f32_e32 v29, s2, v86
	v_rsq_f32_e32 v72, v29
	v_xor_b32_e32 v29, 0x50, v65
	v_or_b32_e32 v29, v29, v64
	v_cvt_pk_bf16_f32 v28, v28, s0
	v_add_u32_e32 v119, s51, v29
	ds_write_b16 v119, v28 offset:640
	v_lshlrev_b32_e32 v54, 16, v160
	v_pk_mul_f32 v[28:29], v[4:5], v[34:35] op_sel_hi:[0,1]
	v_pk_fma_f32 v[28:29], v[2:3], v[50:51], v[28:29] op_sel_hi:[0,1,1]
	v_pk_mov_b32 v[58:59], v[34:35], v[54:55] op_sel:[1,0]
	v_fmac_f32_e32 v49, v5, v60
	v_pk_fma_f32 v[28:29], v[6:7], v[58:59], v[28:29] op_sel_hi:[0,1,1]
	v_pk_fma_f32 v[28:29], v[8:9], v[54:55], v[28:29] op_sel_hi:[0,1,1]
	v_mul_f32_e32 v34, 0xbfb8aa3b, v28
	v_mul_f32_e32 v35, 0xbfb8aa3b, v29
	v_exp_f32_e32 v34, v34
	v_exp_f32_e32 v35, v35
	v_fmac_f32_e32 v49, v7, v32
	v_fmac_f32_e32 v49, v105, v103
	v_add_f32_e32 v34, 1.0, v34
	v_add_f32_e32 v35, 1.0, v35
	v_mul_f32_e32 v50, 0xbfb8aa3b, v49
	v_rcp_f32_e32 v34, v34
	v_rcp_f32_e32 v35, v35
	v_exp_f32_e32 v50, v50
	v_mov_b32_e32 v60, 0
	v_readlane_b32 s2, v3, 5
	v_pk_mul_f32 v[28:29], v[28:29], v[34:35]
	v_add_f32_e32 v34, 1.0, v50
	v_rcp_f32_e32 v34, v34
	v_mov_b32_e32 v73, s2
	v_pk_mul_f32 v[50:51], v[70:71], v[72:73]
	v_pk_mul_f32 v[28:29], v[28:29], s[6:7]
	v_mul_f32_e32 v49, v49, v34
	v_mul_f32_e32 v34, v49, v49
	v_cvt_pk_bf16_f32 v35, v50, s0
	ds_write_b16 v119, v35 offset:4736
	v_mov_b32_dpp v60, v34 quad_perm:[1,0,3,2] row_mask:0xf bank_mask:0xf
	v_fmac_f32_e32 v60, v49, v49
	v_mul_f32_e32 v93, v50, v51
	v_xor_b32_e32 v51, 0x60, v65
	v_add_f32_dpp v34, v60, v60 quad_perm:[2,3,0,1] row_mask:0xf bank_mask:0xf bound_ctrl:1
	v_mov_b32_e32 v60, 0
	v_or_b32_e32 v51, v51, v64
	v_add_f32_dpp v34, v34, v34 row_half_mirror row_mask:0xf bank_mask:0xf bound_ctrl:1
	v_add_u32_e32 v124, s51, v51
	v_mov_b32_e32 v51, 0
	v_add_f32_dpp v34, v34, v34 row_mirror row_mask:0xf bank_mask:0xf bound_ctrl:1
	v_readlane_b32 s6, v102, 12
	v_readlane_b32 s7, v102, 13
	v_mov_b32_dpp v60, v34 row_bcast:15 row_mask:0xa bank_mask:0xf
	v_add_f32_e32 v34, v34, v60
	v_mov_b32_e32 v60, 0
	s_nop 1
	v_mov_b32_dpp v60, v34 row_bcast:31 row_mask:0xc bank_mask:0xf
	v_add_f32_e32 v34, v34, v60
	s_nop 0
	v_readlane_b32 s2, v34, 63
	s_nop 1
	v_add_f32_e32 v34, s2, v86
	v_rsq_f32_e32 v60, v34
	v_pk_mul_f32 v[34:35], v[14:15], v[52:53]
	v_readlane_b32 s2, v102, 6
	v_add_f32_e32 v34, v34, v35
	v_mul_f32_e32 v49, v49, v60
	v_lshlrev_b32_e32 v60, 16, v161
	v_pk_mov_b32 v[62:63], v[30:31], v[60:61] op_sel:[1,0]
	v_mul_f32_e32 v49, 0x3e000000, v49
	v_pk_mul_f32 v[52:53], v[10:11], v[62:63]
	v_cvt_pk_bf16_f32 v49, v49, s0
	v_add_f32_e32 v34, v34, v52
	v_add_f32_e32 v34, v34, v53
	v_mul_f32_e32 v35, 0xbfb8aa3b, v34
	v_exp_f32_e32 v35, v35
	ds_write_b16 v124, v49 offset:768
	v_mul_f32_e32 v49, v9, v32
	v_fmac_f32_e32 v49, v5, v68
	v_add_f32_e32 v35, 1.0, v35
	v_rcp_f32_e32 v35, v35
	v_pk_mul_f32 v[30:31], v[14:15], v[30:31]
	v_mov_b32_e32 v53, s3
	v_fmac_f32_e32 v49, v7, v103
	v_mul_f32_e32 v34, v34, v35
	v_mul_f32_e32 v35, v34, v34
	v_add_f32_e32 v30, v30, v31
	v_fmac_f32_e32 v49, v105, v98
	v_mov_b32_dpp v51, v35 quad_perm:[1,0,3,2] row_mask:0xf bank_mask:0xf
	v_fmac_f32_e32 v51, v34, v34
	v_mul_f32_e32 v31, 0xbfb8aa3b, v49
	v_exp_f32_e32 v31, v31
	v_add_f32_dpp v35, v51, v51 quad_perm:[2,3,0,1] row_mask:0xf bank_mask:0xf bound_ctrl:1
	v_mov_b32_e32 v51, 0
	v_pk_mul_f32 v[76:77], v[14:15], v[62:63]
	v_add_f32_dpp v35, v35, v35 row_half_mirror row_mask:0xf bank_mask:0xf bound_ctrl:1
	v_add_f32_e32 v31, 1.0, v31
	v_rcp_f32_e32 v31, v31
	v_add_f32_dpp v35, v35, v35 row_mirror row_mask:0xf bank_mask:0xf bound_ctrl:1
	v_mul_f32_e32 v31, v49, v31
	s_nop 0
	v_mov_b32_dpp v51, v35 row_bcast:15 row_mask:0xa bank_mask:0xf
	v_add_f32_e32 v35, v35, v51
	v_mov_b32_e32 v51, 0
	s_nop 1
	v_mov_b32_dpp v51, v35 row_bcast:31 row_mask:0xc bank_mask:0xf
	v_add_f32_e32 v35, v35, v51
	s_nop 0
	v_readlane_b32 s4, v35, 63
	s_nop 1
	v_add_f32_e32 v35, s4, v86
	v_rsq_f32_e32 v52, v35
	v_mov_b32_e32 v35, s2
	v_readlane_b32 s4, v3, 7
	v_pk_mul_f32 v[52:53], v[34:35], v[52:53]
	v_pk_mul_f32 v[34:35], v[10:11], v[60:61]
	v_mul_f32_e32 v94, v52, v53
	v_add_f32_e32 v30, v30, v34
	v_add_f32_e32 v30, v30, v35
	v_mul_f32_e32 v34, 0xbfb8aa3b, v30
	v_exp_f32_e32 v34, v34
	v_cvt_pk_bf16_f32 v35, v52, s0
	ds_write_b16 v124, v35 offset:4864
	v_mov_b32_e32 v71, s4
	v_add_f32_e32 v34, 1.0, v34
	v_rcp_f32_e32 v34, v34
	v_readlane_b32 s4, v3, 9
	v_mul_f32_e32 v68, v30, v34
	v_mul_f32_e32 v30, v31, v31
	v_mov_b32_e32 v34, 0
	s_nop 1
	v_mov_b32_dpp v34, v30 quad_perm:[1,0,3,2] row_mask:0xf bank_mask:0xf
	v_fmac_f32_e32 v34, v31, v31
	s_nop 1
	v_add_f32_dpp v30, v34, v34 quad_perm:[2,3,0,1] row_mask:0xf bank_mask:0xf bound_ctrl:1
	v_mov_b32_e32 v34, 0
	s_nop 0
	v_add_f32_dpp v30, v30, v30 row_half_mirror row_mask:0xf bank_mask:0xf bound_ctrl:1
	s_nop 1
	v_add_f32_dpp v30, v30, v30 row_mirror row_mask:0xf bank_mask:0xf bound_ctrl:1
	s_nop 1
	v_mov_b32_dpp v34, v30 row_bcast:15 row_mask:0xa bank_mask:0xf
	v_add_f32_e32 v30, v30, v34
	v_mov_b32_e32 v34, 0
	s_nop 1
	v_mov_b32_dpp v34, v30 row_bcast:31 row_mask:0xc bank_mask:0xf
	v_add_f32_e32 v30, v30, v34
	v_mov_b32_e32 v34, 0
	v_readlane_b32 s3, v30, 63
	v_mul_f32_e32 v30, v68, v68
	s_nop 0
	v_add_f32_e32 v35, s3, v86
	v_mov_b32_dpp v34, v30 quad_perm:[1,0,3,2] row_mask:0xf bank_mask:0xf
	v_fmac_f32_e32 v34, v68, v68
	v_rsq_f32_e32 v35, v35
	s_nop 0
	v_add_f32_dpp v30, v34, v34 quad_perm:[2,3,0,1] row_mask:0xf bank_mask:0xf bound_ctrl:1
	v_mov_b32_e32 v34, 0
	s_nop 0
	v_add_f32_dpp v30, v30, v30 row_half_mirror row_mask:0xf bank_mask:0xf bound_ctrl:1
	s_nop 1
	v_add_f32_dpp v30, v30, v30 row_mirror row_mask:0xf bank_mask:0xf bound_ctrl:1
	s_nop 1
	v_mov_b32_dpp v34, v30 row_bcast:15 row_mask:0xa bank_mask:0xf
	v_add_f32_e32 v30, v30, v34
	v_mov_b32_e32 v34, 0
	s_nop 1
	v_mov_b32_dpp v34, v30 row_bcast:31 row_mask:0xc bank_mask:0xf
	v_add_f32_e32 v30, v30, v34
	v_lshlrev_b32_e32 v34, 16, v162
	v_readlane_b32 s3, v30, 63
	v_mul_f32_e32 v30, v31, v35
	v_mul_f32_e32 v30, 0x3e000000, v30
	v_add_f32_e32 v31, s3, v86
	v_cvt_pk_bf16_f32 v49, v30, s0
	v_xor_b32_e32 v30, 0x70, v65
	v_rsq_f32_e32 v70, v31
	v_or_b32_e32 v51, v30, v64
	v_lshlrev_b32_e32 v35, 16, v163
	v_pk_mul_f32 v[30:31], v[4:5], v[54:55] op_sel_hi:[0,1]
	v_pk_fma_f32 v[30:31], v[2:3], v[58:59], v[30:31] op_sel_hi:[0,1,1]
	v_pk_mov_b32 v[58:59], v[54:55], v[34:35] op_sel:[1,0]
	v_add_u32_e32 v125, s51, v51
	v_pk_fma_f32 v[30:31], v[6:7], v[58:59], v[30:31] op_sel_hi:[0,1,1]
	v_pk_fma_f32 v[30:31], v[8:9], v[34:35], v[30:31] op_sel_hi:[0,1,1]
	v_mul_f32_e32 v53, 0xbfb8aa3b, v30
	v_exp_f32_e32 v53, v53
	v_mul_f32_e32 v54, 0xbfb8aa3b, v31
	v_exp_f32_e32 v55, v54
	v_readlane_b32 s3, v102, 7
	v_add_f32_e32 v51, 1.0, v53
	v_rcp_f32_e32 v54, v51
	v_add_f32_e32 v51, 1.0, v55
	v_rcp_f32_e32 v55, v51
	v_mov_b32_e32 v69, s3
	ds_write_b16 v125, v49 offset:896
	v_mov_b32_e32 v51, 0
	v_pk_mul_f32 v[30:31], v[30:31], v[54:55]
	v_pk_mul_f32 v[54:55], v[68:69], v[70:71]
	v_pk_mul_f32 v[30:31], v[30:31], s[2:3]
	v_cvt_pk_bf16_f32 v49, v54, s0
	ds_write_b16 v125, v49 offset:4992
	v_mul_f32_e32 v49, v9, v103
	v_fmac_f32_e32 v49, v5, v32
	v_fmac_f32_e32 v49, v7, v98
	v_fmac_f32_e32 v49, v105, v100
	v_mul_f32_e32 v32, 0xbfb8aa3b, v49
	v_exp_f32_e32 v32, v32
	s_mov_b64 s[2:3], 0xc000
	v_lshl_add_u64 v[64:65], v[44:45], 0, s[2:3]
	s_mov_b64 s[2:3], 0xd000
	v_add_f32_e32 v32, 1.0, v32
	v_rcp_f32_e32 v32, v32
	v_lshl_add_u64 v[68:69], v[44:45], 0, s[2:3]
	s_mov_b32 s2, 0xc000
	v_add_co_u32_e32 v70, vcc, s2, v44
	v_mul_f32_e32 v49, v49, v32
	v_mul_f32_e32 v32, v49, v49
	s_mov_b64 s[2:3], 0xe000
	v_addc_co_u32_e32 v71, vcc, 0, v45, vcc
	v_mov_b32_dpp v51, v32 quad_perm:[1,0,3,2] row_mask:0xf bank_mask:0xf
	v_fmac_f32_e32 v51, v49, v49
	v_lshl_add_u64 v[72:73], v[44:45], 0, s[2:3]
	s_mov_b32 s2, 0xd000
	v_add_f32_dpp v32, v51, v51 quad_perm:[2,3,0,1] row_mask:0xf bank_mask:0xf bound_ctrl:1
	v_mov_b32_e32 v51, 0
	v_add_co_u32_e32 v74, vcc, s2, v44
	v_add_f32_dpp v32, v32, v32 row_half_mirror row_mask:0xf bank_mask:0xf bound_ctrl:1
	s_mov_b64 s[2:3], 0xf000
	v_addc_co_u32_e32 v75, vcc, 0, v45, vcc
	v_add_f32_dpp v32, v32, v32 row_mirror row_mask:0xf bank_mask:0xf bound_ctrl:1
	v_lshl_add_u64 v[120:121], v[44:45], 0, s[2:3]
	s_mov_b32 s2, 0xe000
	v_mov_b32_dpp v51, v32 row_bcast:15 row_mask:0xa bank_mask:0xf
	v_add_f32_e32 v32, v32, v51
	v_mov_b32_e32 v51, 0
	v_add_co_u32_e32 v128, vcc, s2, v44
	s_nop 0
	v_mov_b32_dpp v51, v32 row_bcast:31 row_mask:0xc bank_mask:0xf
	v_add_f32_e32 v32, v32, v51
	v_addc_co_u32_e32 v129, vcc, 0, v45, vcc
	v_readlane_b32 s2, v32, 63
	v_mul_f32_e32 v95, v54, v55
	s_mov_b32 s3, 0x12000
	v_add_f32_e32 v32, s2, v86
	v_rsq_f32_e32 v51, v32
	s_mov_b32 s2, 0xf000
	v_add_co_u32_e32 v66, vcc, s2, v44
	v_mul_f32_e32 v49, v49, v51
	v_mul_f32_e32 v49, 0x3e000000, v49
	v_cvt_pk_bf16_f32 v113, v49, s0
	v_mul_f32_e32 v49, 0xbfb8aa3b, v123
	v_exp_f32_e32 v51, v49
	v_mov_b32_e32 v64, 0
	v_mov_b32_e32 v32, v61
	v_add_f32_e32 v51, 1.0, v51
	v_rcp_f32_e32 v56, v51
	v_pk_mul_f32 v[62:63], v[10:11], v[32:33]
	v_mul_f32_e32 v61, v12, v61
	v_mul_f32_e32 v69, v10, v33
	v_mul_f32_e32 v56, v123, v56
	v_mul_f32_e32 v57, v56, v56
	v_mov_b32_e32 v68, v62
	v_lshlrev_b32_e32 v62, 16, v173
	v_mov_b32_dpp v64, v57 quad_perm:[1,0,3,2] row_mask:0xf bank_mask:0xf
	v_fmac_f32_e32 v64, v56, v56
	v_mul_f32_e32 v70, v9, v100
	v_fmac_f32_e32 v70, v5, v98
	v_add_f32_dpp v57, v64, v64 quad_perm:[2,3,0,1] row_mask:0xf bank_mask:0xf bound_ctrl:1
	v_mov_b32_e32 v64, 0
	v_fmac_f32_e32 v70, v7, v41
	v_add_f32_dpp v57, v57, v57 row_half_mirror row_mask:0xf bank_mask:0xf bound_ctrl:1
	v_fmac_f32_e32 v70, v105, v39
	v_addc_co_u32_e32 v67, vcc, 0, v45, vcc
	v_add_f32_dpp v57, v57, v57 row_mirror row_mask:0xf bank_mask:0xf bound_ctrl:1
	v_mov_b32_dpp v64, v57 row_bcast:15 row_mask:0xa bank_mask:0xf
	v_add_f32_e32 v57, v57, v64
	v_mov_b32_e32 v64, 0
	ds_write_b16 v114, v113 offset:1024
	s_mov_b64 s[98:99], 0x10000
	v_lshl_add_u64 v[150:151], v[44:45], 0, s[98:99]
	global_load_ushort v192, v[150:151], off offset:-1024
	global_load_ushort v198, v[150:151], off
	global_load_ushort v199, v[150:151], off offset:1024
	s_mov_b64 s[98:99], 0x11000
	v_lshl_add_u64 v[150:151], v[44:45], 0, s[98:99]
	global_load_ushort v195, v[150:151], off offset:-1024
	global_load_ushort v197, v[150:151], off offset:1024
	global_load_ushort v200, v[150:151], off
	s_mov_b64 s[98:99], 0x12000
	v_lshl_add_u64 v[150:151], v[44:45], 0, s[98:99]
	global_load_ushort v193, v[150:151], off offset:-1024
	global_load_ushort v201, v[150:151], off
	s_mov_b64 s[98:99], 0x13000
	v_lshl_add_u64 v[150:151], v[44:45], 0, s[98:99]
	global_load_ushort v194, v[150:151], off offset:-1024
	s_waitcnt vmcnt(11) lgkmcnt(0)
	v_lshlrev_b32_e32 v107, 16, v177
	v_mov_b32_dpp v64, v57 row_bcast:31 row_mask:0xc bank_mask:0xf
	v_add_f32_e32 v57, v57, v64
	v_lshlrev_b32_e32 v121, 16, v178
	v_readlane_b32 s2, v57, 63
	s_nop 1
	v_add_f32_e32 v57, s2, v86
	v_rsq_f32_e32 v64, v57
	v_mul_f32_e32 v57, v13, v60
	v_mov_b32_e32 v60, v77
	v_mul_f32_e32 v56, v56, v64
	v_mul_f32_e32 v64, 0x3e000000, v56
	v_mov_b32_e32 v56, v76
	v_pk_add_f32 v[56:57], v[56:57], v[60:61]
	v_mul_f32_e32 v61, v11, v62
	v_pk_add_f32 v[56:57], v[56:57], v[68:69]
	v_mov_b32_e32 v60, v63
	v_pk_add_f32 v[56:57], v[56:57], v[60:61]
	v_mov_b32_e32 v63, 0
	v_mul_f32_e32 v60, 0xbfb8aa3b, v56
	v_mul_f32_e32 v61, 0xbfb8aa3b, v57
	v_exp_f32_e32 v60, v60
	v_exp_f32_e32 v61, v61
	v_pk_mul_f32 v[68:69], v[14:15], v[32:33]
	v_cvt_pk_bf16_f32 v64, v64, s0
	v_add_f32_e32 v60, 1.0, v60
	v_add_f32_e32 v61, 1.0, v61
	v_rcp_f32_e32 v60, v60
	v_rcp_f32_e32 v61, v61
	v_mul_f32_e32 v33, v13, v33
	v_mov_b32_e32 v76, 0
	v_pk_mul_f32 v[56:57], v[56:57], v[60:61]
	s_nop 0
	v_pk_mul_f32 v[60:61], v[56:57], v[56:57]
	s_nop 1
	v_add_f32_dpp v60, v60, v60 quad_perm:[1,0,3,2] row_mask:0xf bank_mask:0xf bound_ctrl:1
	v_add_f32_dpp v61, v61, v61 quad_perm:[1,0,3,2] row_mask:0xf bank_mask:0xf bound_ctrl:1
	s_nop 0
	v_add_f32_dpp v60, v60, v60 quad_perm:[2,3,0,1] row_mask:0xf bank_mask:0xf bound_ctrl:1
	v_add_f32_dpp v61, v61, v61 quad_perm:[2,3,0,1] row_mask:0xf bank_mask:0xf bound_ctrl:1
	s_nop 0
	v_add_f32_dpp v60, v60, v60 row_half_mirror row_mask:0xf bank_mask:0xf bound_ctrl:1
	v_add_f32_dpp v61, v61, v61 row_half_mirror row_mask:0xf bank_mask:0xf bound_ctrl:1
	s_nop 0
	v_add_f32_dpp v60, v60, v60 row_mirror row_mask:0xf bank_mask:0xf bound_ctrl:1
	v_add_f32_dpp v61, v61, v61 row_mirror row_mask:0xf bank_mask:0xf bound_ctrl:1
	s_nop 0
	v_mov_b32_dpp v63, v60 row_bcast:15 row_mask:0xa bank_mask:0xf
	v_add_f32_e32 v60, v60, v63
	v_mov_b32_e32 v63, 0
	s_nop 1
	v_mov_b32_dpp v63, v60 row_bcast:31 row_mask:0xc bank_mask:0xf
	v_add_f32_e32 v60, v60, v63
	v_mov_b32_e32 v63, 0
	v_readlane_b32 s2, v60, 63
	s_nop 0
	v_mov_b32_dpp v63, v61 row_bcast:15 row_mask:0xa bank_mask:0xf
	v_add_f32_e32 v61, v61, v63
	v_mov_b32_e32 v63, 0
	v_add_f32_e32 v60, s2, v86
	v_rsq_f32_e32 v60, v60
	v_mov_b32_dpp v63, v61 row_bcast:31 row_mask:0xc bank_mask:0xf
	v_add_f32_e32 v61, v61, v63
	v_mul_f32_e32 v63, 0xbfb8aa3b, v70
	v_exp_f32_e32 v71, v63
	v_readlane_b32 s2, v61, 63
	v_lshlrev_b32_e32 v63, 16, v174
	v_mul_f32_e32 v73, v10, v63
	v_add_f32_e32 v61, s2, v86
	v_rsq_f32_e32 v61, v61
	v_add_f32_e32 v32, 1.0, v71
	v_rcp_f32_e32 v32, v32
	v_mul_f32_e32 v71, v12, v62
	v_pk_mul_f32 v[56:57], v[56:57], v[60:61]
	v_mov_b32_e32 v61, 0
	v_cvt_pk_bf16_f32 v60, v56, s0
	v_mul_f32_e32 v32, v70, v32
	ds_write_b16 v114, v60 offset:5120
	ds_write_b16 v116, v64 offset:1152
	v_mul_f32_e32 v60, v32, v32
	v_lshlrev_b32_e32 v104, 16, v179
	v_lshlrev_b32_e32 v110, 16, v180
	v_mov_b32_dpp v61, v60 quad_perm:[1,0,3,2] row_mask:0xf bank_mask:0xf
	v_fmac_f32_e32 v61, v32, v32
	v_fmac_f32_e32 v132, v105, v104
	v_cvt_pk_bf16_f32 v38, v56, v57
	v_add_f32_dpp v60, v61, v61 quad_perm:[2,3,0,1] row_mask:0xf bank_mask:0xf bound_ctrl:1
	v_mov_b32_e32 v61, 0
	s_nop 0
	v_add_f32_dpp v60, v60, v60 row_half_mirror row_mask:0xf bank_mask:0xf bound_ctrl:1
	s_nop 1
	v_add_f32_dpp v60, v60, v60 row_mirror row_mask:0xf bank_mask:0xf bound_ctrl:1
	s_nop 1
	v_mov_b32_dpp v61, v60 row_bcast:15 row_mask:0xa bank_mask:0xf
	v_add_f32_e32 v60, v60, v61
	v_mov_b32_e32 v61, 0
	s_nop 1
	v_mov_b32_dpp v61, v60 row_bcast:31 row_mask:0xc bank_mask:0xf
	v_add_f32_e32 v60, v60, v61
	s_nop 0
	v_readlane_b32 s2, v60, 63
	s_nop 1
	v_add_f32_e32 v60, s2, v86
	v_rsq_f32_e32 v64, v60
	v_cvt_pk_bf16_f32 v60, v57, s0
	ds_write_b16 v116, v60 offset:5248
	v_pk_mul_f32 v[60:61], v[10:11], v[62:63]
	v_mul_f32_e32 v32, v32, v64
	v_mul_f32_e32 v64, v9, v41
	v_fmac_f32_e32 v64, v5, v100
	v_fmac_f32_e32 v64, v7, v39
	v_fmac_f32_e32 v64, v105, v37
	v_mul_f32_e32 v70, 0xbfb8aa3b, v64
	v_exp_f32_e32 v70, v70
	v_mul_f32_e32 v32, 0x3e000000, v32
	v_cvt_pk_bf16_f32 v32, v32, s0
	ds_write_b16 v115, v32 offset:1280
	v_add_f32_e32 v32, 1.0, v70
	v_rcp_f32_e32 v32, v32
	v_mov_b32_e32 v70, v69
	v_mov_b32_e32 v72, v60
	v_mul_f32_e32 v41, 0xbfb8aa3b, v132
	v_mul_f32_e32 v74, v64, v32
	v_mul_f32_e32 v32, v74, v74
	v_mov_b32_e32 v64, 0
	v_exp_f32_e32 v41, v41
	s_nop 0
	v_mov_b32_dpp v64, v32 quad_perm:[1,0,3,2] row_mask:0xf bank_mask:0xf
	v_fmac_f32_e32 v64, v74, v74
	v_add_f32_e32 v41, 1.0, v41
	v_rcp_f32_e32 v41, v41
	v_add_f32_dpp v32, v64, v64 quad_perm:[2,3,0,1] row_mask:0xf bank_mask:0xf bound_ctrl:1
	v_mov_b32_e32 v64, 0
	v_mul_f32_e32 v41, v132, v41
	v_add_f32_dpp v32, v32, v32 row_half_mirror row_mask:0xf bank_mask:0xf bound_ctrl:1
	s_nop 1
	v_add_f32_dpp v32, v32, v32 row_mirror row_mask:0xf bank_mask:0xf bound_ctrl:1
	s_nop 1
	v_mov_b32_dpp v64, v32 row_bcast:15 row_mask:0xa bank_mask:0xf
	v_add_f32_e32 v75, v32, v64
	v_mov_b32_e32 v32, v68
	v_pk_add_f32 v[32:33], v[32:33], v[70:71]
	v_lshlrev_b32_e32 v64, 16, v181
	v_pk_add_f32 v[32:33], v[32:33], v[72:73]
	v_mul_f32_e32 v69, v11, v64
	v_mov_b32_e32 v68, v61
	v_pk_add_f32 v[32:33], v[32:33], v[68:69]
	v_mov_b32_e32 v69, 0
	v_mul_f32_e32 v60, 0xbfb8aa3b, v32
	v_mul_f32_e32 v61, 0xbfb8aa3b, v33
	v_exp_f32_e32 v60, v60
	v_exp_f32_e32 v61, v61
	v_mov_b32_dpp v76, v75 row_bcast:31 row_mask:0xc bank_mask:0xf
	v_add_f32_e32 v68, v75, v76
	v_add_f32_e32 v60, 1.0, v60
	v_add_f32_e32 v61, 1.0, v61
	v_rcp_f32_e32 v60, v60
	v_rcp_f32_e32 v61, v61
	v_readlane_b32 s2, v68, 63
	v_pk_mul_f32 v[32:33], v[32:33], v[60:61]
	s_nop 0
	v_pk_mul_f32 v[60:61], v[32:33], v[32:33]
	v_add_f32_e32 v68, s2, v86
	v_rsq_f32_e32 v68, v68
	v_add_f32_dpp v60, v60, v60 quad_perm:[1,0,3,2] row_mask:0xf bank_mask:0xf bound_ctrl:1
	v_add_f32_dpp v61, v61, v61 quad_perm:[1,0,3,2] row_mask:0xf bank_mask:0xf bound_ctrl:1
	v_mul_f32_e32 v68, v74, v68
	v_add_f32_dpp v60, v60, v60 quad_perm:[2,3,0,1] row_mask:0xf bank_mask:0xf bound_ctrl:1
	v_add_f32_dpp v61, v61, v61 quad_perm:[2,3,0,1] row_mask:0xf bank_mask:0xf bound_ctrl:1
	v_mul_f32_e32 v68, 0x3e000000, v68
	v_add_f32_dpp v60, v60, v60 row_half_mirror row_mask:0xf bank_mask:0xf bound_ctrl:1
	v_add_f32_dpp v61, v61, v61 row_half_mirror row_mask:0xf bank_mask:0xf bound_ctrl:1
	v_cvt_pk_bf16_f32 v68, v68, s0
	v_add_f32_dpp v60, v60, v60 row_mirror row_mask:0xf bank_mask:0xf bound_ctrl:1
	v_add_f32_dpp v61, v61, v61 row_mirror row_mask:0xf bank_mask:0xf bound_ctrl:1
	s_nop 0
	v_mov_b32_dpp v69, v60 row_bcast:15 row_mask:0xa bank_mask:0xf
	v_add_f32_e32 v60, v60, v69
	v_mov_b32_e32 v69, 0
	s_nop 1
	v_mov_b32_dpp v69, v60 row_bcast:31 row_mask:0xc bank_mask:0xf
	v_add_f32_e32 v60, v60, v69
	v_mov_b32_e32 v69, 0
	v_readlane_b32 s2, v60, 63
	s_nop 0
	v_mov_b32_dpp v69, v61 row_bcast:15 row_mask:0xa bank_mask:0xf
	v_add_f32_e32 v61, v61, v69
	v_mov_b32_e32 v69, 0
	v_add_f32_e32 v60, s2, v86
	v_rsq_f32_e32 v60, v60
	v_mov_b32_dpp v69, v61 row_bcast:31 row_mask:0xc bank_mask:0xf
	v_add_f32_e32 v61, v61, v69
	s_nop 0
	v_readlane_b32 s2, v61, 63
	s_nop 1
	v_add_f32_e32 v61, s2, v86
	v_rsq_f32_e32 v61, v61
	s_mov_b32 s2, 0x10000
	v_add_co_u32_e32 v72, vcc, s2, v44
	v_pk_mul_f32 v[60:61], v[32:33], v[60:61]
	s_nop 0
	v_addc_co_u32_e32 v73, vcc, 0, v45, vcc
	v_cvt_pk_bf16_f32 v32, v60, s0
	ds_write_b16 v115, v32 offset:5376
	ds_write_b16 v117, v68 offset:1408
	v_cvt_pk_bf16_f32 v32, v61, s0
	ds_write_b16 v117, v32 offset:5504
	s_mov_b32 s2, 0x11000
	v_add_co_u32_e32 v76, vcc, s2, v44
	v_pk_mul_f32 v[32:33], v[4:5], v[34:35] op_sel_hi:[0,1]
	s_nop 0
	v_addc_co_u32_e32 v77, vcc, 0, v45, vcc
	v_add_co_u32_e32 v74, vcc, s3, v44
	v_lshlrev_b32_e32 v67, 16, v175
	s_nop 0
	v_addc_co_u32_e32 v75, vcc, 0, v45, vcc
	v_lshlrev_b32_e32 v66, 16, v176
	v_pk_fma_f32 v[32:33], v[2:3], v[58:59], v[32:33] op_sel_hi:[0,1,1]
	v_pk_mov_b32 v[34:35], v[34:35], v[66:67] op_sel:[1,0]
	v_readlane_b32 s3, v3, 8
	v_pk_fma_f32 v[32:33], v[6:7], v[34:35], v[32:33] op_sel_hi:[0,1,1]
	v_pk_fma_f32 v[32:33], v[8:9], v[66:67], v[32:33] op_sel_hi:[0,1,1]
	v_mul_f32_e32 v47, 0xbfb8aa3b, v32
	v_exp_f32_e32 v47, v47
	v_mul_f32_e32 v58, 0xbfb8aa3b, v33
	v_exp_f32_e32 v59, v58
	v_mov_b32_e32 v65, s3
	v_add_f32_e32 v47, 1.0, v47
	v_rcp_f32_e32 v58, v47
	v_add_f32_e32 v47, 1.0, v59
	v_rcp_f32_e32 v59, v47
	v_readlane_b32 s3, v102, 9
	v_pk_mul_f32 v[68:69], v[4:5], v[66:67] op_sel_hi:[0,1]
	v_pk_fma_f32 v[34:35], v[2:3], v[34:35], v[68:69] op_sel_hi:[0,1,1]
	v_pk_mul_f32 v[32:33], v[32:33], v[58:59]
	v_mov_b32_e32 v58, s4
	v_mul_f32_e32 v58, s3, v58
	v_mul_f32_e32 v97, v57, v58
	v_lshlrev_b32_e32 v59, 16, v182
	v_lshlrev_b32_e32 v58, 16, v183
	v_pk_mov_b32 v[70:71], v[66:67], v[58:59] op_sel:[1,0]
	v_readlane_b32 s2, v102, 8
	v_pk_fma_f32 v[34:35], v[6:7], v[70:71], v[34:35] op_sel_hi:[0,1,1]
	v_pk_fma_f32 v[34:35], v[8:9], v[58:59], v[34:35] op_sel_hi:[0,1,1]
	v_mul_f32_e32 v47, s2, v65
	v_mul_f32_e32 v98, v56, v47
	v_mul_f32_e32 v47, 0xbfb8aa3b, v34
	v_exp_f32_e32 v47, v47
	v_mul_f32_e32 v65, 0xbfb8aa3b, v35
	v_exp_f32_e32 v65, v65
	v_pk_mul_f32 v[32:33], v[32:33], s[2:3]
	v_readlane_b32 s3, v3, 10
	v_add_f32_e32 v47, 1.0, v47
	v_readlane_b32 s2, v102, 10
	v_mov_b32_e32 v68, s3
	v_rcp_f32_e32 v66, v47
	v_add_f32_e32 v47, 1.0, v65
	v_rcp_f32_e32 v67, v47
	v_mul_f32_e32 v47, s2, v68
	v_pk_mul_f32 v[68:69], v[14:15], v[62:63]
	v_mul_f32_e32 v100, v60, v47
	v_mul_f32_e32 v47, v41, v41
	v_mov_b32_e32 v62, 0
	v_readlane_b32 s4, v3, 11
	v_readlane_b32 s3, v102, 11
	v_mov_b32_dpp v62, v47 quad_perm:[1,0,3,2] row_mask:0xf bank_mask:0xf
	v_fmac_f32_e32 v62, v41, v41
	v_pk_mul_f32 v[34:35], v[34:35], v[66:67]
	v_mov_b32_e32 v65, s4
	v_add_f32_dpp v47, v62, v62 quad_perm:[2,3,0,1] row_mask:0xf bank_mask:0xf bound_ctrl:1
	v_mov_b32_e32 v62, 0
	v_pk_mul_f32 v[34:35], v[34:35], s[2:3]
	v_add_f32_dpp v47, v47, v47 row_half_mirror row_mask:0xf bank_mask:0xf bound_ctrl:1
	v_mul_f32_e32 v66, s3, v65
	s_mov_b32 s2, 0x13000
	v_add_f32_dpp v47, v47, v47 row_mirror row_mask:0xf bank_mask:0xf bound_ctrl:1
	v_mul_f32_e32 v99, v61, v66
	v_add_co_u32_e32 v66, vcc, s2, v44
	v_mov_b32_dpp v62, v47 row_bcast:15 row_mask:0xa bank_mask:0xf
	v_add_f32_e32 v47, v47, v62
	v_mov_b32_e32 v62, 0
	v_addc_co_u32_e32 v67, vcc, 0, v45, vcc
	s_nop 0
	v_mov_b32_dpp v62, v47 row_bcast:31 row_mask:0xc bank_mask:0xf
	v_add_f32_e32 v47, v47, v62
	v_mul_f32_e32 v62, v9, v37
	v_fmac_f32_e32 v62, v5, v39
	v_fmac_f32_e32 v62, v7, v104
	v_fmac_f32_e32 v62, v105, v107
	v_mul_f32_e32 v39, 0xbfb8aa3b, v62
	v_exp_f32_e32 v39, v39
	v_readlane_b32 s2, v47, 63
	v_lshlrev_b32_e32 v65, 16, v184
	v_add_f32_e32 v47, s2, v86
	v_rsq_f32_e32 v47, v47
	v_add_f32_e32 v39, 1.0, v39
	v_rcp_f32_e32 v39, v39
	s_mov_b64 s[98:99], 0x12000
	v_lshl_add_u64 v[150:151], v[44:45], 0, s[98:99]
	global_load_ushort v206, v[150:151], off offset:1024
	s_mov_b64 s[98:99], 0x13000
	v_lshl_add_u64 v[150:151], v[44:45], 0, s[98:99]
	global_load_ushort v205, v[150:151], off offset:1024
	global_load_ushort v204, v[150:151], off
	s_mov_b64 s[98:99], 0x14000
	v_lshl_add_u64 v[150:151], v[44:45], 0, s[98:99]
	global_load_ushort v202, v[150:151], off offset:-1024
	global_load_ushort v207, v[150:151], off
	global_load_ushort v209, v[150:151], off offset:1024
	s_mov_b64 s[98:99], 0x15000
	v_lshl_add_u64 v[150:151], v[44:45], 0, s[98:99]
	global_load_ushort v203, v[150:151], off offset:-1024
	global_load_ushort v210, v[150:151], off
	global_load_ushort v208, v[150:151], off offset:1024
	s_mov_b64 s[98:99], 0x16000
	v_lshl_add_u64 v[150:151], v[44:45], 0, s[98:99]
	global_load_ushort v212, v[150:151], off offset:1024
	s_mov_b64 s[98:99], 0x17000
	v_lshl_add_u64 v[150:151], v[44:45], 0, s[98:99]
	global_load_ushort v211, v[150:151], off offset:1024
	s_waitcnt vmcnt(11) lgkmcnt(0)
	v_lshlrev_b32_e32 v120, 16, v192
	v_mul_f32_e32 v41, v41, v47
	v_mul_f32_e32 v41, 0x3e000000, v41
	v_cvt_pk_bf16_f32 v41, v41, s0
	v_mul_f32_e32 v39, v62, v39
	ds_write_b16 v118, v41 offset:1536
	v_mul_f32_e32 v41, v39, v39
	v_mov_b32_e32 v47, 0
	v_mul_f32_e32 v63, v13, v63
	v_mul_f32_e32 v73, v12, v64
	v_mov_b32_dpp v47, v41 quad_perm:[1,0,3,2] row_mask:0xf bank_mask:0xf
	v_fmac_f32_e32 v47, v39, v39
	v_mov_b32_e32 v62, v68
	v_mov_b32_e32 v72, v69
	v_add_f32_dpp v41, v47, v47 quad_perm:[2,3,0,1] row_mask:0xf bank_mask:0xf bound_ctrl:1
	v_mov_b32_e32 v47, 0
	v_pk_add_f32 v[62:63], v[62:63], v[72:73]
	v_add_f32_dpp v41, v41, v41 row_half_mirror row_mask:0xf bank_mask:0xf bound_ctrl:1
	v_lshlrev_b32_e32 v69, 16, v185
	v_lshlrev_b32_e32 v68, 16, v186
	v_add_f32_dpp v41, v41, v41 row_mirror row_mask:0xf bank_mask:0xf bound_ctrl:1
	v_pk_mul_f32 v[72:73], v[4:5], v[58:59] op_sel_hi:[0,1]
	v_pk_fma_f32 v[72:73], v[2:3], v[70:71], v[72:73] op_sel_hi:[0,1,1]
	v_mov_b32_dpp v47, v41 row_bcast:15 row_mask:0xa bank_mask:0xf
	v_add_f32_e32 v41, v41, v47
	v_mov_b32_e32 v47, 0
	v_pk_mov_b32 v[70:71], v[58:59], v[68:69] op_sel:[1,0]
	v_pk_mul_f32 v[74:75], v[10:11], v[64:65]
	v_mov_b32_dpp v47, v41 row_bcast:31 row_mask:0xc bank_mask:0xf
	v_pk_fma_f32 v[58:59], v[6:7], v[70:71], v[72:73] op_sel_hi:[0,1,1]
	v_lshlrev_b32_e32 v77, 16, v193
	v_lshlrev_b32_e32 v76, 16, v194
	v_add_f32_e32 v41, v41, v47
	v_mul_f32_e32 v131, v10, v65
	v_mov_b32_e32 v130, v74
	v_pk_fma_f32 v[72:73], v[8:9], v[68:69], v[58:59] op_sel_hi:[0,1,1]
	v_lshlrev_b32_e32 v58, 16, v187
	v_readlane_b32 s3, v41, 63
	v_pk_add_f32 v[62:63], v[62:63], v[130:131]
	v_mul_f32_e32 v131, v11, v58
	v_mov_b32_e32 v130, v75
	v_add_f32_e32 v41, s3, v86
	v_pk_add_f32 v[62:63], v[62:63], v[130:131]
	v_rsq_f32_e32 v41, v41
	v_mul_f32_e32 v47, 0xbfb8aa3b, v62
	v_exp_f32_e32 v47, v47
	v_mul_f32_e32 v59, 0xbfb8aa3b, v63
	v_exp_f32_e32 v59, v59
	v_mul_f32_e32 v39, v39, v41
	v_mul_f32_e32 v41, v9, v104
	v_fmac_f32_e32 v41, v5, v37
	v_add_f32_e32 v37, 1.0, v47
	v_rcp_f32_e32 v74, v37
	v_add_f32_e32 v37, 1.0, v59
	v_rcp_f32_e32 v75, v37
	v_mov_b32_e32 v47, 0
	v_fmac_f32_e32 v41, v7, v107
	v_fmac_f32_e32 v41, v105, v121
	v_pk_mul_f32 v[62:63], v[62:63], v[74:75]
	v_mul_f32_e32 v39, 0x3e000000, v39
	v_pk_mul_f32 v[74:75], v[62:63], v[62:63]
	v_cvt_pk_bf16_f32 v39, v39, s0
	v_pk_mul_f32 v[130:131], v[14:15], v[64:65]
	v_add_f32_dpp v37, v74, v74 quad_perm:[1,0,3,2] row_mask:0xf bank_mask:0xf bound_ctrl:1
	v_lshlrev_b32_e32 v59, 16, v188
	v_mul_f32_e32 v65, v13, v65
	v_add_f32_dpp v37, v37, v37 quad_perm:[2,3,0,1] row_mask:0xf bank_mask:0xf bound_ctrl:1
	v_mul_f32_e32 v133, v12, v58
	v_mov_b32_e32 v132, v131
	v_add_f32_dpp v37, v37, v37 row_half_mirror row_mask:0xf bank_mask:0xf bound_ctrl:1
	v_mul_f32_e32 v135, v10, v59
	v_readlane_b32 s2, v3, 12
	v_add_f32_dpp v37, v37, v37 row_mirror row_mask:0xf bank_mask:0xf bound_ctrl:1
	v_readlane_b32 s4, v3, 15
	v_lshlrev_b32_e32 v78, 16, v195
	v_mov_b32_dpp v47, v37 row_bcast:15 row_mask:0xa bank_mask:0xf
	v_add_f32_e32 v37, v37, v47
	v_mov_b32_e32 v47, 0
	v_lshlrev_b32_e32 v53, 16, v197
	v_mul_f32_e32 v126, v9, v77
	v_mov_b32_dpp v47, v37 row_bcast:31 row_mask:0xc bank_mask:0xf
	v_add_f32_e32 v37, v37, v47
	v_mov_b32_e32 v47, 0
	v_readlane_b32 s3, v37, 63
	v_fmac_f32_e32 v126, v5, v78
	v_fmac_f32_e32 v126, v7, v76
	v_add_f32_e32 v37, s3, v86
	v_rsq_f32_e32 v74, v37
	s_nop 0
	v_add_f32_dpp v37, v75, v75 quad_perm:[1,0,3,2] row_mask:0xf bank_mask:0xf bound_ctrl:1
	s_nop 1
	v_add_f32_dpp v37, v37, v37 quad_perm:[2,3,0,1] row_mask:0xf bank_mask:0xf bound_ctrl:1
	s_nop 1
	v_add_f32_dpp v37, v37, v37 row_half_mirror row_mask:0xf bank_mask:0xf bound_ctrl:1
	s_nop 1
	v_add_f32_dpp v37, v37, v37 row_mirror row_mask:0xf bank_mask:0xf bound_ctrl:1
	s_nop 1
	v_mov_b32_dpp v47, v37 row_bcast:15 row_mask:0xa bank_mask:0xf
	v_add_f32_e32 v37, v37, v47
	v_mov_b32_e32 v47, 0
	s_nop 1
	v_mov_b32_dpp v47, v37 row_bcast:31 row_mask:0xc bank_mask:0xf
	v_add_f32_e32 v37, v37, v47
	s_nop 0
	v_readlane_b32 s3, v37, 63
	s_nop 1
	v_add_f32_e32 v37, s3, v86
	v_rsq_f32_e32 v75, v37
	v_mul_f32_e32 v37, 0xbfb8aa3b, v41
	v_exp_f32_e32 v37, v37
	v_pk_mul_f32 v[74:75], v[62:63], v[74:75]
	s_nop 0
	v_cvt_pk_bf16_f32 v47, v74, s0
	v_add_f32_e32 v37, 1.0, v37
	v_rcp_f32_e32 v37, v37
	ds_write_b16 v118, v47 offset:5632
	ds_write_b16 v119, v39 offset:1664
	v_mov_b32_e32 v47, 0
	v_cvt_pk_bf16_f32 v39, v75, s0
	v_mul_f32_e32 v37, v41, v37
	v_mul_f32_e32 v41, v37, v37
	ds_write_b16 v119, v39 offset:5760
	s_nop 0
	v_mov_b32_dpp v47, v41 quad_perm:[1,0,3,2] row_mask:0xf bank_mask:0xf
	v_fmac_f32_e32 v47, v37, v37
	s_nop 1
	v_add_f32_dpp v41, v47, v47 quad_perm:[2,3,0,1] row_mask:0xf bank_mask:0xf bound_ctrl:1
	v_mov_b32_e32 v47, 0
	s_nop 0
	v_add_f32_dpp v41, v41, v41 row_half_mirror row_mask:0xf bank_mask:0xf bound_ctrl:1
	s_nop 1
	v_add_f32_dpp v41, v41, v41 row_mirror row_mask:0xf bank_mask:0xf bound_ctrl:1
	s_nop 1
	v_mov_b32_dpp v47, v41 row_bcast:15 row_mask:0xa bank_mask:0xf
	v_add_f32_e32 v41, v41, v47
	v_mov_b32_e32 v47, 0
	s_nop 1
	v_mov_b32_dpp v47, v41 row_bcast:31 row_mask:0xc bank_mask:0xf
	v_add_f32_e32 v41, v41, v47
	v_mul_f32_e32 v47, v9, v107
	v_fmac_f32_e32 v47, v5, v104
	v_fmac_f32_e32 v47, v7, v121
	v_fmac_f32_e32 v47, v105, v110
	v_mul_f32_e32 v62, 0xbfb8aa3b, v47
	v_readlane_b32 s3, v41, 63
	v_exp_f32_e32 v64, v62
	v_pk_mul_f32 v[62:63], v[10:11], v[58:59]
	v_add_f32_e32 v41, s3, v86
	v_rsq_f32_e32 v41, v41
	v_add_f32_e32 v39, 1.0, v64
	v_rcp_f32_e32 v39, v39
	v_mov_b32_e32 v64, v130
	v_mul_f32_e32 v37, v37, v41
	v_mul_f32_e32 v37, 0x3e000000, v37
	v_cvt_pk_bf16_f32 v37, v37, s0
	ds_write_b16 v124, v37 offset:1792
	v_mul_f32_e32 v37, v47, v39
	v_mul_f32_e32 v39, v37, v37
	v_mov_b32_e32 v41, 0
	v_pk_add_f32 v[64:65], v[64:65], v[132:133]
	v_mov_b32_e32 v134, v62
	v_mov_b32_dpp v41, v39 quad_perm:[1,0,3,2] row_mask:0xf bank_mask:0xf
	v_fmac_f32_e32 v41, v37, v37
	v_lshlrev_b32_e32 v62, 16, v189
	v_pk_add_f32 v[64:65], v[64:65], v[134:135]
	v_add_f32_dpp v39, v41, v41 quad_perm:[2,3,0,1] row_mask:0xf bank_mask:0xf bound_ctrl:1
	v_mov_b32_e32 v41, 0
	v_mul_f32_e32 v131, v11, v62
	v_add_f32_dpp v39, v39, v39 row_half_mirror row_mask:0xf bank_mask:0xf bound_ctrl:1
	v_mov_b32_e32 v130, v63
	v_pk_add_f32 v[64:65], v[64:65], v[130:131]
	v_add_f32_dpp v39, v39, v39 row_mirror row_mask:0xf bank_mask:0xf bound_ctrl:1
	v_mov_b32_e32 v55, 0
	v_cvt_pk_bf16_f32 v132, v74, v75
	v_mov_b32_dpp v41, v39 row_bcast:15 row_mask:0xa bank_mask:0xf
	v_add_f32_e32 v39, v39, v41
	v_mov_b32_e32 v41, 0
	v_lshlrev_b32_e32 v63, 16, v198
	s_nop 0
	v_mov_b32_dpp v41, v39 row_bcast:31 row_mask:0xc bank_mask:0xf
	v_add_f32_e32 v39, v39, v41
	s_nop 0
	v_readlane_b32 s3, v39, 63
	s_nop 1
	v_add_f32_e32 v39, s3, v86
	v_rsq_f32_e32 v39, v39
	s_nop 0
	v_mul_f32_e32 v37, v37, v39
	v_mul_f32_e32 v37, 0x3e000000, v37
	v_cvt_pk_bf16_f32 v103, v37, s0
	v_mul_f32_e32 v37, 0xbfb8aa3b, v64
	v_exp_f32_e32 v37, v37
	v_mul_f32_e32 v39, 0xbfb8aa3b, v65
	v_exp_f32_e32 v39, v39
	v_add_f32_e32 v37, 1.0, v37
	v_rcp_f32_e32 v130, v37
	v_add_f32_e32 v37, 1.0, v39
	v_rcp_f32_e32 v131, v37
	v_cvt_pk_bf16_f32 v37, v40, v46
	v_cvt_pk_bf16_f32 v39, v60, v61
	v_pk_mul_f32 v[40:41], v[64:65], v[130:131]
	s_nop 0
	v_pk_mul_f32 v[46:47], v[40:41], v[40:41]
	v_cvt_pk_bf16_f32 v131, v52, v54
	v_cvt_pk_bf16_f32 v130, v48, v50
	v_add_f32_dpp v46, v46, v46 quad_perm:[1,0,3,2] row_mask:0xf bank_mask:0xf bound_ctrl:1
	v_add_f32_dpp v47, v47, v47 quad_perm:[1,0,3,2] row_mask:0xf bank_mask:0xf bound_ctrl:1
	s_nop 0
	v_add_f32_dpp v46, v46, v46 quad_perm:[2,3,0,1] row_mask:0xf bank_mask:0xf bound_ctrl:1
	v_add_f32_dpp v47, v47, v47 quad_perm:[2,3,0,1] row_mask:0xf bank_mask:0xf bound_ctrl:1
	s_nop 0
	v_add_f32_dpp v46, v46, v46 row_half_mirror row_mask:0xf bank_mask:0xf bound_ctrl:1
	v_add_f32_dpp v47, v47, v47 row_half_mirror row_mask:0xf bank_mask:0xf bound_ctrl:1
	s_nop 0
	v_add_f32_dpp v46, v46, v46 row_mirror row_mask:0xf bank_mask:0xf bound_ctrl:1
	v_add_f32_dpp v47, v47, v47 row_mirror row_mask:0xf bank_mask:0xf bound_ctrl:1
	s_nop 0
	v_mov_b32_dpp v55, v46 row_bcast:15 row_mask:0xa bank_mask:0xf
	v_add_f32_e32 v46, v46, v55
	v_mov_b32_e32 v55, 0
	s_nop 1
	v_mov_b32_dpp v55, v46 row_bcast:31 row_mask:0xc bank_mask:0xf
	v_add_f32_e32 v46, v46, v55
	v_mov_b32_e32 v55, 0
	v_readlane_b32 s3, v46, 63
	s_nop 0
	v_mov_b32_dpp v55, v47 row_bcast:15 row_mask:0xa bank_mask:0xf
	v_add_f32_e32 v47, v47, v55
	v_mov_b32_e32 v55, 0
	v_add_f32_e32 v46, s3, v86
	v_rsq_f32_e32 v46, v46
	v_mov_b32_dpp v55, v47 row_bcast:31 row_mask:0xc bank_mask:0xf
	v_add_f32_e32 v47, v47, v55
	s_nop 0
	v_readlane_b32 s3, v47, 63
	s_nop 1
	v_add_f32_e32 v47, s3, v86
	v_rsq_f32_e32 v47, v47
	s_mov_b32 s3, 0x14000
	v_pk_mul_f32 v[54:55], v[40:41], v[46:47]
	s_nop 0
	v_cvt_pk_bf16_f32 v40, v54, s0
	ds_write_b16 v124, v40 offset:5888
	ds_write_b16 v125, v103 offset:1920
	v_cvt_pk_bf16_f32 v40, v55, s0
	ds_write_b16 v125, v40 offset:6016
	v_add_co_u32_e32 v40, vcc, s14, v42
	v_cvt_pk_bf16_f32 v133, v54, v55
	s_nop 0
	v_addc_co_u32_e32 v41, vcc, 0, v43, vcc
	global_store_dwordx4 v[40:41], v[36:39], off offset:2048
	global_store_dwordx4 v[16:17], v[130:133], off offset:512
	v_add_co_u32_e32 v56, vcc, s3, v44
	v_mov_b32_e32 v38, s2
	s_nop 0
	v_addc_co_u32_e32 v57, vcc, 0, v45, vcc
	v_readlane_b32 s2, v3, 13
	v_mul_f32_e32 v38, s6, v38
	v_mul_f32_e32 v104, v74, v38
	v_mov_b32_e32 v39, s2
	v_mul_f32_e32 v39, s7, v39
	v_mul_f32_e32 v103, v75, v39
	v_lshlrev_b32_e32 v41, 16, v190
	v_lshlrev_b32_e32 v40, 16, v191
	v_pk_mul_f32 v[38:39], v[4:5], v[68:69] op_sel_hi:[0,1]
	v_pk_fma_f32 v[38:39], v[2:3], v[70:71], v[38:39] op_sel_hi:[0,1,1]
	v_pk_mov_b32 v[42:43], v[68:69], v[40:41] op_sel:[1,0]
	v_mul_f32_e32 v69, v9, v121
	v_pk_fma_f32 v[38:39], v[6:7], v[42:43], v[38:39] op_sel_hi:[0,1,1]
	v_pk_fma_f32 v[38:39], v[8:9], v[40:41], v[38:39] op_sel_hi:[0,1,1]
	v_mul_f32_e32 v46, 0xbfb8aa3b, v38
	v_mul_f32_e32 v47, 0xbfb8aa3b, v39
	v_exp_f32_e32 v46, v46
	v_exp_f32_e32 v47, v47
	v_readlane_b32 s3, v3, 14
	v_fmac_f32_e32 v69, v5, v107
	v_add_f32_e32 v46, 1.0, v46
	v_add_f32_e32 v47, 1.0, v47
	v_rcp_f32_e32 v46, v46
	v_rcp_f32_e32 v47, v47
	v_readlane_b32 s2, v102, 14
	v_mov_b32_e32 v48, s3
	v_fmac_f32_e32 v69, v7, v110
	v_mul_f32_e32 v66, s2, v48
	v_fmac_f32_e32 v69, v105, v120
	v_mul_f32_e32 v36, 0xbfb8aa3b, v72
	v_mul_f32_e32 v37, 0xbfb8aa3b, v73
	v_readlane_b32 s3, v102, 15
	v_pk_mul_f32 v[38:39], v[38:39], v[46:47]
	v_mov_b32_e32 v46, s4
	v_mul_f32_e32 v107, v54, v66
	v_mul_f32_e32 v54, 0xbfb8aa3b, v69
	v_exp_f32_e32 v36, v36
	v_exp_f32_e32 v37, v37
	v_mul_f32_e32 v67, s3, v46
	v_pk_mul_f32 v[46:47], v[14:15], v[58:59]
	v_exp_f32_e32 v58, v54
	v_pk_mul_f32 v[38:39], v[38:39], s[2:3]
	s_mov_b64 s[2:3], 0x14000
	v_lshl_add_u64 v[48:49], v[44:45], 0, s[2:3]
	s_mov_b64 s[2:3], 0x15000
	v_add_f32_e32 v36, 1.0, v36
	v_add_f32_e32 v37, 1.0, v37
	v_lshl_add_u64 v[50:51], v[44:45], 0, s[2:3]
	s_mov_b64 s[2:3], 0x16000
	v_add_f32_e32 v58, 1.0, v58
	v_rcp_f32_e32 v36, v36
	v_rcp_f32_e32 v37, v37
	v_lshl_add_u64 v[60:61], v[44:45], 0, s[2:3]
	s_mov_b64 s[2:3], 0x17000
	v_rcp_f32_e32 v58, v58
	v_lshl_add_u64 v[64:65], v[44:45], 0, s[2:3]
	s_mov_b32 s2, 0x15000
	v_add_co_u32_e32 v54, vcc, s2, v44
	v_mul_f32_e32 v106, v55, v67
	s_nop 0
	v_addc_co_u32_e32 v55, vcc, 0, v45, vcc
	v_pk_mul_f32 v[36:37], v[72:73], v[36:37]
	v_mul_f32_e32 v50, v69, v58
	v_mul_f32_e32 v48, v50, v50
	v_mov_b32_e32 v49, 0
	v_mul_f32_e32 v61, v9, v110
	v_fmac_f32_e32 v61, v5, v121
	v_mov_b32_dpp v49, v48 quad_perm:[1,0,3,2] row_mask:0xf bank_mask:0xf
	v_fmac_f32_e32 v49, v50, v50
	v_fmac_f32_e32 v61, v7, v120
	v_fmac_f32_e32 v61, v105, v78
	v_add_f32_dpp v48, v49, v49 quad_perm:[2,3,0,1] row_mask:0xf bank_mask:0xf bound_ctrl:1
	v_mov_b32_e32 v49, 0
	s_mov_b32 s2, 0x16000
	v_add_f32_dpp v48, v48, v48 row_half_mirror row_mask:0xf bank_mask:0xf bound_ctrl:1
	v_add_co_u32_e32 v56, vcc, s2, v44
	s_nop 0
	v_add_f32_dpp v48, v48, v48 row_mirror row_mask:0xf bank_mask:0xf bound_ctrl:1
	s_mov_b64 s[98:99], 0x16000
	v_lshl_add_u64 v[150:151], v[44:45], 0, s[98:99]
	global_load_ushort v213, v[150:151], off offset:-1024
	global_load_ushort v215, v[150:151], off
	s_mov_b64 s[98:99], 0x17000
	v_lshl_add_u64 v[150:151], v[44:45], 0, s[98:99]
	global_load_ushort v214, v[150:151], off offset:-1024
	global_load_ushort v216, v[150:151], off
	s_waitcnt vmcnt(4) lgkmcnt(0)
	v_lshlrev_b32_e32 v71, 16, v202
	v_addc_co_u32_e32 v57, vcc, 0, v45, vcc
	v_mov_b32_dpp v49, v48 row_bcast:15 row_mask:0xa bank_mask:0xf
	v_add_f32_e32 v48, v48, v49
	v_mov_b32_e32 v49, 0
	s_mov_b32 s2, 0x17000
	v_readlane_b32 s4, v3, 17
	v_mov_b32_dpp v49, v48 row_bcast:31 row_mask:0xc bank_mask:0xf
	v_add_f32_e32 v48, v48, v49
	v_fmac_f32_e32 v126, v105, v71
	v_readlane_b32 s3, v48, 63
	v_lshlrev_b32_e32 v122, 16, v203
	v_pk_mul_f32 v[36:37], v[36:37], s[6:7]
	v_add_f32_e32 v48, s3, v86
	v_rsq_f32_e32 v51, v48
	v_pk_mul_f32 v[48:49], v[10:11], v[62:63]
	v_readlane_b32 s3, v3, 16
	v_readlane_b32 s7, v102, 21
	v_mul_f32_e32 v50, v50, v51
	v_mul_f32_e32 v50, 0x3e000000, v50
	v_cvt_pk_bf16_f32 v58, v50, s0
	v_mul_f32_e32 v50, 0xbfb8aa3b, v61
	v_exp_f32_e32 v52, v50
	v_add_co_u32_e32 v50, vcc, s2, v44
	v_readlane_b32 s6, v102, 20
	v_add_f32_e32 v52, 1.0, v52
	v_rcp_f32_e32 v64, v52
	v_addc_co_u32_e32 v51, vcc, 0, v45, vcc
	v_mul_f32_e32 v54, v61, v64
	v_mul_f32_e32 v55, v54, v54
	v_mov_b32_e32 v56, 0
	v_mul_f32_e32 v57, v12, v62
	ds_write_b16 v114, v58 offset:2048
	v_mov_b32_dpp v56, v55 quad_perm:[1,0,3,2] row_mask:0xf bank_mask:0xf
	v_fmac_f32_e32 v56, v54, v54
	v_mov_b32_e32 v58, v48
	v_mul_f32_e32 v64, v9, v120
	v_add_f32_dpp v55, v56, v56 quad_perm:[2,3,0,1] row_mask:0xf bank_mask:0xf bound_ctrl:1
	v_mov_b32_e32 v56, 0
	v_fmac_f32_e32 v64, v5, v110
	v_add_f32_dpp v55, v55, v55 row_half_mirror row_mask:0xf bank_mask:0xf bound_ctrl:1
	v_fmac_f32_e32 v64, v7, v78
	v_fmac_f32_e32 v64, v105, v77
	v_add_f32_dpp v55, v55, v55 row_mirror row_mask:0xf bank_mask:0xf bound_ctrl:1
	v_mov_b32_e32 v110, 0
	s_mov_b64 s[98:99], 0x18000
	v_lshl_add_u64 v[150:151], v[44:45], 0, s[98:99]
	global_load_ushort v217, v[150:151], off offset:-1024
	global_load_ushort v221, v[150:151], off
	global_load_ushort v223, v[150:151], off offset:1024
	s_mov_b64 s[98:99], 0x19000
	v_lshl_add_u64 v[150:151], v[44:45], 0, s[98:99]
	global_load_ushort v218, v[150:151], off offset:-1024
	global_load_ushort v222, v[150:151], off offset:1024
	global_load_ushort v224, v[150:151], off
	s_mov_b64 s[98:99], 0x1a000
	v_lshl_add_u64 v[150:151], v[44:45], 0, s[98:99]
	global_load_ushort v219, v[150:151], off offset:-1024
	global_load_ushort v225, v[150:151], off
	s_mov_b64 s[98:99], 0x1b000
	v_lshl_add_u64 v[150:151], v[44:45], 0, s[98:99]
	global_load_ushort v220, v[150:151], off offset:-1024
	s_waitcnt vmcnt(10) lgkmcnt(0)
	v_lshlrev_b32_e32 v134, 16, v213
	v_mov_b32_dpp v56, v55 row_bcast:15 row_mask:0xa bank_mask:0xf
	v_add_f32_e32 v55, v55, v56
	v_mov_b32_e32 v56, 0
	v_lshlrev_b32_e32 v52, 16, v199
	v_lshlrev_b32_e32 v129, 16, v214
	v_mov_b32_dpp v56, v55 row_bcast:31 row_mask:0xc bank_mask:0xf
	v_add_f32_e32 v55, v55, v56
	v_mul_f32_e32 v149, v9, v134
	v_readlane_b32 s2, v55, 63
	v_fmac_f32_e32 v149, v5, v122
	v_fmac_f32_e32 v149, v7, v129
	v_add_f32_e32 v55, s2, v86
	v_rsq_f32_e32 v56, v55
	v_mul_f32_e32 v55, v13, v59
	v_mul_f32_e32 v59, v10, v63
	v_mul_f32_e32 v54, v54, v56
	v_mul_f32_e32 v61, 0x3e000000, v54
	v_mov_b32_e32 v54, v46
	v_mov_b32_e32 v56, v47
	v_pk_add_f32 v[46:47], v[54:55], v[56:57]
	v_mov_b32_e32 v56, v49
	v_pk_add_f32 v[54:55], v[46:47], v[58:59]
	v_lshlrev_b32_e32 v46, 16, v200
	v_mul_f32_e32 v57, v11, v46
	v_pk_add_f32 v[48:49], v[54:55], v[56:57]
	v_cvt_pk_bf16_f32 v61, v61, s0
	v_mul_f32_e32 v47, 0xbfb8aa3b, v48
	v_exp_f32_e32 v47, v47
	v_mul_f32_e32 v54, 0xbfb8aa3b, v49
	v_exp_f32_e32 v55, v54
	v_pk_mul_f32 v[58:59], v[14:15], v[62:63]
	v_add_f32_e32 v47, 1.0, v47
	v_rcp_f32_e32 v54, v47
	v_add_f32_e32 v47, 1.0, v55
	v_rcp_f32_e32 v55, v47
	v_mov_b32_e32 v62, 0
	v_pk_mul_f32 v[48:49], v[48:49], v[54:55]
	s_nop 0
	v_pk_mul_f32 v[54:55], v[48:49], v[48:49]
	s_nop 1
	v_add_f32_dpp v47, v54, v54 quad_perm:[1,0,3,2] row_mask:0xf bank_mask:0xf bound_ctrl:1
	v_mov_b32_e32 v54, 0
	s_nop 0
	v_add_f32_dpp v47, v47, v47 quad_perm:[2,3,0,1] row_mask:0xf bank_mask:0xf bound_ctrl:1
	s_nop 1
	v_add_f32_dpp v47, v47, v47 row_half_mirror row_mask:0xf bank_mask:0xf bound_ctrl:1
	s_nop 1
	v_add_f32_dpp v47, v47, v47 row_mirror row_mask:0xf bank_mask:0xf bound_ctrl:1
	s_nop 1
	v_mov_b32_dpp v54, v47 row_bcast:15 row_mask:0xa bank_mask:0xf
	v_add_f32_e32 v47, v47, v54
	v_mov_b32_e32 v54, 0
	s_nop 1
	v_mov_b32_dpp v54, v47 row_bcast:31 row_mask:0xc bank_mask:0xf
	v_add_f32_e32 v47, v47, v54
	s_nop 0
	v_readlane_b32 s2, v47, 63
	s_nop 1
	v_add_f32_e32 v47, s2, v86
	v_rsq_f32_e32 v54, v47
	s_nop 0
	v_add_f32_dpp v47, v55, v55 quad_perm:[1,0,3,2] row_mask:0xf bank_mask:0xf bound_ctrl:1
	v_mov_b32_e32 v55, 0
	s_nop 0
	v_add_f32_dpp v47, v47, v47 quad_perm:[2,3,0,1] row_mask:0xf bank_mask:0xf bound_ctrl:1
	s_nop 1
	v_add_f32_dpp v47, v47, v47 row_half_mirror row_mask:0xf bank_mask:0xf bound_ctrl:1
	s_nop 1
	v_add_f32_dpp v47, v47, v47 row_mirror row_mask:0xf bank_mask:0xf bound_ctrl:1
	s_nop 1
	v_mov_b32_dpp v55, v47 row_bcast:15 row_mask:0xa bank_mask:0xf
	v_add_f32_e32 v47, v47, v55
	v_mov_b32_e32 v55, 0
	s_nop 1
	v_mov_b32_dpp v55, v47 row_bcast:31 row_mask:0xc bank_mask:0xf
	v_add_f32_e32 v47, v47, v55
	s_nop 0
	v_readlane_b32 s2, v47, 63
	s_nop 1
	v_add_f32_e32 v47, s2, v86
	v_rsq_f32_e32 v55, v47
	v_mul_f32_e32 v47, 0xbfb8aa3b, v64
	v_exp_f32_e32 v65, v47
	v_lshlrev_b32_e32 v47, 16, v201
	v_pk_mul_f32 v[56:57], v[48:49], v[54:55]
	v_add_f32_e32 v48, 1.0, v65
	v_rcp_f32_e32 v48, v48
	v_cvt_pk_bf16_f32 v49, v56, s0
	ds_write_b16 v114, v49 offset:6144
	ds_write_b16 v116, v61 offset:2176
	v_mov_b32_e32 v49, 0
	v_mul_f32_e32 v54, v64, v48
	v_mul_f32_e32 v48, v54, v54
	v_mul_f32_e32 v61, v9, v78
	v_fmac_f32_e32 v61, v5, v120
	v_mov_b32_dpp v49, v48 quad_perm:[1,0,3,2] row_mask:0xf bank_mask:0xf
	v_fmac_f32_e32 v49, v54, v54
	v_fmac_f32_e32 v61, v7, v77
	v_fmac_f32_e32 v61, v105, v76
	v_add_f32_dpp v48, v49, v49 quad_perm:[2,3,0,1] row_mask:0xf bank_mask:0xf bound_ctrl:1
	v_mov_b32_e32 v49, 0
	v_mul_f32_e32 v65, v10, v47
	v_add_f32_dpp v48, v48, v48 row_half_mirror row_mask:0xf bank_mask:0xf bound_ctrl:1
	s_nop 1
	v_add_f32_dpp v48, v48, v48 row_mirror row_mask:0xf bank_mask:0xf bound_ctrl:1
	s_nop 1
	v_mov_b32_dpp v49, v48 row_bcast:15 row_mask:0xa bank_mask:0xf
	v_add_f32_e32 v48, v48, v49
	v_mov_b32_e32 v49, 0
	s_nop 1
	v_mov_b32_dpp v49, v48 row_bcast:31 row_mask:0xc bank_mask:0xf
	v_add_f32_e32 v48, v48, v49
	s_nop 0
	v_readlane_b32 s2, v48, 63
	s_nop 1
	v_add_f32_e32 v48, s2, v86
	v_rsq_f32_e32 v55, v48
	v_cvt_pk_bf16_f32 v48, v57, s0
	ds_write_b16 v116, v48 offset:6272
	v_pk_mul_f32 v[48:49], v[10:11], v[46:47]
	v_mul_f32_e32 v54, v54, v55
	v_mul_f32_e32 v55, 0xbfb8aa3b, v61
	v_exp_f32_e32 v55, v55
	v_mul_f32_e32 v54, 0x3e000000, v54
	v_cvt_pk_bf16_f32 v54, v54, s0
	ds_write_b16 v115, v54 offset:2304
	v_add_f32_e32 v54, 1.0, v55
	v_rcp_f32_e32 v54, v54
	v_mul_f32_e32 v55, v13, v63
	v_mul_f32_e32 v63, v12, v46
	v_mov_b32_e32 v64, v48
	v_mul_f32_e32 v61, v61, v54
	v_mul_f32_e32 v54, v61, v61
	v_lshlrev_b32_e32 v48, 16, v204
	s_nop 0
	v_mov_b32_dpp v62, v54 quad_perm:[1,0,3,2] row_mask:0xf bank_mask:0xf
	v_fmac_f32_e32 v62, v61, v61
	s_nop 1
	v_add_f32_dpp v54, v62, v62 quad_perm:[2,3,0,1] row_mask:0xf bank_mask:0xf bound_ctrl:1
	v_mov_b32_e32 v62, 0
	s_nop 0
	v_add_f32_dpp v54, v54, v54 row_half_mirror row_mask:0xf bank_mask:0xf bound_ctrl:1
	s_nop 1
	v_add_f32_dpp v54, v54, v54 row_mirror row_mask:0xf bank_mask:0xf bound_ctrl:1
	s_nop 1
	v_mov_b32_dpp v62, v54 row_bcast:15 row_mask:0xa bank_mask:0xf
	v_add_f32_e32 v69, v54, v62
	v_mov_b32_e32 v54, v58
	v_mov_b32_e32 v62, v59
	v_pk_add_f32 v[54:55], v[54:55], v[62:63]
	v_mul_f32_e32 v59, v11, v48
	v_pk_add_f32 v[54:55], v[54:55], v[64:65]
	v_mov_b32_e32 v58, v49
	v_pk_add_f32 v[54:55], v[54:55], v[58:59]
	v_mov_b32_dpp v110, v69 row_bcast:31 row_mask:0xc bank_mask:0xf
	v_mul_f32_e32 v49, 0xbfb8aa3b, v54
	v_exp_f32_e32 v49, v49
	v_mul_f32_e32 v58, 0xbfb8aa3b, v55
	v_exp_f32_e32 v59, v58
	v_add_f32_e32 v62, v69, v110
	v_add_f32_e32 v49, 1.0, v49
	v_rcp_f32_e32 v58, v49
	v_add_f32_e32 v49, 1.0, v59
	v_rcp_f32_e32 v59, v49
	v_readlane_b32 s2, v62, 63
	v_mov_b32_e32 v62, 0
	v_pk_mul_f32 v[54:55], v[54:55], v[58:59]
	s_nop 0
	v_pk_mul_f32 v[58:59], v[54:55], v[54:55]
	v_add_f32_e32 v49, s2, v86
	v_rsq_f32_e32 v49, v49
	v_add_f32_dpp v58, v58, v58 quad_perm:[1,0,3,2] row_mask:0xf bank_mask:0xf bound_ctrl:1
	v_add_f32_dpp v59, v59, v59 quad_perm:[1,0,3,2] row_mask:0xf bank_mask:0xf bound_ctrl:1
	v_mul_f32_e32 v49, v61, v49
	v_add_f32_dpp v58, v58, v58 quad_perm:[2,3,0,1] row_mask:0xf bank_mask:0xf bound_ctrl:1
	v_add_f32_dpp v59, v59, v59 quad_perm:[2,3,0,1] row_mask:0xf bank_mask:0xf bound_ctrl:1
	v_mul_f32_e32 v49, 0x3e000000, v49
	v_add_f32_dpp v58, v58, v58 row_half_mirror row_mask:0xf bank_mask:0xf bound_ctrl:1
	v_add_f32_dpp v59, v59, v59 row_half_mirror row_mask:0xf bank_mask:0xf bound_ctrl:1
	v_cvt_pk_bf16_f32 v49, v49, s0
	v_add_f32_dpp v58, v58, v58 row_mirror row_mask:0xf bank_mask:0xf bound_ctrl:1
	v_add_f32_dpp v59, v59, v59 row_mirror row_mask:0xf bank_mask:0xf bound_ctrl:1
	v_pk_mov_b32 v[60:61], v[40:41], v[52:53] op_sel:[1,0]
	v_mov_b32_dpp v62, v58 row_bcast:15 row_mask:0xa bank_mask:0xf
	v_add_f32_e32 v58, v58, v62
	v_mov_b32_e32 v62, 0
	s_nop 1
	v_mov_b32_dpp v62, v58 row_bcast:31 row_mask:0xc bank_mask:0xf
	v_add_f32_e32 v58, v58, v62
	v_mov_b32_e32 v62, 0
	v_readlane_b32 s2, v58, 63
	s_nop 0
	v_mov_b32_dpp v62, v59 row_bcast:15 row_mask:0xa bank_mask:0xf
	v_add_f32_e32 v59, v59, v62
	v_mov_b32_e32 v62, 0
	v_add_f32_e32 v58, s2, v86
	v_rsq_f32_e32 v58, v58
	v_mov_b32_dpp v62, v59 row_bcast:31 row_mask:0xc bank_mask:0xf
	v_add_f32_e32 v59, v59, v62
	s_nop 0
	v_readlane_b32 s2, v59, 63
	s_nop 1
	v_add_f32_e32 v59, s2, v86
	v_rsq_f32_e32 v59, v59
	s_mov_b32 s2, 0x18000
	v_pk_mul_f32 v[58:59], v[54:55], v[58:59]
	s_nop 0
	v_cvt_pk_bf16_f32 v54, v58, s0
	ds_write_b16 v115, v54 offset:6400
	ds_write_b16 v117, v49 offset:2432
	v_cvt_pk_bf16_f32 v49, v59, s0
	v_add_co_u32_e32 v54, vcc, s2, v44
	ds_write_b16 v117, v49 offset:6528
	s_nop 0
	v_addc_co_u32_e32 v55, vcc, 0, v45, vcc
	s_mov_b32 s2, 0x19000
	v_add_co_u32_e32 v62, vcc, s2, v44
	v_mov_b32_e32 v49, s3
	s_nop 0
	v_addc_co_u32_e32 v63, vcc, 0, v45, vcc
	v_pk_mul_f32 v[50:51], v[4:5], v[40:41] op_sel_hi:[0,1]
	v_pk_fma_f32 v[42:43], v[2:3], v[42:43], v[50:51] op_sel_hi:[0,1,1]
	v_pk_fma_f32 v[40:41], v[6:7], v[60:61], v[42:43] op_sel_hi:[0,1,1]
	v_pk_fma_f32 v[40:41], v[8:9], v[52:53], v[40:41] op_sel_hi:[0,1,1]
	v_mul_f32_e32 v42, 0xbfb8aa3b, v40
	v_mul_f32_e32 v43, 0xbfb8aa3b, v41
	v_exp_f32_e32 v42, v42
	v_exp_f32_e32 v43, v43
	s_mov_b32 s3, 0x1a000
	v_add_co_u32_e32 v64, vcc, s3, v44
	v_add_f32_e32 v42, 1.0, v42
	v_add_f32_e32 v43, 1.0, v43
	v_rcp_f32_e32 v42, v42
	v_rcp_f32_e32 v43, v43
	v_readlane_b32 s3, v102, 17
	v_lshlrev_b32_e32 v51, 16, v205
	v_lshlrev_b32_e32 v50, 16, v206
	v_pk_mul_f32 v[40:41], v[40:41], v[42:43]
	v_mov_b32_e32 v42, s4
	v_mul_f32_e32 v42, s3, v42
	v_mul_f32_e32 v110, v57, v42
	v_pk_mul_f32 v[42:43], v[4:5], v[52:53] op_sel_hi:[0,1]
	v_pk_fma_f32 v[42:43], v[2:3], v[60:61], v[42:43] op_sel_hi:[0,1,1]
	v_pk_mov_b32 v[52:53], v[52:53], v[50:51] op_sel:[1,0]
	v_readlane_b32 s2, v102, 16
	v_pk_fma_f32 v[42:43], v[6:7], v[52:53], v[42:43] op_sel_hi:[0,1,1]
	v_pk_fma_f32 v[42:43], v[8:9], v[50:51], v[42:43] op_sel_hi:[0,1,1]
	v_mul_f32_e32 v49, s2, v49
	v_mul_f32_e32 v111, v56, v49
	v_mul_f32_e32 v49, 0xbfb8aa3b, v42
	v_exp_f32_e32 v49, v49
	v_mul_f32_e32 v60, 0xbfb8aa3b, v43
	v_exp_f32_e32 v61, v60
	v_pk_mul_f32 v[40:41], v[40:41], s[2:3]
	v_add_f32_e32 v49, 1.0, v49
	v_rcp_f32_e32 v60, v49
	v_add_f32_e32 v49, 1.0, v61
	v_rcp_f32_e32 v61, v49
	v_readlane_b32 s3, v3, 18
	v_readlane_b32 s4, v3, 19
	v_readlane_b32 s2, v102, 18
	v_pk_mul_f32 v[42:43], v[42:43], v[60:61]
	v_pk_mul_f32 v[60:61], v[14:15], v[46:47]
	v_mul_f32_e32 v46, 0xbfb8aa3b, v126
	v_exp_f32_e32 v46, v46
	v_mov_b32_e32 v112, s3
	v_readlane_b32 s3, v102, 19
	v_mov_b32_e32 v49, s4
	v_add_f32_e32 v46, 1.0, v46
	v_rcp_f32_e32 v46, v46
	v_addc_co_u32_e32 v65, vcc, 0, v45, vcc
	v_mul_f32_e32 v112, s2, v112
	v_mul_f32_e32 v123, s3, v49
	v_mul_f32_e32 v46, v126, v46
	v_mul_f32_e32 v113, v58, v112
	v_mul_f32_e32 v112, v59, v123
	v_mul_f32_e32 v54, v46, v46
	v_mov_b32_e32 v55, 0
	v_pk_mul_f32 v[42:43], v[42:43], s[2:3]
	v_lshlrev_b32_e32 v49, 16, v207
	v_mov_b32_dpp v55, v54 quad_perm:[1,0,3,2] row_mask:0xf bank_mask:0xf
	v_fmac_f32_e32 v55, v46, v46
	v_pk_mul_f32 v[62:63], v[10:11], v[48:49]
	v_mul_f32_e32 v47, v13, v47
	v_add_f32_dpp v54, v55, v55 quad_perm:[2,3,0,1] row_mask:0xf bank_mask:0xf bound_ctrl:1
	v_mov_b32_e32 v55, 0
	v_readlane_b32 s3, v3, 22
	v_add_f32_dpp v54, v54, v54 row_half_mirror row_mask:0xf bank_mask:0xf bound_ctrl:1
	v_readlane_b32 s4, v3, 23
	s_mov_b64 s[98:99], 0x1a000
	v_lshl_add_u64 v[150:151], v[44:45], 0, s[98:99]
	global_load_ushort v232, v[150:151], off offset:1024
	s_mov_b64 s[98:99], 0x1b000
	v_lshl_add_u64 v[150:151], v[44:45], 0, s[98:99]
	global_load_ushort v231, v[150:151], off offset:1024
	global_load_ushort v233, v[150:151], off
	s_mov_b64 s[98:99], 0x1c000
	v_lshl_add_u64 v[150:151], v[44:45], 0, s[98:99]
	global_load_ushort v226, v[150:151], off offset:-1024
	global_load_ushort v234, v[150:151], off
	global_load_ushort v152, v[150:151], off offset:1024
	s_mov_b64 s[98:99], 0x1d000
	v_lshl_add_u64 v[150:151], v[44:45], 0, s[98:99]
	global_load_ushort v227, v[150:151], off offset:-1024
	global_load_ushort v153, v[150:151], off
	global_load_ushort v242, v[150:151], off offset:1024
	s_mov_b64 s[98:99], 0x1e000
	v_lshl_add_u64 v[150:151], v[44:45], 0, s[98:99]
	global_load_ushort v228, v[150:151], off offset:-1024
	global_load_ushort v155, v[150:151], off offset:1024
	global_load_ushort v154, v[150:151], off
	s_mov_b64 s[98:99], 0x1f000
	v_lshl_add_u64 v[150:151], v[44:45], 0, s[98:99]
	global_load_ushort v230, v[150:151], off offset:-1024
	global_load_ushort v229, v[150:151], off
	global_load_ushort v156, v[150:151], off offset:1024
	s_waitcnt vmcnt(15) lgkmcnt(0)
	v_lshlrev_b32_e32 v133, 16, v217
	v_add_f32_dpp v54, v54, v54 row_mirror row_mask:0xf bank_mask:0xf bound_ctrl:1
	v_mul_f32_e32 v69, v10, v49
	v_lshlrev_b32_e32 v128, 16, v218
	v_mov_b32_dpp v55, v54 row_bcast:15 row_mask:0xa bank_mask:0xf
	v_add_f32_e32 v54, v54, v55
	v_mov_b32_e32 v55, 0
	v_mov_b32_e32 v120, 0
	v_lshlrev_b32_e32 v127, 16, v219
	v_mov_b32_dpp v55, v54 row_bcast:31 row_mask:0xc bank_mask:0xf
	v_add_f32_e32 v54, v54, v55
	v_fmac_f32_e32 v149, v105, v133
	v_readlane_b32 s2, v54, 63
	v_lshlrev_b32_e32 v126, 16, v220
	s_nop 0
	v_add_f32_e32 v54, s2, v86
	s_mov_b32 s2, 0x1b000
	v_rsq_f32_e32 v68, v54
	v_add_co_u32_e32 v54, vcc, s2, v44
	v_readlane_b32 s2, v3, 20
	s_nop 0
	v_addc_co_u32_e32 v55, vcc, 0, v45, vcc
	v_mul_f32_e32 v64, v9, v76
	v_fmac_f32_e32 v64, v5, v77
	v_fmac_f32_e32 v64, v7, v71
	v_fmac_f32_e32 v64, v105, v122
	v_mul_f32_e32 v65, 0xbfb8aa3b, v64
	v_exp_f32_e32 v65, v65
	v_mul_f32_e32 v46, v46, v68
	v_mul_f32_e32 v46, 0x3e000000, v46
	v_cvt_pk_bf16_f32 v46, v46, s0
	ds_write_b16 v118, v46 offset:2560
	v_add_f32_e32 v46, 1.0, v65
	v_rcp_f32_e32 v46, v46
	v_mov_b32_e32 v65, 0
	v_mov_b32_e32 v77, s2
	v_mov_b32_e32 v68, v62
	v_mul_f32_e32 v46, v64, v46
	v_mul_f32_e32 v64, v46, v46
	s_nop 1
	v_mov_b32_dpp v65, v64 quad_perm:[1,0,3,2] row_mask:0xf bank_mask:0xf
	v_fmac_f32_e32 v65, v46, v46
	s_nop 1
	v_add_f32_dpp v64, v65, v65 quad_perm:[2,3,0,1] row_mask:0xf bank_mask:0xf bound_ctrl:1
	v_mov_b32_e32 v65, 0
	s_nop 0
	v_add_f32_dpp v64, v64, v64 row_half_mirror row_mask:0xf bank_mask:0xf bound_ctrl:1
	s_nop 1
	v_add_f32_dpp v64, v64, v64 row_mirror row_mask:0xf bank_mask:0xf bound_ctrl:1
	s_nop 1
	v_mov_b32_dpp v65, v64 row_bcast:15 row_mask:0xa bank_mask:0xf
	v_add_f32_e32 v64, v64, v65
	v_mov_b32_e32 v65, 0
	s_nop 1
	v_mov_b32_dpp v65, v64 row_bcast:31 row_mask:0xc bank_mask:0xf
	v_add_f32_e32 v64, v64, v65
	v_mul_f32_e32 v65, v12, v48
	v_readlane_b32 s2, v64, 63
	s_nop 1
	v_add_f32_e32 v64, s2, v86
	v_rsq_f32_e32 v64, v64
	s_nop 0
	v_mul_f32_e32 v46, v46, v64
	v_mul_f32_e32 v78, 0x3e000000, v46
	v_mov_b32_e32 v46, v60
	v_mov_b32_e32 v64, v61
	v_pk_add_f32 v[46:47], v[46:47], v[64:65]
	v_lshlrev_b32_e32 v65, 16, v208
	v_pk_add_f32 v[60:61], v[46:47], v[68:69]
	v_lshlrev_b32_e32 v64, 16, v209
	v_pk_mul_f32 v[46:47], v[4:5], v[50:51] op_sel_hi:[0,1]
	v_pk_fma_f32 v[46:47], v[2:3], v[52:53], v[46:47] op_sel_hi:[0,1,1]
	v_pk_mov_b32 v[66:67], v[50:51], v[64:65] op_sel:[1,0]
	v_mov_b32_e32 v52, v63
	v_pk_fma_f32 v[46:47], v[6:7], v[66:67], v[46:47] op_sel_hi:[0,1,1]
	v_pk_fma_f32 v[46:47], v[8:9], v[64:65], v[46:47] op_sel_hi:[0,1,1]
	v_mul_f32_e32 v50, 0xbfb8aa3b, v46
	v_exp_f32_e32 v50, v50
	v_mul_f32_e32 v51, 0xbfb8aa3b, v47
	v_exp_f32_e32 v51, v51
	v_pk_mul_f32 v[62:63], v[14:15], v[48:49]
	v_add_f32_e32 v50, 1.0, v50
	v_rcp_f32_e32 v68, v50
	v_add_f32_e32 v50, 1.0, v51
	v_rcp_f32_e32 v69, v50
	v_lshlrev_b32_e32 v50, 16, v210
	v_mul_f32_e32 v53, v11, v50
	v_pk_add_f32 v[52:53], v[60:61], v[52:53]
	v_mul_f32_e32 v73, v9, v71
	v_mul_f32_e32 v51, 0xbfb8aa3b, v52
	v_exp_f32_e32 v51, v51
	v_mul_f32_e32 v60, 0xbfb8aa3b, v53
	v_exp_f32_e32 v61, v60
	v_fmac_f32_e32 v73, v5, v76
	v_add_f32_e32 v51, 1.0, v51
	v_rcp_f32_e32 v60, v51
	v_add_f32_e32 v51, 1.0, v61
	v_rcp_f32_e32 v61, v51
	v_fmac_f32_e32 v73, v7, v122
	v_fmac_f32_e32 v73, v105, v134
	v_cvt_pk_bf16_f32 v78, v78, s0
	v_pk_mul_f32 v[52:53], v[52:53], v[60:61]
	v_mul_f32_e32 v49, v13, v49
	v_pk_mul_f32 v[60:61], v[52:53], v[52:53]
	v_pk_mul_f32 v[46:47], v[46:47], v[68:69]
	v_lshlrev_b32_e32 v69, 16, v211
	v_add_f32_dpp v51, v60, v60 quad_perm:[1,0,3,2] row_mask:0xf bank_mask:0xf bound_ctrl:1
	v_mov_b32_e32 v60, 0
	v_pk_mul_f32 v[46:47], v[46:47], s[6:7]
	v_add_f32_dpp v51, v51, v51 quad_perm:[2,3,0,1] row_mask:0xf bank_mask:0xf bound_ctrl:1
	s_nop 1
	v_add_f32_dpp v51, v51, v51 row_half_mirror row_mask:0xf bank_mask:0xf bound_ctrl:1
	s_nop 1
	v_add_f32_dpp v51, v51, v51 row_mirror row_mask:0xf bank_mask:0xf bound_ctrl:1
	s_nop 1
	v_mov_b32_dpp v60, v51 row_bcast:15 row_mask:0xa bank_mask:0xf
	v_add_f32_e32 v51, v51, v60
	v_mov_b32_e32 v60, 0
	s_nop 1
	v_mov_b32_dpp v60, v51 row_bcast:31 row_mask:0xc bank_mask:0xf
	v_add_f32_e32 v51, v51, v60
	s_nop 0
	v_readlane_b32 s2, v51, 63
	s_nop 1
	v_add_f32_e32 v51, s2, v86
	v_rsq_f32_e32 v60, v51
	s_nop 0
	v_add_f32_dpp v51, v61, v61 quad_perm:[1,0,3,2] row_mask:0xf bank_mask:0xf bound_ctrl:1
	v_mov_b32_e32 v61, 0
	s_nop 0
	v_add_f32_dpp v51, v51, v51 quad_perm:[2,3,0,1] row_mask:0xf bank_mask:0xf bound_ctrl:1
	s_nop 1
	v_add_f32_dpp v51, v51, v51 row_half_mirror row_mask:0xf bank_mask:0xf bound_ctrl:1
	s_nop 1
	v_add_f32_dpp v51, v51, v51 row_mirror row_mask:0xf bank_mask:0xf bound_ctrl:1
	s_nop 1
	v_mov_b32_dpp v61, v51 row_bcast:15 row_mask:0xa bank_mask:0xf
	v_add_f32_e32 v51, v51, v61
	v_mov_b32_e32 v61, 0
	s_nop 1
	v_mov_b32_dpp v61, v51 row_bcast:31 row_mask:0xc bank_mask:0xf
	v_add_f32_e32 v51, v51, v61
	s_nop 0
	v_readlane_b32 s2, v51, 63
	s_nop 1
	v_add_f32_e32 v51, s2, v86
	v_rsq_f32_e32 v61, v51
	v_mul_f32_e32 v51, 0xbfb8aa3b, v73
	v_exp_f32_e32 v76, v51
	v_lshlrev_b32_e32 v51, 16, v215
	v_pk_mul_f32 v[60:61], v[52:53], v[60:61]
	v_mov_b32_e32 v53, 0
	v_add_f32_e32 v48, 1.0, v76
	v_rcp_f32_e32 v48, v48
	v_cvt_pk_bf16_f32 v52, v60, s0
	ds_write_b16 v118, v52 offset:6656
	ds_write_b16 v119, v78 offset:2688
	v_mul_f32_e32 v79, v10, v51
	v_mul_f32_e32 v48, v73, v48
	v_mul_f32_e32 v52, v48, v48
	v_mul_f32_e32 v73, v12, v50
	s_nop 0
	v_mov_b32_dpp v53, v52 quad_perm:[1,0,3,2] row_mask:0xf bank_mask:0xf
	v_fmac_f32_e32 v53, v48, v48
	s_nop 1
	v_add_f32_dpp v52, v53, v53 quad_perm:[2,3,0,1] row_mask:0xf bank_mask:0xf bound_ctrl:1
	v_mov_b32_e32 v53, 0
	s_nop 0
	v_add_f32_dpp v52, v52, v52 row_half_mirror row_mask:0xf bank_mask:0xf bound_ctrl:1
	s_nop 1
	v_add_f32_dpp v52, v52, v52 row_mirror row_mask:0xf bank_mask:0xf bound_ctrl:1
	s_nop 1
	v_mov_b32_dpp v53, v52 row_bcast:15 row_mask:0xa bank_mask:0xf
	v_add_f32_e32 v52, v52, v53
	v_mov_b32_e32 v53, 0
	s_nop 1
	v_mov_b32_dpp v53, v52 row_bcast:31 row_mask:0xc bank_mask:0xf
	v_add_f32_e32 v52, v52, v53
	s_nop 0
	v_readlane_b32 s2, v52, 63
	s_nop 1
	v_add_f32_e32 v52, s2, v86
	v_rsq_f32_e32 v72, v52
	v_cvt_pk_bf16_f32 v52, v61, s0
	ds_write_b16 v119, v52 offset:6784
	v_pk_mul_f32 v[52:53], v[10:11], v[50:51]
	v_mul_f32_e32 v48, v48, v72
	v_mul_f32_e32 v72, v9, v122
	v_fmac_f32_e32 v72, v5, v71
	v_fmac_f32_e32 v72, v7, v134
	v_fmac_f32_e32 v72, v105, v129
	v_mul_f32_e32 v71, 0xbfb8aa3b, v72
	v_exp_f32_e32 v71, v71
	v_mul_f32_e32 v48, 0x3e000000, v48
	v_cvt_pk_bf16_f32 v48, v48, s0
	ds_write_b16 v124, v48 offset:2816
	v_add_f32_e32 v48, 1.0, v71
	v_rcp_f32_e32 v48, v48
	v_mov_b32_e32 v78, v52
	v_lshlrev_b32_e32 v52, 16, v216
	v_mul_f32_e32 v71, v72, v48
	v_mul_f32_e32 v48, v71, v71
	v_mov_b32_e32 v72, 0
	s_nop 1
	v_mov_b32_dpp v72, v48 quad_perm:[1,0,3,2] row_mask:0xf bank_mask:0xf
	v_fmac_f32_e32 v72, v71, v71
	s_nop 1
	v_add_f32_dpp v48, v72, v72 quad_perm:[2,3,0,1] row_mask:0xf bank_mask:0xf bound_ctrl:1
	v_mov_b32_e32 v72, 0
	s_nop 0
	v_add_f32_dpp v48, v48, v48 row_half_mirror row_mask:0xf bank_mask:0xf bound_ctrl:1
	s_nop 1
	v_add_f32_dpp v48, v48, v48 row_mirror row_mask:0xf bank_mask:0xf bound_ctrl:1
	s_nop 1
	v_mov_b32_dpp v72, v48 row_bcast:15 row_mask:0xa bank_mask:0xf
	v_add_f32_e32 v76, v48, v72
	v_mov_b32_e32 v48, v62
	v_mov_b32_e32 v72, v63
	v_pk_add_f32 v[48:49], v[48:49], v[72:73]
	v_mul_f32_e32 v63, v11, v52
	v_pk_add_f32 v[48:49], v[48:49], v[78:79]
	v_mov_b32_e32 v62, v53
	v_pk_add_f32 v[48:49], v[48:49], v[62:63]
	v_mov_b32_dpp v120, v76 row_bcast:31 row_mask:0xc bank_mask:0xf
	v_mul_f32_e32 v53, 0xbfb8aa3b, v48
	v_exp_f32_e32 v53, v53
	v_mul_f32_e32 v62, 0xbfb8aa3b, v49
	v_exp_f32_e32 v63, v62
	v_add_f32_e32 v70, v76, v120
	v_add_f32_e32 v53, 1.0, v53
	v_rcp_f32_e32 v62, v53
	v_add_f32_e32 v53, 1.0, v63
	v_rcp_f32_e32 v63, v53
	v_readlane_b32 s2, v70, 63
	v_mov_b32_e32 v70, 0
	v_pk_mul_f32 v[48:49], v[48:49], v[62:63]
	s_nop 0
	v_pk_mul_f32 v[62:63], v[48:49], v[48:49]
	v_add_f32_e32 v53, s2, v86
	v_rsq_f32_e32 v53, v53
	v_add_f32_dpp v62, v62, v62 quad_perm:[1,0,3,2] row_mask:0xf bank_mask:0xf bound_ctrl:1
	v_add_f32_dpp v63, v63, v63 quad_perm:[1,0,3,2] row_mask:0xf bank_mask:0xf bound_ctrl:1
	v_mul_f32_e32 v53, v71, v53
	v_add_f32_dpp v62, v62, v62 quad_perm:[2,3,0,1] row_mask:0xf bank_mask:0xf bound_ctrl:1
	v_add_f32_dpp v63, v63, v63 quad_perm:[2,3,0,1] row_mask:0xf bank_mask:0xf bound_ctrl:1
	v_mul_f32_e32 v53, 0x3e000000, v53
	v_add_f32_dpp v62, v62, v62 row_half_mirror row_mask:0xf bank_mask:0xf bound_ctrl:1
	v_add_f32_dpp v63, v63, v63 row_half_mirror row_mask:0xf bank_mask:0xf bound_ctrl:1
	v_cvt_pk_bf16_f32 v53, v53, s0
	v_add_f32_dpp v62, v62, v62 row_mirror row_mask:0xf bank_mask:0xf bound_ctrl:1
	v_add_f32_dpp v63, v63, v63 row_mirror row_mask:0xf bank_mask:0xf bound_ctrl:1
	s_nop 0
	v_mov_b32_dpp v70, v62 row_bcast:15 row_mask:0xa bank_mask:0xf
	v_add_f32_e32 v62, v62, v70
	v_mov_b32_e32 v70, 0
	s_nop 1
	v_mov_b32_dpp v70, v62 row_bcast:31 row_mask:0xc bank_mask:0xf
	v_add_f32_e32 v62, v62, v70
	v_mov_b32_e32 v70, 0
	v_readlane_b32 s2, v62, 63
	s_nop 0
	v_mov_b32_dpp v70, v63 row_bcast:15 row_mask:0xa bank_mask:0xf
	v_add_f32_e32 v63, v63, v70
	v_mov_b32_e32 v70, 0
	v_add_f32_e32 v62, s2, v86
	v_rsq_f32_e32 v62, v62
	v_mov_b32_dpp v70, v63 row_bcast:31 row_mask:0xc bank_mask:0xf
	v_add_f32_e32 v63, v63, v70
	s_nop 0
	v_readlane_b32 s2, v63, 63
	s_nop 1
	v_add_f32_e32 v63, s2, v86
	v_rsq_f32_e32 v63, v63
	s_mov_b32 s2, 0x1c000
	v_add_co_u32_e32 v70, vcc, s2, v44
	v_pk_mul_f32 v[62:63], v[48:49], v[62:63]
	s_nop 0
	v_addc_co_u32_e32 v71, vcc, 0, v45, vcc
	v_cvt_pk_bf16_f32 v48, v62, s0
	ds_write_b16 v124, v48 offset:6912
	ds_write_b16 v125, v53 offset:2944
	v_cvt_pk_bf16_f32 v48, v63, s0
	ds_write_b16 v125, v48 offset:7040
	s_mov_b32 s2, 0x1d000
	v_add_co_u32_e32 v54, vcc, s2, v44
	v_readlane_b32 s2, v3, 21
	s_nop 0
	v_addc_co_u32_e32 v55, vcc, 0, v45, vcc
	v_mov_b32_e32 v48, s2
	s_mov_b32 s2, 0x1e000
	v_add_co_u32_e32 v72, vcc, s2, v44
	s_mov_b32 s2, 0x1f000
	s_nop 0
	v_addc_co_u32_e32 v73, vcc, 0, v45, vcc
	v_mul_f32_e32 v68, s7, v48
	v_add_co_u32_e32 v48, vcc, s2, v44
	s_nop 0
	v_addc_co_u32_e32 v49, vcc, 0, v45, vcc
	v_mul_f32_e32 v120, v61, v68
	v_lshlrev_b32_e32 v68, 16, v212
	v_pk_mul_f32 v[48:49], v[4:5], v[64:65] op_sel_hi:[0,1]
	v_pk_fma_f32 v[48:49], v[2:3], v[66:67], v[48:49] op_sel_hi:[0,1,1]
	v_pk_mov_b32 v[64:65], v[64:65], v[68:69] op_sel:[1,0]
	v_mul_f32_e32 v53, s6, v77
	v_pk_fma_f32 v[48:49], v[6:7], v[64:65], v[48:49] op_sel_hi:[0,1,1]
	v_pk_fma_f32 v[48:49], v[8:9], v[68:69], v[48:49] op_sel_hi:[0,1,1]
	v_mul_f32_e32 v121, v60, v53
	v_mul_f32_e32 v53, 0xbfb8aa3b, v48
	v_exp_f32_e32 v53, v53
	v_mul_f32_e32 v66, 0xbfb8aa3b, v49
	v_exp_f32_e32 v67, v66
	v_readlane_b32 s2, v102, 22
	v_add_f32_e32 v53, 1.0, v53
	v_rcp_f32_e32 v66, v53
	v_add_f32_e32 v53, 1.0, v67
	v_rcp_f32_e32 v67, v53
	v_mov_b32_e32 v74, s3
	v_readlane_b32 s3, v102, 23
	v_mov_b32_e32 v53, s4
	v_pk_mul_f32 v[48:49], v[48:49], v[66:67]
	v_mul_f32_e32 v139, s2, v74
	v_pk_mul_f32 v[48:49], v[48:49], s[2:3]
	v_mul_f32_e32 v140, s3, v53
	s_mov_b64 s[2:3], 0x1c000
	v_lshl_add_u64 v[76:77], v[44:45], 0, s[2:3]
	s_mov_b64 s[2:3], 0x1d000
	v_lshl_add_u64 v[78:79], v[44:45], 0, s[2:3]
	s_mov_b64 s[2:3], 0x1e000
	v_lshl_add_u64 v[66:67], v[44:45], 0, s[2:3]
	s_mov_b64 s[2:3], 0x1f000
	v_lshl_add_u64 v[74:75], v[44:45], 0, s[2:3]
	v_pk_mul_f32 v[44:45], v[14:15], v[50:51]
	v_mul_f32_e32 v50, 0xbfb8aa3b, v149
	v_exp_f32_e32 v50, v50
	v_lshlrev_b32_e32 v53, 16, v221
	v_mul_f32_e32 v123, v62, v139
	v_mul_f32_e32 v122, v63, v140
	v_add_f32_e32 v50, 1.0, v50
	v_rcp_f32_e32 v50, v50
	s_nop 0
	s_nop 0
	v_mov_b32_e32 v66, 0
	v_mul_f32_e32 v50, v149, v50
	v_mul_f32_e32 v55, v50, v50
	v_readlane_b32 s3, v3, 24
	v_mul_f32_e32 v51, v13, v51
	v_mov_b32_dpp v66, v55 quad_perm:[1,0,3,2] row_mask:0xf bank_mask:0xf
	v_fmac_f32_e32 v66, v50, v50
	v_pk_mul_f32 v[70:71], v[10:11], v[52:53]
	v_mul_f32_e32 v73, v10, v53
	v_add_f32_dpp v55, v66, v66 quad_perm:[2,3,0,1] row_mask:0xf bank_mask:0xf bound_ctrl:1
	v_mov_b32_e32 v66, 0
	v_mov_b32_e32 v72, v70
	v_add_f32_dpp v55, v55, v55 row_half_mirror row_mask:0xf bank_mask:0xf bound_ctrl:1
	v_readlane_b32 s4, v3, 25
	v_mul_f32_e32 v77, v9, v133
	v_add_f32_dpp v55, v55, v55 row_mirror row_mask:0xf bank_mask:0xf bound_ctrl:1
	v_fmac_f32_e32 v77, v5, v129
	v_fmac_f32_e32 v77, v7, v128
	v_mov_b32_dpp v66, v55 row_bcast:15 row_mask:0xa bank_mask:0xf
	v_add_f32_e32 v55, v55, v66
	v_mov_b32_e32 v66, 0
	v_fmac_f32_e32 v77, v105, v127
	s_waitcnt vmcnt(0) lgkmcnt(0)
	v_lshlrev_b32_e32 v54, 16, v226
	v_mov_b32_dpp v66, v55 row_bcast:31 row_mask:0xc bank_mask:0xf
	v_add_f32_e32 v55, v55, v66
	v_lshlrev_b32_e32 v142, 16, v227
	v_readlane_b32 s2, v55, 63
	v_cmp_gt_u32_e32 vcc, 32, v22
	v_lshlrev_b32_e32 v141, 16, v228
	v_add_f32_e32 v55, s2, v86
	v_rsq_f32_e32 v66, v55
	v_readlane_b32 s2, v102, 24
	v_lshlrev_b32_e32 v55, 16, v229
	v_lshlrev_b32_e32 v143, 16, v230
	v_mul_f32_e32 v50, v50, v66
	v_mul_f32_e32 v66, v9, v129
	v_fmac_f32_e32 v66, v5, v134
	v_fmac_f32_e32 v66, v7, v133
	v_fmac_f32_e32 v66, v105, v128
	v_mul_f32_e32 v67, 0xbfb8aa3b, v66
	v_exp_f32_e32 v67, v67
	v_mul_f32_e32 v50, 0x3e000000, v50
	v_cvt_pk_bf16_f32 v50, v50, s0
	ds_write_b16 v114, v50 offset:3072
	v_add_f32_e32 v50, 1.0, v67
	v_rcp_f32_e32 v50, v50
	v_mov_b32_e32 v67, s3
	v_mul_f32_e32 v74, s2, v67
	v_mov_b32_e32 v67, 0
	v_mul_f32_e32 v50, v66, v50
	v_mul_f32_e32 v66, v50, v50
	s_nop 1
	v_mov_b32_dpp v67, v66 quad_perm:[1,0,3,2] row_mask:0xf bank_mask:0xf
	v_fmac_f32_e32 v67, v50, v50
	s_nop 1
	v_add_f32_dpp v66, v67, v67 quad_perm:[2,3,0,1] row_mask:0xf bank_mask:0xf bound_ctrl:1
	v_mov_b32_e32 v67, 0
	s_nop 0
	v_add_f32_dpp v66, v66, v66 row_half_mirror row_mask:0xf bank_mask:0xf bound_ctrl:1
	s_nop 1
	v_add_f32_dpp v66, v66, v66 row_mirror row_mask:0xf bank_mask:0xf bound_ctrl:1
	s_nop 1
	v_mov_b32_dpp v67, v66 row_bcast:15 row_mask:0xa bank_mask:0xf
	v_add_f32_e32 v66, v66, v67
	v_mov_b32_e32 v67, 0
	s_nop 1
	v_mov_b32_dpp v67, v66 row_bcast:31 row_mask:0xc bank_mask:0xf
	v_add_f32_e32 v66, v66, v67
	v_mul_f32_e32 v67, v12, v52
	v_readlane_b32 s3, v66, 63
	s_nop 1
	v_add_f32_e32 v66, s3, v86
	v_rsq_f32_e32 v66, v66
	v_readlane_b32 s3, v102, 25
	v_mul_f32_e32 v50, v50, v66
	v_mul_f32_e32 v75, 0x3e000000, v50
	v_mov_b32_e32 v50, v44
	v_mov_b32_e32 v66, v45
	v_pk_add_f32 v[44:45], v[50:51], v[66:67]
	v_lshlrev_b32_e32 v51, 16, v222
	v_lshlrev_b32_e32 v50, 16, v223
	v_pk_mul_f32 v[66:67], v[4:5], v[68:69] op_sel_hi:[0,1]
	v_pk_fma_f32 v[64:65], v[2:3], v[64:65], v[66:67] op_sel_hi:[0,1,1]
	v_pk_mov_b32 v[66:67], v[68:69], v[50:51] op_sel:[1,0]
	v_pk_add_f32 v[72:73], v[44:45], v[72:73]
	v_pk_fma_f32 v[64:65], v[6:7], v[66:67], v[64:65] op_sel_hi:[0,1,1]
	v_pk_fma_f32 v[64:65], v[8:9], v[50:51], v[64:65] op_sel_hi:[0,1,1]
	v_mul_f32_e32 v68, 0xbfb8aa3b, v64
	v_mul_f32_e32 v69, 0xbfb8aa3b, v65
	v_exp_f32_e32 v68, v68
	v_exp_f32_e32 v69, v69
	v_cvt_pk_bf16_f32 v75, v75, s0
	v_add_f32_e32 v44, 1.0, v68
	v_add_f32_e32 v45, 1.0, v69
	v_rcp_f32_e32 v44, v44
	v_rcp_f32_e32 v45, v45
	v_lshlrev_b32_e32 v68, 16, v224
	v_pk_mul_f32 v[44:45], v[64:65], v[44:45]
	v_mov_b32_e32 v64, s4
	v_mul_f32_e32 v76, s3, v64
	v_mul_f32_e32 v65, v11, v68
	v_mov_b32_e32 v64, v71
	v_pk_add_f32 v[64:65], v[72:73], v[64:65]
	v_pk_mul_f32 v[72:73], v[14:15], v[52:53]
	v_mul_f32_e32 v69, 0xbfb8aa3b, v64
	v_exp_f32_e32 v69, v69
	v_mul_f32_e32 v70, 0xbfb8aa3b, v65
	v_exp_f32_e32 v71, v70
	v_pk_mul_f32 v[44:45], v[44:45], s[2:3]
	v_add_f32_e32 v69, 1.0, v69
	v_rcp_f32_e32 v70, v69
	v_add_f32_e32 v69, 1.0, v71
	v_rcp_f32_e32 v71, v69
	v_mov_b32_e32 v69, 0
	v_readlane_b32 s3, v3, 26
	v_mul_f32_e32 v53, v13, v53
	v_pk_mul_f32 v[64:65], v[64:65], v[70:71]
	v_readlane_b32 s4, v3, 27
	v_pk_mul_f32 v[70:71], v[64:65], v[64:65]
	s_nop 1
	v_add_f32_dpp v52, v70, v70 quad_perm:[1,0,3,2] row_mask:0xf bank_mask:0xf bound_ctrl:1
	s_nop 1
	v_add_f32_dpp v52, v52, v52 quad_perm:[2,3,0,1] row_mask:0xf bank_mask:0xf bound_ctrl:1
	s_nop 1
	v_add_f32_dpp v52, v52, v52 row_half_mirror row_mask:0xf bank_mask:0xf bound_ctrl:1
	s_nop 1
	v_add_f32_dpp v52, v52, v52 row_mirror row_mask:0xf bank_mask:0xf bound_ctrl:1
	s_nop 1
	v_mov_b32_dpp v69, v52 row_bcast:15 row_mask:0xa bank_mask:0xf
	v_add_f32_e32 v52, v52, v69
	v_mov_b32_e32 v69, 0
	s_nop 1
	v_mov_b32_dpp v69, v52 row_bcast:31 row_mask:0xc bank_mask:0xf
	v_add_f32_e32 v52, v52, v69
	v_mov_b32_e32 v69, 0
	v_readlane_b32 s2, v52, 63
	s_nop 1
	v_add_f32_e32 v52, s2, v86
	v_rsq_f32_e32 v70, v52
	s_nop 0
	v_add_f32_dpp v52, v71, v71 quad_perm:[1,0,3,2] row_mask:0xf bank_mask:0xf bound_ctrl:1
	s_nop 1
	v_add_f32_dpp v52, v52, v52 quad_perm:[2,3,0,1] row_mask:0xf bank_mask:0xf bound_ctrl:1
	s_nop 1
	v_add_f32_dpp v52, v52, v52 row_half_mirror row_mask:0xf bank_mask:0xf bound_ctrl:1
	s_nop 1
	v_add_f32_dpp v52, v52, v52 row_mirror row_mask:0xf bank_mask:0xf bound_ctrl:1
	s_nop 1
	v_mov_b32_dpp v69, v52 row_bcast:15 row_mask:0xa bank_mask:0xf
	v_add_f32_e32 v52, v52, v69
	v_mov_b32_e32 v69, 0
	s_nop 1
	v_mov_b32_dpp v69, v52 row_bcast:31 row_mask:0xc bank_mask:0xf
	v_add_f32_e32 v52, v52, v69
	v_lshlrev_b32_e32 v69, 16, v225
	v_readlane_b32 s2, v52, 63
	v_mul_f32_e32 v135, v10, v69
	v_mul_f32_e32 v13, v13, v69
	v_add_f32_e32 v52, s2, v86
	v_rsq_f32_e32 v71, v52
	v_mul_f32_e32 v52, 0xbfb8aa3b, v77
	v_exp_f32_e32 v52, v52
	v_pk_mul_f32 v[64:65], v[64:65], v[70:71]
	s_nop 0
	v_cvt_pk_bf16_f32 v70, v64, s0
	v_add_f32_e32 v52, 1.0, v52
	v_rcp_f32_e32 v52, v52
	ds_write_b16 v114, v70 offset:7168
	ds_write_b16 v116, v75 offset:3200
	v_mov_b32_e32 v75, 0
	v_mul_f32_e32 v52, v77, v52
	v_mul_f32_e32 v71, v52, v52
	v_cvt_pk_bf16_f32 v70, v65, s0
	ds_write_b16 v116, v70 offset:7296
	v_mov_b32_dpp v75, v71 quad_perm:[1,0,3,2] row_mask:0xf bank_mask:0xf
	v_fmac_f32_e32 v75, v52, v52
	v_mul_f32_e32 v74, v64, v74
	s_nop 0
	v_add_f32_dpp v71, v75, v75 quad_perm:[2,3,0,1] row_mask:0xf bank_mask:0xf bound_ctrl:1
	v_mov_b32_e32 v75, 0
	s_nop 0
	v_add_f32_dpp v71, v71, v71 row_half_mirror row_mask:0xf bank_mask:0xf bound_ctrl:1
	s_nop 1
	v_add_f32_dpp v71, v71, v71 row_mirror row_mask:0xf bank_mask:0xf bound_ctrl:1
	s_nop 1
	v_mov_b32_dpp v75, v71 row_bcast:15 row_mask:0xa bank_mask:0xf
	v_add_f32_e32 v71, v71, v75
	v_mov_b32_e32 v75, 0
	s_nop 1
	v_mov_b32_dpp v75, v71 row_bcast:31 row_mask:0xc bank_mask:0xf
	v_add_f32_e32 v71, v71, v75
	v_mul_f32_e32 v75, v65, v76
	v_readlane_b32 s2, v71, 63
	v_mul_f32_e32 v76, v9, v128
	v_fmac_f32_e32 v76, v5, v133
	v_add_f32_e32 v71, s2, v86
	v_rsq_f32_e32 v77, v71
	v_fmac_f32_e32 v76, v7, v127
	v_fmac_f32_e32 v76, v105, v126
	v_readlane_b32 s2, v102, 26
	v_mul_f32_e32 v52, v52, v77
	v_mul_f32_e32 v77, 0xbfb8aa3b, v76
	v_exp_f32_e32 v77, v77
	v_mul_f32_e32 v52, 0x3e000000, v52
	v_cvt_pk_bf16_f32 v52, v52, s0
	ds_write_b16 v115, v52 offset:3328
	v_add_f32_e32 v52, 1.0, v77
	v_rcp_f32_e32 v52, v52
	v_mov_b32_e32 v77, s3
	v_mul_f32_e32 v114, s2, v77
	v_mov_b32_e32 v77, 0
	v_mul_f32_e32 v52, v76, v52
	v_mul_f32_e32 v76, v52, v52
	v_pk_mul_f32 v[70:71], v[10:11], v[68:69]
	s_nop 0
	v_mov_b32_dpp v77, v76 quad_perm:[1,0,3,2] row_mask:0xf bank_mask:0xf
	v_fmac_f32_e32 v77, v52, v52
	v_mov_b32_e32 v134, v70
	s_nop 0
	v_add_f32_dpp v76, v77, v77 quad_perm:[2,3,0,1] row_mask:0xf bank_mask:0xf bound_ctrl:1
	v_mov_b32_e32 v77, 0
	s_nop 0
	v_add_f32_dpp v76, v76, v76 row_half_mirror row_mask:0xf bank_mask:0xf bound_ctrl:1
	s_nop 1
	v_add_f32_dpp v76, v76, v76 row_mirror row_mask:0xf bank_mask:0xf bound_ctrl:1
	s_nop 1
	v_mov_b32_dpp v77, v76 row_bcast:15 row_mask:0xa bank_mask:0xf
	v_add_f32_e32 v76, v76, v77
	v_mov_b32_e32 v77, 0
	s_nop 1
	v_mov_b32_dpp v77, v76 row_bcast:31 row_mask:0xc bank_mask:0xf
	v_add_f32_e32 v76, v76, v77
	v_mul_f32_e32 v77, v12, v68
	v_readlane_b32 s3, v76, 63
	s_nop 1
	v_add_f32_e32 v76, s3, v86
	v_rsq_f32_e32 v76, v76
	v_readlane_b32 s3, v102, 27
	v_mul_f32_e32 v52, v52, v76
	v_mul_f32_e32 v116, 0x3e000000, v52
	v_mov_b32_e32 v52, v72
	v_mov_b32_e32 v76, v73
	v_pk_add_f32 v[76:77], v[52:53], v[76:77]
	v_lshlrev_b32_e32 v53, 16, v231
	v_lshlrev_b32_e32 v52, 16, v232
	v_pk_mul_f32 v[72:73], v[4:5], v[50:51] op_sel_hi:[0,1]
	v_pk_fma_f32 v[66:67], v[2:3], v[66:67], v[72:73] op_sel_hi:[0,1,1]
	v_pk_mov_b32 v[72:73], v[50:51], v[52:53] op_sel:[1,0]
	v_mul_f32_e32 v131, v9, v127
	v_pk_fma_f32 v[50:51], v[6:7], v[72:73], v[66:67] op_sel_hi:[0,1,1]
	v_pk_fma_f32 v[50:51], v[8:9], v[52:53], v[50:51] op_sel_hi:[0,1,1]
	v_mul_f32_e32 v66, 0xbfb8aa3b, v50
	v_exp_f32_e32 v70, v66
	v_mul_f32_e32 v66, 0xbfb8aa3b, v51
	v_exp_f32_e32 v129, v66
	v_pk_add_f32 v[66:67], v[76:77], v[134:135]
	v_add_f32_e32 v70, 1.0, v70
	v_rcp_f32_e32 v76, v70
	v_add_f32_e32 v70, 1.0, v129
	v_rcp_f32_e32 v77, v70
	v_lshlrev_b32_e32 v70, 16, v233
	v_fmac_f32_e32 v131, v5, v128
	v_fmac_f32_e32 v131, v7, v126
	v_pk_mul_f32 v[50:51], v[50:51], v[76:77]
	v_mul_f32_e32 v77, v11, v70
	v_mov_b32_e32 v76, v71
	v_pk_add_f32 v[66:67], v[66:67], v[76:77]
	v_pk_mul_f32 v[50:51], v[50:51], s[2:3]
	v_mul_f32_e32 v71, 0xbfb8aa3b, v66
	v_exp_f32_e32 v71, v71
	v_mul_f32_e32 v76, 0xbfb8aa3b, v67
	v_exp_f32_e32 v77, v76
	v_mov_b32_e32 v129, s4
	v_add_f32_e32 v71, 1.0, v71
	v_rcp_f32_e32 v76, v71
	v_add_f32_e32 v71, 1.0, v77
	v_rcp_f32_e32 v77, v71
	v_fmac_f32_e32 v131, v105, v54
	v_mul_f32_e32 v130, s3, v129
	v_pk_mul_f32 v[128:129], v[14:15], v[68:69]
	v_pk_mul_f32 v[66:67], v[66:67], v[76:77]
	v_mul_f32_e32 v68, 0xbfb8aa3b, v131
	v_pk_mul_f32 v[76:77], v[66:67], v[66:67]
	v_exp_f32_e32 v68, v68
	v_cvt_pk_bf16_f32 v116, v116, s0
	v_add_f32_dpp v71, v76, v76 quad_perm:[1,0,3,2] row_mask:0xf bank_mask:0xf bound_ctrl:1
	v_mov_b32_e32 v76, 0
	v_add_f32_e32 v68, 1.0, v68
	v_add_f32_dpp v71, v71, v71 quad_perm:[2,3,0,1] row_mask:0xf bank_mask:0xf bound_ctrl:1
	v_rcp_f32_e32 v68, v68
	v_readlane_b32 s3, v3, 28
	v_add_f32_dpp v71, v71, v71 row_half_mirror row_mask:0xf bank_mask:0xf bound_ctrl:1
	v_mul_f32_e32 v69, v12, v70
	v_mul_f32_e32 v68, v131, v68
	v_add_f32_dpp v71, v71, v71 row_mirror row_mask:0xf bank_mask:0xf bound_ctrl:1
	v_readlane_b32 s4, v3, 29
	s_nop 0
	v_mov_b32_dpp v76, v71 row_bcast:15 row_mask:0xa bank_mask:0xf
	v_add_f32_e32 v71, v71, v76
	v_mov_b32_e32 v76, 0
	s_nop 1
	v_mov_b32_dpp v76, v71 row_bcast:31 row_mask:0xc bank_mask:0xf
	v_add_f32_e32 v71, v71, v76
	s_nop 0
	v_readlane_b32 s2, v71, 63
	s_nop 1
	v_add_f32_e32 v71, s2, v86
	v_rsq_f32_e32 v76, v71
	s_nop 0
	v_add_f32_dpp v71, v77, v77 quad_perm:[1,0,3,2] row_mask:0xf bank_mask:0xf bound_ctrl:1
	v_mov_b32_e32 v77, 0
	s_nop 0
	v_add_f32_dpp v71, v71, v71 quad_perm:[2,3,0,1] row_mask:0xf bank_mask:0xf bound_ctrl:1
	s_nop 1
	v_add_f32_dpp v71, v71, v71 row_half_mirror row_mask:0xf bank_mask:0xf bound_ctrl:1
	s_nop 1
	v_add_f32_dpp v71, v71, v71 row_mirror row_mask:0xf bank_mask:0xf bound_ctrl:1
	s_nop 1
	v_mov_b32_dpp v77, v71 row_bcast:15 row_mask:0xa bank_mask:0xf
	v_add_f32_e32 v71, v71, v77
	v_mov_b32_e32 v77, 0
	s_nop 1
	v_mov_b32_dpp v77, v71 row_bcast:31 row_mask:0xc bank_mask:0xf
	v_add_f32_e32 v71, v71, v77
	s_nop 0
	v_readlane_b32 s2, v71, 63
	s_nop 1
	v_add_f32_e32 v71, s2, v86
	v_rsq_f32_e32 v77, v71
	v_lshlrev_b32_e32 v71, 16, v234
	v_pk_mul_f32 v[66:67], v[66:67], v[76:77]
	s_nop 0
	v_cvt_pk_bf16_f32 v76, v66, s0
	v_cvt_pk_bf16_f32 v77, v67, s0
	ds_write_b16 v115, v76 offset:7424
	v_mul_f32_e32 v76, v66, v114
	ds_write_b16 v117, v77 offset:7552
	v_mul_f32_e32 v77, v68, v68
	v_mov_b32_e32 v114, 0
	ds_write_b16 v117, v116 offset:3456
	s_nop 0
	v_mov_b32_dpp v114, v77 quad_perm:[1,0,3,2] row_mask:0xf bank_mask:0xf
	v_fmac_f32_e32 v114, v68, v68
	s_nop 1
	v_add_f32_dpp v77, v114, v114 quad_perm:[2,3,0,1] row_mask:0xf bank_mask:0xf bound_ctrl:1
	v_mov_b32_e32 v114, 0
	s_nop 0
	v_add_f32_dpp v77, v77, v77 row_half_mirror row_mask:0xf bank_mask:0xf bound_ctrl:1
	s_nop 1
	v_add_f32_dpp v77, v77, v77 row_mirror row_mask:0xf bank_mask:0xf bound_ctrl:1
	s_nop 1
	v_mov_b32_dpp v114, v77 row_bcast:15 row_mask:0xa bank_mask:0xf
	v_add_f32_e32 v77, v77, v114
	v_mov_b32_e32 v114, 0
	s_nop 1
	v_mov_b32_dpp v114, v77 row_bcast:31 row_mask:0xc bank_mask:0xf
	v_add_f32_e32 v77, v77, v114
	v_pk_mul_f32 v[114:115], v[10:11], v[70:71]
	v_readlane_b32 s2, v77, 63
	s_nop 1
	v_add_f32_e32 v77, s2, v86
	v_rsq_f32_e32 v116, v77
	v_readlane_b32 s2, v102, 28
	v_mul_f32_e32 v77, v67, v130
	v_mul_f32_e32 v68, v68, v116
	v_mul_f32_e32 v116, v9, v126
	v_fmac_f32_e32 v116, v5, v127
	v_fmac_f32_e32 v116, v7, v54
	v_fmac_f32_e32 v116, v105, v142
	v_mul_f32_e32 v117, 0xbfb8aa3b, v116
	v_exp_f32_e32 v117, v117
	v_mul_f32_e32 v68, 0x3e000000, v68
	v_cvt_pk_bf16_f32 v68, v68, s0
	ds_write_b16 v118, v68 offset:3584
	v_add_f32_e32 v68, 1.0, v117
	v_rcp_f32_e32 v68, v68
	v_mov_b32_e32 v117, s3
	v_mul_f32_e32 v130, s2, v117
	v_mov_b32_e32 v117, 0
	v_mul_f32_e32 v68, v116, v68
	v_mul_f32_e32 v116, v68, v68
	s_nop 1
	v_mov_b32_dpp v117, v116 quad_perm:[1,0,3,2] row_mask:0xf bank_mask:0xf
	v_fmac_f32_e32 v117, v68, v68
	s_nop 1
	v_add_f32_dpp v116, v117, v117 quad_perm:[2,3,0,1] row_mask:0xf bank_mask:0xf bound_ctrl:1
	v_mov_b32_e32 v117, 0
	s_nop 0
	v_add_f32_dpp v116, v116, v116 row_half_mirror row_mask:0xf bank_mask:0xf bound_ctrl:1
	s_nop 1
	v_add_f32_dpp v116, v116, v116 row_mirror row_mask:0xf bank_mask:0xf bound_ctrl:1
	s_nop 1
	v_mov_b32_dpp v117, v116 row_bcast:15 row_mask:0xa bank_mask:0xf
	v_add_f32_e32 v116, v116, v117
	v_mov_b32_e32 v117, 0
	s_nop 1
	v_mov_b32_dpp v117, v116 row_bcast:31 row_mask:0xc bank_mask:0xf
	v_add_f32_e32 v116, v116, v117
	v_mul_f32_e32 v117, v10, v71
	v_readlane_b32 s3, v116, 63
	s_nop 1
	v_add_f32_e32 v116, s3, v86
	v_rsq_f32_e32 v116, v116
	v_readlane_b32 s3, v102, 29
	v_mul_f32_e32 v12, v68, v116
	v_mul_f32_e32 v127, 0x3e000000, v12
	v_mov_b32_e32 v12, v128
	v_mov_b32_e32 v68, v129
	v_pk_add_f32 v[128:129], v[12:13], v[68:69]
	v_lshlrev_b32_e32 v13, 16, v242
	v_lshlrev_b32_e32 v12, 16, v152
	v_pk_mul_f32 v[68:69], v[4:5], v[52:53] op_sel_hi:[0,1]
	v_pk_fma_f32 v[72:73], v[2:3], v[72:73], v[68:69] op_sel_hi:[0,1,1]
	v_pk_mov_b32 v[68:69], v[52:53], v[12:13] op_sel:[1,0]
	v_mov_b32_e32 v116, v114
	v_pk_fma_f32 v[52:53], v[6:7], v[68:69], v[72:73] op_sel_hi:[0,1,1]
	v_pk_fma_f32 v[52:53], v[8:9], v[12:13], v[52:53] op_sel_hi:[0,1,1]
	v_mul_f32_e32 v72, 0xbfb8aa3b, v52
	v_exp_f32_e32 v79, v72
	v_mul_f32_e32 v72, 0xbfb8aa3b, v53
	v_exp_f32_e32 v114, v72
	v_pk_add_f32 v[72:73], v[128:129], v[116:117]
	v_add_f32_e32 v79, 1.0, v79
	v_rcp_f32_e32 v116, v79
	v_add_f32_e32 v79, 1.0, v114
	v_rcp_f32_e32 v117, v79
	v_lshlrev_b32_e32 v114, 16, v153
	v_cvt_pk_bf16_f32 v79, v127, s0
	v_mov_b32_e32 v127, s4
	v_pk_mul_f32 v[52:53], v[52:53], v[116:117]
	v_mul_f32_e32 v117, v11, v114
	v_mov_b32_e32 v116, v115
	v_pk_add_f32 v[72:73], v[72:73], v[116:117]
	v_pk_mul_f32 v[52:53], v[52:53], s[2:3]
	v_mul_f32_e32 v115, 0xbfb8aa3b, v72
	v_exp_f32_e32 v115, v115
	v_mul_f32_e32 v116, 0xbfb8aa3b, v73
	v_exp_f32_e32 v117, v116
	v_mul_f32_e32 v129, v9, v54
	v_add_f32_e32 v115, 1.0, v115
	v_rcp_f32_e32 v116, v115
	v_add_f32_e32 v115, 1.0, v117
	v_rcp_f32_e32 v117, v115
	v_mul_f32_e32 v128, s3, v127
	v_fmac_f32_e32 v129, v5, v126
	v_pk_mul_f32 v[126:127], v[14:15], v[70:71]
	v_pk_mul_f32 v[72:73], v[72:73], v[116:117]
	v_fmac_f32_e32 v129, v7, v142
	v_pk_mul_f32 v[116:117], v[72:73], v[72:73]
	v_fmac_f32_e32 v129, v105, v141
	v_mul_f32_e32 v9, v9, v142
	v_add_f32_dpp v115, v116, v116 quad_perm:[1,0,3,2] row_mask:0xf bank_mask:0xf bound_ctrl:1
	v_mov_b32_e32 v116, 0
	v_fmac_f32_e32 v9, v5, v54
	v_add_f32_dpp v115, v115, v115 quad_perm:[2,3,0,1] row_mask:0xf bank_mask:0xf bound_ctrl:1
	v_fmac_f32_e32 v9, v7, v141
	v_fmac_f32_e32 v9, v105, v143
	v_add_f32_dpp v115, v115, v115 row_half_mirror row_mask:0xf bank_mask:0xf bound_ctrl:1
	v_mul_f32_e32 v7, 0xbfb8aa3b, v9
	v_exp_f32_e32 v7, v7
	v_add_f32_dpp v115, v115, v115 row_mirror row_mask:0xf bank_mask:0xf bound_ctrl:1
	v_readlane_b32 s3, v3, 30
	v_readlane_b32 s4, v3, 31
	v_mov_b32_dpp v116, v115 row_bcast:15 row_mask:0xa bank_mask:0xf
	v_add_f32_e32 v115, v115, v116
	v_mov_b32_e32 v116, 0
	v_add_f32_e32 v7, 1.0, v7
	v_rcp_f32_e32 v7, v7
	v_mov_b32_dpp v116, v115 row_bcast:31 row_mask:0xc bank_mask:0xf
	v_add_f32_e32 v115, v115, v116
	v_mul_f32_e32 v7, v9, v7
	v_readlane_b32 s2, v115, 63
	v_mov_b32_e32 v9, 0
	s_nop 0
	v_add_f32_e32 v115, s2, v86
	v_rsq_f32_e32 v116, v115
	s_nop 0
	v_add_f32_dpp v115, v117, v117 quad_perm:[1,0,3,2] row_mask:0xf bank_mask:0xf bound_ctrl:1
	v_mov_b32_e32 v117, 0
	s_nop 0
	v_add_f32_dpp v115, v115, v115 quad_perm:[2,3,0,1] row_mask:0xf bank_mask:0xf bound_ctrl:1
	s_nop 1
	v_add_f32_dpp v115, v115, v115 row_half_mirror row_mask:0xf bank_mask:0xf bound_ctrl:1
	s_nop 1
	v_add_f32_dpp v115, v115, v115 row_mirror row_mask:0xf bank_mask:0xf bound_ctrl:1
	s_nop 1
	v_mov_b32_dpp v117, v115 row_bcast:15 row_mask:0xa bank_mask:0xf
	v_add_f32_e32 v115, v115, v117
	v_mov_b32_e32 v117, 0
	s_nop 1
	v_mov_b32_dpp v117, v115 row_bcast:31 row_mask:0xc bank_mask:0xf
	v_add_f32_e32 v115, v115, v117
	s_nop 0
	v_readlane_b32 s2, v115, 63
	s_nop 1
	v_add_f32_e32 v115, s2, v86
	v_rsq_f32_e32 v117, v115
	v_lshlrev_b32_e32 v115, 16, v154
	v_mov_b32_e32 v54, v115
	v_pk_mul_f32 v[72:73], v[72:73], v[116:117]
	s_nop 0
	v_cvt_pk_bf16_f32 v70, v72, s0
	ds_write_b16 v118, v70 offset:7680
	v_pk_mul_f32 v[116:117], v[10:11], v[114:115]
	v_add_f32_e32 v70, v126, v127
	v_add_f32_e32 v70, v70, v116
	ds_write_b16 v119, v79 offset:3712
	v_add_f32_e32 v70, v70, v117
	v_mul_f32_e32 v79, 0xbfb8aa3b, v129
	v_exp_f32_e32 v79, v79
	v_mul_f32_e32 v116, 0xbfb8aa3b, v70
	v_exp_f32_e32 v116, v116
	v_cvt_pk_bf16_f32 v117, v73, s0
	v_add_f32_e32 v79, 1.0, v79
	v_rcp_f32_e32 v118, v79
	v_add_f32_e32 v79, 1.0, v116
	v_rcp_f32_e32 v116, v79
	ds_write_b16 v119, v117 offset:7808
	v_mul_f32_e32 v117, v129, v118
	v_mov_b32_e32 v118, 0
	v_mul_f32_e32 v116, v70, v116
	v_mul_f32_e32 v70, v117, v117
	v_pk_mul_f32 v[10:11], v[10:11], v[54:55]
	v_lshlrev_b32_e32 v54, 16, v155
	v_mov_b32_dpp v118, v70 quad_perm:[1,0,3,2] row_mask:0xf bank_mask:0xf
	v_fmac_f32_e32 v118, v117, v117
	v_lshlrev_b32_e32 v55, 16, v156
	v_mul_f32_e32 v78, v72, v130
	v_add_f32_dpp v70, v118, v118 quad_perm:[2,3,0,1] row_mask:0xf bank_mask:0xf bound_ctrl:1
	v_mov_b32_e32 v118, 0
	v_mul_f32_e32 v79, v73, v128
	v_add_f32_dpp v70, v70, v70 row_half_mirror row_mask:0xf bank_mask:0xf bound_ctrl:1
	v_and_b32_e32 v127, 7, v22
	s_nop 0
	v_add_f32_dpp v70, v70, v70 row_mirror row_mask:0xf bank_mask:0xf bound_ctrl:1
	s_nop 1
	v_mov_b32_dpp v118, v70 row_bcast:15 row_mask:0xa bank_mask:0xf
	v_add_f32_e32 v70, v70, v118
	v_mov_b32_e32 v118, 0
	s_nop 1
	v_mov_b32_dpp v118, v70 row_bcast:31 row_mask:0xc bank_mask:0xf
	v_add_f32_e32 v70, v70, v118
	v_mov_b32_e32 v118, 0
	v_readlane_b32 s2, v70, 63
	v_mul_f32_e32 v70, v116, v116
	s_nop 0
	v_add_f32_e32 v119, s2, v86
	v_mov_b32_dpp v118, v70 quad_perm:[1,0,3,2] row_mask:0xf bank_mask:0xf
	v_fmac_f32_e32 v118, v116, v116
	v_rsq_f32_e32 v119, v119
	s_nop 0
	v_add_f32_dpp v70, v118, v118 quad_perm:[2,3,0,1] row_mask:0xf bank_mask:0xf bound_ctrl:1
	v_mov_b32_e32 v118, 0
	s_nop 0
	v_add_f32_dpp v70, v70, v70 row_half_mirror row_mask:0xf bank_mask:0xf bound_ctrl:1
	s_nop 1
	v_add_f32_dpp v70, v70, v70 row_mirror row_mask:0xf bank_mask:0xf bound_ctrl:1
	s_nop 1
	v_mov_b32_dpp v118, v70 row_bcast:15 row_mask:0xa bank_mask:0xf
	v_add_f32_e32 v70, v70, v118
	v_mov_b32_e32 v118, 0
	s_nop 1
	v_mov_b32_dpp v118, v70 row_bcast:31 row_mask:0xc bank_mask:0xf
	v_add_f32_e32 v70, v70, v118
	s_nop 0
	v_readlane_b32 s2, v70, 63
	v_mul_f32_e32 v70, v117, v119
	v_mul_f32_e32 v70, 0x3e000000, v70
	v_cvt_pk_bf16_f32 v70, v70, s0
	ds_write_b16 v124, v70 offset:3840
	v_pk_mov_b32 v[70:71], v[70:71], v[114:115] op_sel:[1,0]
	v_add_f32_e32 v117, s2, v86
	v_pk_mul_f32 v[14:15], v[14:15], v[70:71]
	v_rsq_f32_e32 v118, v117
	v_add_f32_e32 v5, v14, v15
	v_add_f32_e32 v5, v5, v10
	v_add_f32_e32 v5, v5, v11
	v_mul_f32_e32 v10, 0xbfb8aa3b, v5
	v_exp_f32_e32 v10, v10
	v_mov_b32_e32 v119, s3
	v_readlane_b32 s2, v102, 30
	v_mov_b32_e32 v15, s4
	v_add_f32_e32 v10, 1.0, v10
	v_rcp_f32_e32 v10, v10
	v_mov_b32_e32 v117, s2
	v_pk_mul_f32 v[116:117], v[116:117], v[118:119]
	v_add_u32_e32 v119, 4, v109
	v_mul_f32_e32 v10, v5, v10
	v_mul_f32_e32 v5, v7, v7
	v_cvt_pk_bf16_f32 v11, v116, s0
	ds_write_b16 v124, v11 offset:7936
	v_mov_b32_dpp v9, v5 quad_perm:[1,0,3,2] row_mask:0xf bank_mask:0xf
	v_fmac_f32_e32 v9, v7, v7
	v_mul_f32_e32 v105, v116, v117
	v_add_u32_e32 v117, 2, v109
	v_add_f32_dpp v5, v9, v9 quad_perm:[2,3,0,1] row_mask:0xf bank_mask:0xf bound_ctrl:1
	v_mov_b32_e32 v9, 0
	v_lshlrev_b32_e32 v115, 2, v109
	v_add_f32_dpp v5, v5, v5 row_half_mirror row_mask:0xf bank_mask:0xf bound_ctrl:1
	v_sub_u32_e32 v128, v96, v115
	s_movk_i32 s4, 0x50
	v_add_f32_dpp v5, v5, v5 row_mirror row_mask:0xf bank_mask:0xf bound_ctrl:1
	s_nop 1
	v_mov_b32_dpp v9, v5 row_bcast:15 row_mask:0xa bank_mask:0xf
	v_add_f32_e32 v5, v5, v9
	v_mov_b32_e32 v9, 0
	s_nop 1
	v_mov_b32_dpp v9, v5 row_bcast:31 row_mask:0xc bank_mask:0xf
	v_add_f32_e32 v5, v5, v9
	v_mov_b32_e32 v9, 0
	v_readlane_b32 s3, v5, 63
	v_mul_f32_e32 v5, v10, v10
	s_nop 0
	v_add_f32_e32 v11, s3, v86
	v_mov_b32_dpp v9, v5 quad_perm:[1,0,3,2] row_mask:0xf bank_mask:0xf
	v_fmac_f32_e32 v9, v10, v10
	v_rsq_f32_e32 v11, v11
	s_nop 0
	v_add_f32_dpp v5, v9, v9 quad_perm:[2,3,0,1] row_mask:0xf bank_mask:0xf bound_ctrl:1
	v_mov_b32_e32 v9, 0
	s_nop 0
	v_add_f32_dpp v5, v5, v5 row_half_mirror row_mask:0xf bank_mask:0xf bound_ctrl:1
	s_nop 1
	v_add_f32_dpp v5, v5, v5 row_mirror row_mask:0xf bank_mask:0xf bound_ctrl:1
	s_nop 1
	v_mov_b32_dpp v9, v5 row_bcast:15 row_mask:0xa bank_mask:0xf
	v_add_f32_e32 v5, v5, v9
	v_mov_b32_e32 v9, 0
	s_nop 1
	v_mov_b32_dpp v9, v5 row_bcast:31 row_mask:0xc bank_mask:0xf
	v_add_f32_e32 v5, v5, v9
	s_nop 0
	v_readlane_b32 s3, v5, 63
	v_mul_f32_e32 v5, v7, v11
	v_mul_f32_e32 v7, 0x3e000000, v5
	v_add_f32_e32 v5, s3, v86
	v_rsq_f32_e32 v14, v5
	v_pk_mul_f32 v[4:5], v[4:5], v[12:13] op_sel_hi:[0,1]
	v_pk_fma_f32 v[4:5], v[2:3], v[68:69], v[4:5] op_sel_hi:[0,1,1]
	v_pk_mov_b32 v[12:13], v[12:13], v[54:55] op_sel:[1,0]
	v_readlane_b32 s3, v102, 31
	v_pk_fma_f32 v[4:5], v[6:7], v[12:13], v[4:5] op_sel_hi:[0,1,1]
	v_pk_fma_f32 v[4:5], v[8:9], v[54:55], v[4:5] op_sel_hi:[0,1,1]
	v_mul_f32_e32 v2, 0xbfb8aa3b, v4
	v_exp_f32_e32 v2, v2
	v_mul_f32_e32 v6, 0xbfb8aa3b, v5
	v_exp_f32_e32 v8, v6
	v_cvt_pk_bf16_f32 v9, v7, s0
	v_add_f32_e32 v2, 1.0, v2
	v_rcp_f32_e32 v6, v2
	v_add_f32_e32 v2, 1.0, v8
	v_rcp_f32_e32 v7, v2
	v_mov_b32_e32 v11, s3
	v_pk_mul_f32 v[10:11], v[10:11], v[14:15]
	ds_write_b16 v125, v9 offset:3968
	v_pk_mul_f32 v[2:3], v[4:5], v[6:7]
	v_cvt_pk_bf16_f32 v4, v64, v65
	v_pk_mul_f32 v[54:55], v[2:3], s[2:3]
	v_cvt_pk_bf16_f32 v2, v10, s0
	ds_write_b16 v125, v2 offset:8064
	v_cvt_pk_bf16_f32 v2, v56, v57
	v_cvt_pk_bf16_f32 v3, v58, v59
	v_cvt_pk_bf16_f32 v5, v66, v67
	v_cvt_pk_bf16_f32 v6, v60, v61
	v_cvt_pk_bf16_f32 v7, v62, v63
	v_cvt_pk_bf16_f32 v8, v72, v73
	v_cvt_pk_bf16_f32 v9, v116, v10
	global_store_dwordx4 v[16:17], v[2:5], off offset:1024
	global_store_dwordx4 v[16:17], v[6:9], off offset:1536
	v_mul_f32_e32 v114, v10, v11
	v_lshlrev_b32_e32 v2, 7, v22
	v_and_b32_e32 v2, 0xf80, v2
	v_add_u32_e32 v64, s51, v2
	v_bitop3_b32 v2, v109, v22, 7 bitop3:0x78
	s_waitcnt lgkmcnt(0)
	v_lshl_add_u32 v116, v2, 4, v64
	ds_read_b128 v[2:5], v116 offset:4096
	ds_read_b128 v[6:9], v116
	s_waitcnt lgkmcnt(0)
	v_mfma_f32_32x32x16_bf16 v[2:17], v[2:5], v[6:9], 0
	v_bitop3_b32 v56, v117, v22, 7 bitop3:0x78
	v_lshl_add_u32 v118, v56, 4, v64
	ds_read_b128 v[56:59], v118 offset:4096
	ds_read_b128 v[60:63], v118
	v_add_u32_e32 v125, 6, v109
	v_readlane_b32 s2, v101, 0
	v_readlane_b32 s3, v101, 4
	s_waitcnt lgkmcnt(0)
	v_mfma_f32_32x32x16_bf16 v[2:17], v[56:59], v[60:63], v[2:17]
	v_bitop3_b32 v56, v119, v22, 7 bitop3:0x78
	v_lshl_add_u32 v124, v56, 4, v64
	ds_read_b128 v[56:59], v124 offset:4096
	ds_read_b128 v[60:63], v124
	s_waitcnt lgkmcnt(0)
	v_mfma_f32_32x32x16_bf16 v[2:17], v[56:59], v[60:63], v[2:17]
	v_bitop3_b32 v56, v125, v22, 7 bitop3:0x78
	v_lshl_add_u32 v126, v56, 4, v64
	ds_read_b128 v[56:59], v126 offset:4096
	ds_read_b128 v[60:63], v126
	s_waitcnt lgkmcnt(0)
	v_mfma_f32_32x32x16_bf16 v[2:17], v[56:59], v[60:63], v[2:17]
	v_mov_b32_e32 v56, s3
	v_mov_b32_e32 v57, s2
	v_cndmask_b32_e32 v56, v56, v57, vcc
	v_sub_f32_e32 v56, v101, v56
	v_mul_f32_e32 v56, 0x3fb8aa3b, v56
	v_readlane_b32 s2, v101, 1
	v_readlane_b32 s3, v101, 5
	v_exp_f32_e32 v64, v56
	v_mov_b32_e32 v57, s2
	v_mov_b32_e32 v56, s3
	v_cndmask_b32_e32 v56, v56, v57, vcc
	v_sub_f32_e32 v56, v101, v56
	v_mul_f32_e32 v56, 0x3fb8aa3b, v56
	v_readlane_b32 s2, v101, 2
	v_readlane_b32 s3, v101, 6
	v_exp_f32_e32 v65, v56
	v_mov_b32_e32 v57, s2
	v_mov_b32_e32 v56, s3
	v_cndmask_b32_e32 v56, v56, v57, vcc
	v_sub_f32_e32 v56, v101, v56
	v_mul_f32_e32 v56, 0x3fb8aa3b, v56
	v_readlane_b32 s2, v101, 3
	v_readlane_b32 s3, v101, 7
	v_exp_f32_e32 v62, v56
	v_mov_b32_e32 v57, s2
	v_mov_b32_e32 v56, s3
	v_cndmask_b32_e32 v56, v56, v57, vcc
	v_sub_f32_e32 v56, v101, v56
	v_mul_f32_e32 v56, 0x3fb8aa3b, v56
	v_readlane_b32 s2, v101, 8
	v_readlane_b32 s3, v101, 12
	v_exp_f32_e32 v63, v56
	v_mov_b32_e32 v57, s2
	v_mov_b32_e32 v56, s3
	v_cndmask_b32_e32 v56, v56, v57, vcc
	v_sub_f32_e32 v56, v101, v56
	v_mul_f32_e32 v56, 0x3fb8aa3b, v56
	v_readlane_b32 s2, v101, 9
	v_readlane_b32 s3, v101, 13
	v_exp_f32_e32 v60, v56
	v_mov_b32_e32 v57, s2
	v_mov_b32_e32 v56, s3
	v_cndmask_b32_e32 v56, v56, v57, vcc
	v_sub_f32_e32 v56, v101, v56
	v_mul_f32_e32 v56, 0x3fb8aa3b, v56
	v_readlane_b32 s2, v101, 10
	v_readlane_b32 s3, v101, 14
	v_exp_f32_e32 v61, v56
	v_mov_b32_e32 v57, s2
	v_mov_b32_e32 v56, s3
	v_cndmask_b32_e32 v56, v56, v57, vcc
	v_sub_f32_e32 v56, v101, v56
	v_mul_f32_e32 v56, 0x3fb8aa3b, v56
	v_readlane_b32 s2, v101, 11
	v_readlane_b32 s3, v101, 15
	v_exp_f32_e32 v58, v56
	v_mov_b32_e32 v57, s2
	v_mov_b32_e32 v56, s3
	v_cndmask_b32_e32 v56, v56, v57, vcc
	v_sub_f32_e32 v56, v101, v56
	v_mul_f32_e32 v56, 0x3fb8aa3b, v56
	v_readlane_b32 s2, v101, 16
	v_readlane_b32 s3, v101, 20
	v_exp_f32_e32 v59, v56
	v_mov_b32_e32 v57, s2
	v_mov_b32_e32 v56, s3
	v_cndmask_b32_e32 v56, v56, v57, vcc
	v_sub_f32_e32 v56, v101, v56
	v_mul_f32_e32 v56, 0x3fb8aa3b, v56
	v_readlane_b32 s2, v101, 17
	v_readlane_b32 s3, v101, 21
	v_exp_f32_e32 v72, v56
	v_mov_b32_e32 v57, s2
	v_mov_b32_e32 v56, s3
	v_cndmask_b32_e32 v56, v56, v57, vcc
	v_sub_f32_e32 v56, v101, v56
	v_mul_f32_e32 v56, 0x3fb8aa3b, v56
	v_readlane_b32 s2, v101, 18
	v_readlane_b32 s3, v101, 22
	v_exp_f32_e32 v73, v56
	v_mov_b32_e32 v57, s2
	v_mov_b32_e32 v56, s3
	v_cndmask_b32_e32 v56, v56, v57, vcc
	v_sub_f32_e32 v56, v101, v56
	v_mul_f32_e32 v56, 0x3fb8aa3b, v56
	v_readlane_b32 s2, v101, 19
	v_readlane_b32 s3, v101, 23
	v_exp_f32_e32 v70, v56
	v_mov_b32_e32 v57, s2
	v_mov_b32_e32 v56, s3
	v_cndmask_b32_e32 v56, v56, v57, vcc
	v_sub_f32_e32 v56, v101, v56
	v_mul_f32_e32 v56, 0x3fb8aa3b, v56
	v_readlane_b32 s2, v101, 24
	v_readlane_b32 s3, v101, 28
	v_exp_f32_e32 v71, v56
	v_mov_b32_e32 v57, s2
	v_mov_b32_e32 v56, s3
	v_cndmask_b32_e32 v56, v56, v57, vcc
	v_sub_f32_e32 v56, v101, v56
	v_mul_f32_e32 v56, 0x3fb8aa3b, v56
	v_readlane_b32 s2, v101, 25
	v_readlane_b32 s3, v101, 29
	v_exp_f32_e32 v68, v56
	v_mov_b32_e32 v57, s2
	v_mov_b32_e32 v56, s3
	v_cndmask_b32_e32 v56, v56, v57, vcc
	v_sub_f32_e32 v56, v101, v56
	v_mul_f32_e32 v56, 0x3fb8aa3b, v56
	v_readlane_b32 s2, v101, 26
	v_readlane_b32 s3, v101, 30
	v_exp_f32_e32 v69, v56
	v_mov_b32_e32 v57, s2
	v_mov_b32_e32 v56, s3
	v_cndmask_b32_e32 v56, v56, v57, vcc
	v_sub_f32_e32 v56, v101, v56
	v_mul_f32_e32 v56, 0x3fb8aa3b, v56
	v_readlane_b32 s2, v101, 27
	v_readlane_b32 s3, v101, 31
	v_pk_mul_f32 v[2:3], v[2:3], v[64:65]
	v_exp_f32_e32 v66, v56
	v_mov_b32_e32 v56, s3
	v_mov_b32_e32 v57, s2
	v_cndmask_b32_e32 v56, v56, v57, vcc
	v_cvt_pk_bf16_f32 v2, v2, v3
	v_cmp_lt_i32_e32 vcc, -1, v128
	v_pk_mul_f32 v[4:5], v[4:5], v[62:63]
	v_pk_mul_f32 v[6:7], v[6:7], v[60:61]
	v_cndmask_b32_e32 v3, 0, v2, vcc
	v_lshrrev_b32_e32 v2, 16, v2
	v_cmp_lt_i32_e32 vcc, 0, v128
	v_pk_mul_f32 v[8:9], v[8:9], v[58:59]
	v_sub_f32_e32 v56, v101, v56
	v_cndmask_b32_e32 v2, 0, v2, vcc
	v_perm_b32 v2, v2, v3, s15
	v_cvt_pk_bf16_f32 v3, v4, v5
	v_cmp_lt_i32_e32 vcc, 1, v128
	v_mul_f32_e32 v56, 0x3fb8aa3b, v56
	v_exp_f32_e32 v67, v56
	v_cndmask_b32_e32 v4, 0, v3, vcc
	v_lshrrev_b32_e32 v3, 16, v3
	v_cmp_lt_i32_e32 vcc, 2, v128
	s_add_u32 s2, s0, 0x2000
	v_lshlrev_b32_e32 v56, 4, v22
	v_cndmask_b32_e32 v3, 0, v3, vcc
	v_perm_b32 v3, v3, v4, s15
	v_cvt_pk_bf16_f32 v4, v6, v7
	v_cmp_lt_i32_e32 vcc, 7, v128
	s_addc_u32 s3, s1, 0
	v_ashrrev_i32_e32 v57, 31, v56
	v_cndmask_b32_e32 v5, 0, v4, vcc
	v_lshrrev_b32_e32 v4, 16, v4
	v_cmp_lt_i32_e32 vcc, 8, v128
	v_pk_mul_f32 v[10:11], v[10:11], v[72:73]
	v_pk_mul_f32 v[12:13], v[12:13], v[70:71]
	v_cndmask_b32_e32 v4, 0, v4, vcc
	v_perm_b32 v4, v4, v5, s15
	v_cvt_pk_bf16_f32 v5, v8, v9
	v_cmp_lt_i32_e32 vcc, 9, v128
	v_pk_mul_f32 v[14:15], v[14:15], v[68:69]
	v_pk_mul_f32 v[16:17], v[16:17], v[66:67]
	v_cndmask_b32_e32 v6, 0, v5, vcc
	v_lshrrev_b32_e32 v5, 16, v5
	v_cmp_lt_i32_e32 vcc, 10, v128
	v_lshl_add_u32 v101, v96, 7, s51
	v_lshl_add_u32 v8, v109, 3, v101
	v_cndmask_b32_e32 v5, 0, v5, vcc
	v_perm_b32 v5, v5, v6, s15
	v_lshl_add_u64 v[6:7], s[2:3], 0, v[56:57]
	flat_store_dwordx4 v[6:7], v[2:5]
	v_cmp_lt_i32_e32 vcc, 15, v128
	v_lshlrev_b32_e32 v9, 4, v127
	v_cvt_pk_bf16_f32 v2, v10, v11
	v_cndmask_b32_e32 v3, 0, v2, vcc
	v_lshrrev_b32_e32 v2, 16, v2
	v_cmp_lt_i32_e32 vcc, 16, v128
	v_lshlrev_b32_e32 v109, 9, v109
	s_nop 0
	v_cndmask_b32_e32 v2, 0, v2, vcc
	v_perm_b32 v2, v2, v3, s15
	v_cvt_pk_bf16_f32 v3, v12, v13
	v_cmp_lt_i32_e32 vcc, 17, v128
	s_nop 1
	v_cndmask_b32_e32 v4, 0, v3, vcc
	v_lshrrev_b32_e32 v3, 16, v3
	v_cmp_lt_i32_e32 vcc, 18, v128
	s_nop 1
	v_cndmask_b32_e32 v3, 0, v3, vcc
	v_perm_b32 v3, v3, v4, s15
	v_cvt_pk_bf16_f32 v4, v14, v15
	v_cmp_lt_i32_e32 vcc, 23, v128
	s_nop 1
	v_cndmask_b32_e32 v5, 0, v4, vcc
	v_lshrrev_b32_e32 v4, 16, v4
	v_cmp_lt_i32_e32 vcc, 24, v128
	s_nop 1
	v_cndmask_b32_e32 v4, 0, v4, vcc
	v_perm_b32 v4, v4, v5, s15
	v_cvt_pk_bf16_f32 v5, v16, v17
	v_cmp_lt_i32_e32 vcc, 25, v128
	s_nop 1
	v_cndmask_b32_e32 v6, 0, v5, vcc
	v_lshrrev_b32_e32 v5, 16, v5
	v_cmp_lt_i32_e32 vcc, 26, v128
	s_nop 1
	v_cndmask_b32_e32 v5, 0, v5, vcc
	v_perm_b32 v5, v5, v6, s15
	v_add_u32_e32 v6, 0x400, v56
	v_ashrrev_i32_e32 v7, 31, v6
	v_lshl_add_u64 v[6:7], s[2:3], 0, v[6:7]
	flat_store_dwordx4 v[6:7], v[2:5]
	s_add_u32 s2, s0, 0x1000
	v_or_b32_e32 v6, v109, v108
	v_add_u32_e32 v2, v8, v9
	v_xad_u32 v4, v9, 16, v8
	ds_read_b64 v[2:3], v2
	ds_read_b64 v[4:5], v4
	s_addc_u32 s3, s1, 0
	v_ashrrev_i32_e32 v7, 31, v6
	v_lshl_add_u64 v[6:7], s[2:3], 0, v[6:7]
	v_cmp_gt_i32_e32 vcc, v96, v115
	s_waitcnt lgkmcnt(0)
	flat_store_dwordx4 v[6:7], v[2:5]
	v_lshl_or_b32 v6, v117, 9, v108
	v_ashrrev_i32_e32 v7, 31, v6
	v_xad_u32 v2, v9, 32, v8
	v_xad_u32 v4, v9, 48, v8
	ds_read_b64 v[2:3], v2
	ds_read_b64 v[4:5], v4
	v_lshl_add_u64 v[6:7], s[2:3], 0, v[6:7]
	s_waitcnt lgkmcnt(0)
	flat_store_dwordx4 v[6:7], v[2:5]
	s_nop 1
	v_xad_u32 v2, v9, 64, v8
	v_xad_u32 v4, v9, s4, v8
	ds_read_b64 v[2:3], v2
	ds_read_b64 v[4:5], v4
	v_lshl_or_b32 v6, v119, 9, v108
	v_ashrrev_i32_e32 v7, 31, v6
	v_lshl_add_u64 v[6:7], s[2:3], 0, v[6:7]
	s_movk_i32 s4, 0x60
	s_waitcnt lgkmcnt(0)
	flat_store_dwordx4 v[6:7], v[2:5]
	v_lshl_or_b32 v6, v125, 9, v108
	v_ashrrev_i32_e32 v7, 31, v6
	v_xad_u32 v2, v9, s4, v8
	s_movk_i32 s4, 0x70
	v_xad_u32 v4, v9, s4, v8
	ds_read_b64 v[2:3], v2
	ds_read_b64 v[4:5], v4
	v_lshl_add_u64 v[6:7], s[2:3], 0, v[6:7]
	s_movk_i32 s2, 0xff84
	v_mad_i32_i24 v101, v96, s2, v101
	s_add_u32 s2, s0, 0x3800
	s_waitcnt lgkmcnt(0)
	flat_store_dwordx4 v[6:7], v[2:5]
	ds_read_b128 v[2:5], v116 offset:4096
	ds_read_b128 v[116:119], v118 offset:4096
	s_waitcnt lgkmcnt(0)
	v_mfma_f32_32x32x16_bf16 v[2:17], v[2:5], v[2:5], 0
	s_addc_u32 s3, s1, 0
	v_mfma_f32_32x32x16_bf16 v[2:17], v[116:119], v[116:119], v[2:17]
	ds_read_b128 v[116:119], v124 offset:4096
	ds_read_b128 v[124:127], v126 offset:4096
	s_waitcnt lgkmcnt(0)
	v_mfma_f32_32x32x16_bf16 v[2:17], v[116:119], v[116:119], v[2:17]
	v_mfma_f32_32x32x16_bf16 v[2:17], v[124:127], v[124:127], v[2:17]
	s_nop 11
	v_mul_f32_e32 v2, v102, v2
	v_mul_f32_e32 v2, v2, v64
	v_cndmask_b32_e32 v2, 0, v2, vcc
	v_add_u32_e32 v64, v101, v109
	ds_write_b32 v64, v2 offset:8192
	v_or_b32_e32 v2, 1, v115
	v_mul_f32_e32 v3, v102, v3
	v_mul_f32_e32 v3, v3, v65
	v_cmp_gt_i32_e32 vcc, v96, v2
	v_lshl_add_u32 v2, v2, 7, v101
	s_nop 0
	v_cndmask_b32_e32 v3, 0, v3, vcc
	ds_write_b32 v2, v3 offset:8192
	v_or_b32_e32 v2, 2, v115
	v_mul_f32_e32 v3, v102, v4
	v_mul_f32_e32 v3, v3, v62
	v_cmp_gt_i32_e32 vcc, v96, v2
	v_lshl_add_u32 v2, v2, 7, v101
	s_nop 0
	v_cndmask_b32_e32 v3, 0, v3, vcc
	ds_write_b32 v2, v3 offset:8192
	v_or_b32_e32 v2, 3, v115
	v_mul_f32_e32 v3, v102, v5
	v_mul_f32_e32 v3, v3, v63
	v_cmp_gt_i32_e32 vcc, v96, v2
	v_lshl_add_u32 v2, v2, 7, v101
	s_nop 0
	v_cndmask_b32_e32 v3, 0, v3, vcc
	ds_write_b32 v2, v3 offset:8192
	v_add_u32_e32 v2, 8, v115
	v_mul_f32_e32 v3, v102, v6
	v_mul_f32_e32 v3, v3, v60
	v_cmp_gt_i32_e32 vcc, v96, v2
	v_lshl_add_u32 v2, v2, 7, v101
	s_nop 0
	v_cndmask_b32_e32 v3, 0, v3, vcc
	ds_write_b32 v2, v3 offset:8192
	v_add_u32_e32 v2, 9, v115
	v_mul_f32_e32 v3, v102, v7
	v_mul_f32_e32 v3, v3, v61
	v_cmp_gt_i32_e32 vcc, v96, v2
	v_lshl_add_u32 v2, v2, 7, v101
	s_nop 0
	v_cndmask_b32_e32 v3, 0, v3, vcc
	ds_write_b32 v2, v3 offset:8192
	v_add_u32_e32 v2, 10, v115
	v_mul_f32_e32 v3, v102, v8
	v_mul_f32_e32 v3, v3, v58
	v_cmp_gt_i32_e32 vcc, v96, v2
	v_lshl_add_u32 v2, v2, 7, v101
	v_mov_b32_e32 v58, 0
	v_cndmask_b32_e32 v3, 0, v3, vcc
	ds_write_b32 v2, v3 offset:8192
	v_add_u32_e32 v2, 11, v115
	v_mul_f32_e32 v3, v102, v9
	v_mul_f32_e32 v3, v3, v59
	v_cmp_gt_i32_e32 vcc, v96, v2
	v_lshl_add_u32 v2, v2, 7, v101
	s_nop 0
	v_cndmask_b32_e32 v3, 0, v3, vcc
	ds_write_b32 v2, v3 offset:8192
	v_add_u32_e32 v2, 16, v115
	v_mul_f32_e32 v3, v102, v10
	v_mul_f32_e32 v3, v3, v72
	v_cmp_gt_i32_e32 vcc, v96, v2
	v_lshl_add_u32 v2, v2, 7, v101
	s_nop 0
	v_cndmask_b32_e32 v3, 0, v3, vcc
	ds_write_b32 v2, v3 offset:8192
	v_add_u32_e32 v2, 17, v115
	v_mul_f32_e32 v3, v102, v11
	v_mul_f32_e32 v3, v3, v73
	v_cmp_gt_i32_e32 vcc, v96, v2
	v_lshl_add_u32 v2, v2, 7, v101
	s_nop 0
	v_cndmask_b32_e32 v3, 0, v3, vcc
	ds_write_b32 v2, v3 offset:8192
	v_add_u32_e32 v2, 18, v115
	v_mul_f32_e32 v3, v102, v12
	v_mul_f32_e32 v3, v3, v70
	v_cmp_gt_i32_e32 vcc, v96, v2
	v_lshl_add_u32 v2, v2, 7, v101
	s_nop 0
	v_cndmask_b32_e32 v3, 0, v3, vcc
	ds_write_b32 v2, v3 offset:8192
	v_add_u32_e32 v2, 19, v115
	v_mul_f32_e32 v3, v102, v13
	v_mul_f32_e32 v3, v3, v71
	v_cmp_gt_i32_e32 vcc, v96, v2
	v_lshl_add_u32 v2, v2, 7, v101
	s_nop 0
	v_cndmask_b32_e32 v3, 0, v3, vcc
	ds_write_b32 v2, v3 offset:8192
	v_add_u32_e32 v2, 24, v115
	v_mul_f32_e32 v3, v102, v14
	v_mul_f32_e32 v3, v3, v68
	v_cmp_gt_i32_e32 vcc, v96, v2
	v_lshl_add_u32 v2, v2, 7, v101
	s_nop 0
	v_cndmask_b32_e32 v3, 0, v3, vcc
	ds_write_b32 v2, v3 offset:8192
	v_add_u32_e32 v2, 25, v115
	v_mul_f32_e32 v3, v102, v15
	v_mul_f32_e32 v3, v3, v69
	v_cmp_gt_i32_e32 vcc, v96, v2
	v_lshl_add_u32 v2, v2, 7, v101
	s_nop 0
	v_cndmask_b32_e32 v3, 0, v3, vcc
	ds_write_b32 v2, v3 offset:8192
	v_add_u32_e32 v2, 26, v115
	v_mul_f32_e32 v3, v102, v16
	v_mul_f32_e32 v3, v3, v66
	v_cmp_gt_i32_e32 vcc, v96, v2
	v_lshl_add_u32 v2, v2, 7, v101
	s_nop 0
	v_cndmask_b32_e32 v3, 0, v3, vcc
	ds_write_b32 v2, v3 offset:8192
	v_add_u32_e32 v2, 27, v115
	v_mul_f32_e32 v3, v102, v17
	v_mul_f32_e32 v3, v3, v67
	v_cmp_gt_i32_e32 vcc, v96, v2
	v_lshl_add_u32 v2, v2, 7, v101
	s_nop 0
	v_cndmask_b32_e32 v3, 0, v3, vcc
	ds_write_b32 v2, v3 offset:8192
	s_waitcnt lgkmcnt(0)
	s_nop 0
	v_add_u32_e32 v14, s51, v58
	ds_read_b128 v[2:5], v14 offset:8192
	ds_read_b128 v[6:9], v14 offset:8208
	ds_read_b128 v[10:13], v14 offset:8224
	ds_read_b128 v[14:17], v14 offset:8240
	s_waitcnt lgkmcnt(0)
	v_fma_f32 v36, -v14, v24, v36
	v_fma_f32 v104, -v14, v88, v104
	v_fma_f32 v39, -v17, v24, v39
	v_fma_f32 v25, -v3, v24, v25
	v_fma_f32 v90, -v3, v88, v90
	v_fma_f32 v26, -v4, v24, v26
	v_fma_f32 v89, -v4, v88, v89
	v_fma_f32 v27, -v5, v24, v27
	s_nop 0
	v_fma_f32 v91, -v5, v88, v91
	v_fma_f32 v28, -v6, v24, v28
	v_fma_f32 v92, -v6, v88, v92
	v_fma_f32 v29, -v7, v24, v29
	v_fma_f32 v93, -v7, v88, v93
	s_nop 0
	v_add_u32_e32 v14, s51, v58
	v_fma_f32 v30, -v8, v24, v30
	v_fma_f32 v94, -v8, v88, v94
	v_fma_f32 v31, -v9, v24, v31
	v_fma_f32 v95, -v9, v88, v95
	v_fma_f32 v32, -v10, v24, v32
	v_fma_f32 v98, -v10, v88, v98
	v_fma_f32 v33, -v11, v24, v33
	v_fma_f32 v97, -v11, v88, v97
	v_fma_f32 v34, -v12, v24, v34
	v_fma_f32 v100, -v12, v88, v100
	v_fma_f32 v35, -v13, v24, v35
	v_fma_f32 v99, -v13, v88, v99
	v_fma_f32 v37, -v15, v24, v37
	v_fma_f32 v103, -v15, v88, v103
	v_fma_f32 v38, -v16, v24, v38
	v_fma_f32 v107, -v16, v88, v107
	ds_read_b128 v[2:5], v14 offset:8256
	v_fma_f32 v106, -v17, v88, v106
	ds_read_b128 v[6:9], v14 offset:8272
	ds_read_b128 v[10:13], v14 offset:8288
	ds_read_b128 v[14:17], v14 offset:8304
	v_mov_b32_e32 v58, 0x80
	s_waitcnt lgkmcnt(0)
	v_fma_f32 v52, -v14, v24, v52
	v_fma_f32 v78, -v14, v88, v78
	v_fma_f32 v40, -v2, v24, v40
	v_fma_f32 v111, -v2, v88, v111
	v_fma_f32 v41, -v3, v24, v41
	v_fma_f32 v110, -v3, v88, v110
	v_fma_f32 v42, -v4, v24, v42
	s_nop 0
	v_add_u32_e32 v14, s51, v58
	v_fma_f32 v113, -v4, v88, v113
	v_fma_f32 v43, -v5, v24, v43
	v_fma_f32 v112, -v5, v88, v112
	v_fma_f32 v46, -v6, v24, v46
	v_fma_f32 v121, -v6, v88, v121
	v_fma_f32 v47, -v7, v24, v47
	v_fma_f32 v120, -v7, v88, v120
	v_fma_f32 v48, -v8, v24, v48
	v_fma_f32 v123, -v8, v88, v123
	v_fma_f32 v49, -v9, v24, v49
	v_fma_f32 v122, -v9, v88, v122
	v_fma_f32 v44, -v10, v24, v44
	v_fma_f32 v74, -v10, v88, v74
	v_fma_f32 v45, -v11, v24, v45
	v_fma_f32 v75, -v11, v88, v75
	v_fma_f32 v50, -v12, v24, v50
	v_fma_f32 v76, -v12, v88, v76
	v_fma_f32 v51, -v13, v24, v51
	v_fma_f32 v77, -v13, v88, v77
	v_fma_f32 v53, -v15, v24, v53
	v_fma_f32 v79, -v15, v88, v79
	v_fma_f32 v54, -v16, v24, v54
	v_fma_f32 v105, -v16, v88, v105
	v_fma_f32 v55, -v17, v24, v55
	ds_read_b128 v[2:5], v14 offset:8192
	v_fma_f32 v114, -v17, v88, v114
	ds_read_b128 v[6:9], v14 offset:8208
	ds_read_b128 v[10:13], v14 offset:8224
	ds_read_b128 v[14:17], v14 offset:8240
	s_waitcnt lgkmcnt(0)
	v_fma_f32 v36, -v14, v25, v36
	v_fma_f32 v104, -v14, v90, v104
	v_fma_f32 v39, -v17, v25, v39
	v_fma_f32 v26, -v4, v25, v26
	v_fma_f32 v89, -v4, v90, v89
	v_fma_f32 v27, -v5, v25, v27
	v_fma_f32 v91, -v5, v90, v91
	v_fma_f32 v28, -v6, v25, v28
	s_nop 0
	v_fma_f32 v92, -v6, v90, v92
	v_fma_f32 v29, -v7, v25, v29
	v_fma_f32 v93, -v7, v90, v93
	v_fma_f32 v30, -v8, v25, v30
	v_fma_f32 v94, -v8, v90, v94
	s_nop 0
	v_add_u32_e32 v14, s51, v58
	v_fma_f32 v31, -v9, v25, v31
	v_fma_f32 v95, -v9, v90, v95
	v_fma_f32 v32, -v10, v25, v32
	v_fma_f32 v98, -v10, v90, v98
	v_fma_f32 v33, -v11, v25, v33
	v_fma_f32 v97, -v11, v90, v97
	v_fma_f32 v34, -v12, v25, v34
	v_fma_f32 v100, -v12, v90, v100
	v_fma_f32 v35, -v13, v25, v35
	v_fma_f32 v99, -v13, v90, v99
	v_fma_f32 v37, -v15, v25, v37
	v_fma_f32 v103, -v15, v90, v103
	v_fma_f32 v38, -v16, v25, v38
	v_fma_f32 v107, -v16, v90, v107
	ds_read_b128 v[2:5], v14 offset:8256
	v_fma_f32 v106, -v17, v90, v106
	ds_read_b128 v[6:9], v14 offset:8272
	ds_read_b128 v[10:13], v14 offset:8288
	ds_read_b128 v[14:17], v14 offset:8304
	v_mov_b32_e32 v58, 0x100
	s_waitcnt lgkmcnt(0)
	v_fma_f32 v52, -v14, v25, v52
	v_fma_f32 v78, -v14, v90, v78
	v_fma_f32 v40, -v2, v25, v40
	v_fma_f32 v111, -v2, v90, v111
	v_fma_f32 v41, -v3, v25, v41
	v_fma_f32 v110, -v3, v90, v110
	v_fma_f32 v42, -v4, v25, v42
	s_nop 0
	v_add_u32_e32 v14, s51, v58
	v_fma_f32 v113, -v4, v90, v113
	v_fma_f32 v43, -v5, v25, v43
	v_fma_f32 v112, -v5, v90, v112
	v_fma_f32 v46, -v6, v25, v46
	v_fma_f32 v121, -v6, v90, v121
	v_fma_f32 v47, -v7, v25, v47
	v_fma_f32 v120, -v7, v90, v120
	v_fma_f32 v48, -v8, v25, v48
	v_fma_f32 v123, -v8, v90, v123
	v_fma_f32 v49, -v9, v25, v49
	v_fma_f32 v122, -v9, v90, v122
	v_fma_f32 v44, -v10, v25, v44
	v_fma_f32 v74, -v10, v90, v74
	v_fma_f32 v45, -v11, v25, v45
	v_fma_f32 v75, -v11, v90, v75
	v_fma_f32 v50, -v12, v25, v50
	v_fma_f32 v76, -v12, v90, v76
	v_fma_f32 v51, -v13, v25, v51
	v_fma_f32 v77, -v13, v90, v77
	v_fma_f32 v53, -v15, v25, v53
	v_fma_f32 v79, -v15, v90, v79
	v_fma_f32 v54, -v16, v25, v54
	v_fma_f32 v105, -v16, v90, v105
	v_fma_f32 v55, -v17, v25, v55
	ds_read_b128 v[2:5], v14 offset:8192
	v_fma_f32 v114, -v17, v90, v114
	ds_read_b128 v[6:9], v14 offset:8208
	ds_read_b128 v[10:13], v14 offset:8224
	ds_read_b128 v[14:17], v14 offset:8240
	s_waitcnt lgkmcnt(0)
	v_fma_f32 v36, -v14, v26, v36
	v_fma_f32 v104, -v14, v89, v104
	v_fma_f32 v39, -v17, v26, v39
	v_fma_f32 v27, -v5, v26, v27
	v_fma_f32 v91, -v5, v89, v91
	v_fma_f32 v28, -v6, v26, v28
	v_fma_f32 v92, -v6, v89, v92
	v_fma_f32 v29, -v7, v26, v29
	s_nop 0
	v_fma_f32 v93, -v7, v89, v93
	v_fma_f32 v30, -v8, v26, v30
	v_fma_f32 v94, -v8, v89, v94
	v_fma_f32 v31, -v9, v26, v31
	v_fma_f32 v95, -v9, v89, v95
	s_nop 0
	v_add_u32_e32 v14, s51, v58
	v_fma_f32 v32, -v10, v26, v32
	v_fma_f32 v98, -v10, v89, v98
	v_fma_f32 v33, -v11, v26, v33
	v_fma_f32 v97, -v11, v89, v97
	v_fma_f32 v34, -v12, v26, v34
	v_fma_f32 v100, -v12, v89, v100
	v_fma_f32 v35, -v13, v26, v35
	v_fma_f32 v99, -v13, v89, v99
	v_fma_f32 v37, -v15, v26, v37
	v_fma_f32 v103, -v15, v89, v103
	v_fma_f32 v38, -v16, v26, v38
	v_fma_f32 v107, -v16, v89, v107
	ds_read_b128 v[2:5], v14 offset:8256
	v_fma_f32 v106, -v17, v89, v106
	ds_read_b128 v[6:9], v14 offset:8272
	ds_read_b128 v[10:13], v14 offset:8288
	ds_read_b128 v[14:17], v14 offset:8304
	v_mov_b32_e32 v58, 0x180
	s_waitcnt lgkmcnt(0)
	v_fma_f32 v52, -v14, v26, v52
	v_fma_f32 v78, -v14, v89, v78
	v_fma_f32 v40, -v2, v26, v40
	v_fma_f32 v111, -v2, v89, v111
	v_fma_f32 v41, -v3, v26, v41
	v_fma_f32 v110, -v3, v89, v110
	v_fma_f32 v42, -v4, v26, v42
	s_nop 0
	v_add_u32_e32 v14, s51, v58
	v_fma_f32 v113, -v4, v89, v113
	v_fma_f32 v43, -v5, v26, v43
	v_fma_f32 v112, -v5, v89, v112
	v_fma_f32 v46, -v6, v26, v46
	v_fma_f32 v121, -v6, v89, v121
	v_fma_f32 v47, -v7, v26, v47
	v_fma_f32 v120, -v7, v89, v120
	v_fma_f32 v48, -v8, v26, v48
	v_fma_f32 v123, -v8, v89, v123
	v_fma_f32 v49, -v9, v26, v49
	v_fma_f32 v122, -v9, v89, v122
	v_fma_f32 v44, -v10, v26, v44
	v_fma_f32 v74, -v10, v89, v74
	v_fma_f32 v45, -v11, v26, v45
	v_fma_f32 v75, -v11, v89, v75
	v_fma_f32 v50, -v12, v26, v50
	v_fma_f32 v76, -v12, v89, v76
	v_fma_f32 v51, -v13, v26, v51
	v_fma_f32 v77, -v13, v89, v77
	v_fma_f32 v53, -v15, v26, v53
	v_fma_f32 v79, -v15, v89, v79
	v_fma_f32 v54, -v16, v26, v54
	v_fma_f32 v105, -v16, v89, v105
	v_fma_f32 v55, -v17, v26, v55
	ds_read_b128 v[2:5], v14 offset:8208
	v_fma_f32 v114, -v17, v89, v114
	ds_read_b128 v[6:9], v14 offset:8224
	ds_read_b128 v[10:13], v14 offset:8240
	ds_read_b128 v[14:17], v14 offset:8256
	s_waitcnt lgkmcnt(0)
	v_fma_f32 v36, -v10, v27, v36
	v_fma_f32 v104, -v10, v91, v104
	v_fma_f32 v43, -v17, v27, v43
	v_fma_f32 v28, -v2, v27, v28
	v_fma_f32 v92, -v2, v91, v92
	v_fma_f32 v29, -v3, v27, v29
	v_fma_f32 v93, -v3, v91, v93
	v_fma_f32 v30, -v4, v27, v30
	s_nop 0
	v_fma_f32 v94, -v4, v91, v94
	v_fma_f32 v31, -v5, v27, v31
	v_fma_f32 v95, -v5, v91, v95
	v_fma_f32 v32, -v6, v27, v32
	v_fma_f32 v98, -v6, v91, v98
	s_nop 0
	v_add_u32_e32 v10, s51, v58
	v_fma_f32 v33, -v7, v27, v33
	v_fma_f32 v97, -v7, v91, v97
	v_fma_f32 v34, -v8, v27, v34
	v_fma_f32 v100, -v8, v91, v100
	v_fma_f32 v35, -v9, v27, v35
	v_fma_f32 v99, -v9, v91, v99
	v_fma_f32 v37, -v11, v27, v37
	v_fma_f32 v103, -v11, v91, v103
	v_fma_f32 v38, -v12, v27, v38
	v_fma_f32 v107, -v12, v91, v107
	v_fma_f32 v39, -v13, v27, v39
	v_fma_f32 v106, -v13, v91, v106
	ds_read_b128 v[2:5], v10 offset:8272
	ds_read_b128 v[6:9], v10 offset:8288
	ds_read_b128 v[10:13], v10 offset:8304
	v_mov_b32_e32 v58, 0x200
	v_fma_f32 v40, -v14, v27, v40
	v_fma_f32 v111, -v14, v91, v111
	v_fma_f32 v41, -v15, v27, v41
	v_fma_f32 v110, -v15, v91, v110
	v_fma_f32 v42, -v16, v27, v42
	v_fma_f32 v113, -v16, v91, v113
	v_fma_f32 v112, -v17, v91, v112
	s_nop 0
	v_add_u32_e32 v14, s51, v58
	s_waitcnt lgkmcnt(0)
	v_fma_f32 v46, -v2, v27, v46
	v_fma_f32 v121, -v2, v91, v121
	v_fma_f32 v47, -v3, v27, v47
	v_fma_f32 v120, -v3, v91, v120
	v_fma_f32 v48, -v4, v27, v48
	v_fma_f32 v123, -v4, v91, v123
	v_fma_f32 v49, -v5, v27, v49
	v_fma_f32 v122, -v5, v91, v122
	v_fma_f32 v44, -v6, v27, v44
	v_fma_f32 v74, -v6, v91, v74
	v_fma_f32 v45, -v7, v27, v45
	v_fma_f32 v75, -v7, v91, v75
	v_fma_f32 v50, -v8, v27, v50
	v_fma_f32 v76, -v8, v91, v76
	v_fma_f32 v51, -v9, v27, v51
	v_fma_f32 v77, -v9, v91, v77
	v_fma_f32 v52, -v10, v27, v52
	v_fma_f32 v78, -v10, v91, v78
	v_fma_f32 v53, -v11, v27, v53
	v_fma_f32 v79, -v11, v91, v79
	v_fma_f32 v54, -v12, v27, v54
	v_fma_f32 v105, -v12, v91, v105
	v_fma_f32 v55, -v13, v27, v55
	ds_read_b128 v[2:5], v14 offset:8208
	v_fma_f32 v114, -v13, v91, v114
	ds_read_b128 v[6:9], v14 offset:8224
	ds_read_b128 v[10:13], v14 offset:8240
	ds_read_b128 v[14:17], v14 offset:8256
	s_waitcnt lgkmcnt(0)
	v_fma_f32 v36, -v10, v28, v36
	v_fma_f32 v104, -v10, v92, v104
	v_fma_f32 v43, -v17, v28, v43
	v_fma_f32 v29, -v3, v28, v29
	v_fma_f32 v93, -v3, v92, v93
	v_fma_f32 v30, -v4, v28, v30
	v_fma_f32 v94, -v4, v92, v94
	v_fma_f32 v31, -v5, v28, v31
	s_nop 0
	v_fma_f32 v95, -v5, v92, v95
	v_fma_f32 v32, -v6, v28, v32
	v_fma_f32 v98, -v6, v92, v98
	v_fma_f32 v33, -v7, v28, v33
	v_fma_f32 v97, -v7, v92, v97
	s_nop 0
	v_add_u32_e32 v10, s51, v58
	v_fma_f32 v34, -v8, v28, v34
	v_fma_f32 v100, -v8, v92, v100
	v_fma_f32 v35, -v9, v28, v35
	v_fma_f32 v99, -v9, v92, v99
	v_fma_f32 v37, -v11, v28, v37
	v_fma_f32 v103, -v11, v92, v103
	v_fma_f32 v38, -v12, v28, v38
	v_fma_f32 v107, -v12, v92, v107
	v_fma_f32 v39, -v13, v28, v39
	v_fma_f32 v106, -v13, v92, v106
	ds_read_b128 v[2:5], v10 offset:8272
	ds_read_b128 v[6:9], v10 offset:8288
	ds_read_b128 v[10:13], v10 offset:8304
	v_mov_b32_e32 v58, 0x280
	v_fma_f32 v40, -v14, v28, v40
	v_fma_f32 v111, -v14, v92, v111
	v_fma_f32 v41, -v15, v28, v41
	v_fma_f32 v110, -v15, v92, v110
	v_fma_f32 v42, -v16, v28, v42
	v_fma_f32 v113, -v16, v92, v113
	v_fma_f32 v112, -v17, v92, v112
	s_nop 0
	v_add_u32_e32 v14, s51, v58
	s_waitcnt lgkmcnt(0)
	v_fma_f32 v46, -v2, v28, v46
	v_fma_f32 v121, -v2, v92, v121
	v_fma_f32 v47, -v3, v28, v47
	v_fma_f32 v120, -v3, v92, v120
	v_fma_f32 v48, -v4, v28, v48
	v_fma_f32 v123, -v4, v92, v123
	v_fma_f32 v49, -v5, v28, v49
	v_fma_f32 v122, -v5, v92, v122
	v_fma_f32 v44, -v6, v28, v44
	v_fma_f32 v74, -v6, v92, v74
	v_fma_f32 v45, -v7, v28, v45
	v_fma_f32 v75, -v7, v92, v75
	v_fma_f32 v50, -v8, v28, v50
	v_fma_f32 v76, -v8, v92, v76
	v_fma_f32 v51, -v9, v28, v51
	v_fma_f32 v77, -v9, v92, v77
	v_fma_f32 v52, -v10, v28, v52
	v_fma_f32 v78, -v10, v92, v78
	v_fma_f32 v53, -v11, v28, v53
	v_fma_f32 v79, -v11, v92, v79
	v_fma_f32 v54, -v12, v28, v54
	v_fma_f32 v105, -v12, v92, v105
	v_fma_f32 v55, -v13, v28, v55
	ds_read_b128 v[2:5], v14 offset:8208
	v_fma_f32 v114, -v13, v92, v114
	ds_read_b128 v[6:9], v14 offset:8224
	ds_read_b128 v[10:13], v14 offset:8240
	ds_read_b128 v[14:17], v14 offset:8256
	s_waitcnt lgkmcnt(0)
	v_fma_f32 v36, -v10, v29, v36
	v_fma_f32 v104, -v10, v93, v104
	v_fma_f32 v43, -v17, v29, v43
	v_fma_f32 v30, -v4, v29, v30
	v_fma_f32 v94, -v4, v93, v94
	v_fma_f32 v31, -v5, v29, v31
	v_fma_f32 v95, -v5, v93, v95
	v_fma_f32 v32, -v6, v29, v32
	s_nop 0
	v_fma_f32 v98, -v6, v93, v98
	v_fma_f32 v33, -v7, v29, v33
	v_fma_f32 v97, -v7, v93, v97
	v_fma_f32 v34, -v8, v29, v34
	v_fma_f32 v100, -v8, v93, v100
	s_nop 0
	v_add_u32_e32 v10, s51, v58
	v_fma_f32 v35, -v9, v29, v35
	v_fma_f32 v99, -v9, v93, v99
	v_fma_f32 v37, -v11, v29, v37
	v_fma_f32 v103, -v11, v93, v103
	v_fma_f32 v38, -v12, v29, v38
	v_fma_f32 v107, -v12, v93, v107
	v_fma_f32 v39, -v13, v29, v39
	v_fma_f32 v106, -v13, v93, v106
	ds_read_b128 v[2:5], v10 offset:8272
	ds_read_b128 v[6:9], v10 offset:8288
	ds_read_b128 v[10:13], v10 offset:8304
	v_mov_b32_e32 v58, 0x300
	v_fma_f32 v40, -v14, v29, v40
	v_fma_f32 v111, -v14, v93, v111
	v_fma_f32 v41, -v15, v29, v41
	v_fma_f32 v110, -v15, v93, v110
	v_fma_f32 v42, -v16, v29, v42
	v_fma_f32 v113, -v16, v93, v113
	v_fma_f32 v112, -v17, v93, v112
	s_nop 0
	v_add_u32_e32 v14, s51, v58
	s_waitcnt lgkmcnt(0)
	v_fma_f32 v46, -v2, v29, v46
	v_fma_f32 v121, -v2, v93, v121
	v_fma_f32 v47, -v3, v29, v47
	v_fma_f32 v120, -v3, v93, v120
	v_fma_f32 v48, -v4, v29, v48
	v_fma_f32 v123, -v4, v93, v123
	v_fma_f32 v49, -v5, v29, v49
	v_fma_f32 v122, -v5, v93, v122
	v_fma_f32 v44, -v6, v29, v44
	v_fma_f32 v74, -v6, v93, v74
	v_fma_f32 v45, -v7, v29, v45
	v_fma_f32 v75, -v7, v93, v75
	v_fma_f32 v50, -v8, v29, v50
	v_fma_f32 v76, -v8, v93, v76
	v_fma_f32 v51, -v9, v29, v51
	v_fma_f32 v77, -v9, v93, v77
	v_fma_f32 v52, -v10, v29, v52
	v_fma_f32 v78, -v10, v93, v78
	v_fma_f32 v53, -v11, v29, v53
	v_fma_f32 v79, -v11, v93, v79
	v_fma_f32 v54, -v12, v29, v54
	v_fma_f32 v105, -v12, v93, v105
	v_fma_f32 v55, -v13, v29, v55
	ds_read_b128 v[2:5], v14 offset:8208
	v_fma_f32 v114, -v13, v93, v114
	ds_read_b128 v[6:9], v14 offset:8224
	ds_read_b128 v[10:13], v14 offset:8240
	ds_read_b128 v[14:17], v14 offset:8256
	s_waitcnt lgkmcnt(0)
	v_fma_f32 v36, -v10, v30, v36
	v_fma_f32 v104, -v10, v94, v104
	v_fma_f32 v43, -v17, v30, v43
	v_fma_f32 v31, -v5, v30, v31
	v_fma_f32 v95, -v5, v94, v95
	v_fma_f32 v32, -v6, v30, v32
	v_fma_f32 v98, -v6, v94, v98
	v_fma_f32 v33, -v7, v30, v33
	s_nop 0
	v_fma_f32 v97, -v7, v94, v97
	v_fma_f32 v34, -v8, v30, v34
	v_fma_f32 v100, -v8, v94, v100
	v_fma_f32 v35, -v9, v30, v35
	v_fma_f32 v99, -v9, v94, v99
	s_nop 0
	v_add_u32_e32 v10, s51, v58
	v_fma_f32 v37, -v11, v30, v37
	v_fma_f32 v103, -v11, v94, v103
	v_fma_f32 v38, -v12, v30, v38
	v_fma_f32 v107, -v12, v94, v107
	v_fma_f32 v39, -v13, v30, v39
	v_fma_f32 v106, -v13, v94, v106
	ds_read_b128 v[2:5], v10 offset:8272
	ds_read_b128 v[6:9], v10 offset:8288
	ds_read_b128 v[10:13], v10 offset:8304
	v_mov_b32_e32 v58, 0x380
	v_fma_f32 v40, -v14, v30, v40
	v_fma_f32 v111, -v14, v94, v111
	v_fma_f32 v41, -v15, v30, v41
	v_fma_f32 v110, -v15, v94, v110
	v_fma_f32 v42, -v16, v30, v42
	v_fma_f32 v113, -v16, v94, v113
	v_fma_f32 v112, -v17, v94, v112
	s_nop 0
	v_add_u32_e32 v14, s51, v58
	s_waitcnt lgkmcnt(0)
	v_fma_f32 v46, -v2, v30, v46
	v_fma_f32 v121, -v2, v94, v121
	v_fma_f32 v47, -v3, v30, v47
	v_fma_f32 v120, -v3, v94, v120
	v_fma_f32 v48, -v4, v30, v48
	v_fma_f32 v123, -v4, v94, v123
	v_fma_f32 v49, -v5, v30, v49
	v_fma_f32 v122, -v5, v94, v122
	v_fma_f32 v44, -v6, v30, v44
	v_fma_f32 v74, -v6, v94, v74
	v_fma_f32 v45, -v7, v30, v45
	v_fma_f32 v75, -v7, v94, v75
	v_fma_f32 v50, -v8, v30, v50
	v_fma_f32 v76, -v8, v94, v76
	v_fma_f32 v51, -v9, v30, v51
	v_fma_f32 v77, -v9, v94, v77
	v_fma_f32 v52, -v10, v30, v52
	v_fma_f32 v78, -v10, v94, v78
	v_fma_f32 v53, -v11, v30, v53
	v_fma_f32 v79, -v11, v94, v79
	v_fma_f32 v54, -v12, v30, v54
	v_fma_f32 v105, -v12, v94, v105
	v_fma_f32 v55, -v13, v30, v55
	ds_read_b128 v[2:5], v14 offset:8224
	v_fma_f32 v114, -v13, v94, v114
	ds_read_b128 v[6:9], v14 offset:8240
	ds_read_b128 v[10:13], v14 offset:8256
	ds_read_b128 v[14:17], v14 offset:8272
	s_waitcnt lgkmcnt(0)
	v_fma_f32 v49, -v17, v31, v49
	s_nop 0
	v_fma_f32 v36, -v6, v31, v36
	v_fma_f32 v104, -v6, v95, v104
	v_fma_f32 v32, -v2, v31, v32
	v_fma_f32 v98, -v2, v95, v98
	v_fma_f32 v33, -v3, v31, v33
	s_nop 0
	v_add_u32_e32 v6, s51, v58
	v_mov_b32_e32 v58, 0x400
	v_fma_f32 v97, -v3, v95, v97
	v_fma_f32 v34, -v4, v31, v34
	v_fma_f32 v100, -v4, v95, v100
	v_fma_f32 v35, -v5, v31, v35
	v_fma_f32 v99, -v5, v95, v99
	v_fma_f32 v37, -v7, v31, v37
	v_fma_f32 v103, -v7, v95, v103
	v_fma_f32 v38, -v8, v31, v38
	v_fma_f32 v107, -v8, v95, v107
	v_fma_f32 v39, -v9, v31, v39
	v_fma_f32 v106, -v9, v95, v106
	v_fma_f32 v46, -v14, v31, v46
	v_fma_f32 v121, -v14, v95, v121
	ds_read_b128 v[2:5], v6 offset:8288
	ds_read_b128 v[6:9], v6 offset:8304
	v_fma_f32 v40, -v10, v31, v40
	v_fma_f32 v111, -v10, v95, v111
	v_fma_f32 v41, -v11, v31, v41
	v_fma_f32 v110, -v11, v95, v110
	v_fma_f32 v42, -v12, v31, v42
	s_nop 0
	v_add_u32_e32 v14, s51, v58
	v_fma_f32 v113, -v12, v95, v113
	v_fma_f32 v43, -v13, v31, v43
	v_fma_f32 v112, -v13, v95, v112
	v_fma_f32 v47, -v15, v31, v47
	v_fma_f32 v120, -v15, v95, v120
	v_fma_f32 v48, -v16, v31, v48
	v_fma_f32 v123, -v16, v95, v123
	v_fma_f32 v122, -v17, v95, v122
	s_waitcnt lgkmcnt(0)
	v_fma_f32 v44, -v2, v31, v44
	v_fma_f32 v74, -v2, v95, v74
	v_fma_f32 v45, -v3, v31, v45
	v_fma_f32 v75, -v3, v95, v75
	v_fma_f32 v50, -v4, v31, v50
	v_fma_f32 v76, -v4, v95, v76
	v_fma_f32 v51, -v5, v31, v51
	v_fma_f32 v77, -v5, v95, v77
	v_fma_f32 v52, -v6, v31, v52
	v_fma_f32 v78, -v6, v95, v78
	v_fma_f32 v53, -v7, v31, v53
	v_fma_f32 v79, -v7, v95, v79
	v_fma_f32 v54, -v8, v31, v54
	v_fma_f32 v105, -v8, v95, v105
	v_fma_f32 v55, -v9, v31, v55
	ds_read_b128 v[2:5], v14 offset:8224
	v_fma_f32 v114, -v9, v95, v114
	ds_read_b128 v[6:9], v14 offset:8240
	ds_read_b128 v[10:13], v14 offset:8256
	ds_read_b128 v[14:17], v14 offset:8272
	s_waitcnt lgkmcnt(0)
	v_fma_f32 v49, -v17, v32, v49
	s_nop 0
	v_fma_f32 v36, -v6, v32, v36
	v_fma_f32 v104, -v6, v98, v104
	v_fma_f32 v33, -v3, v32, v33
	v_fma_f32 v97, -v3, v98, v97
	v_fma_f32 v34, -v4, v32, v34
	s_nop 0
	v_add_u32_e32 v6, s51, v58
	v_mov_b32_e32 v58, 0x480
	v_fma_f32 v100, -v4, v98, v100
	v_fma_f32 v35, -v5, v32, v35
	v_fma_f32 v99, -v5, v98, v99
	v_fma_f32 v37, -v7, v32, v37
	v_fma_f32 v103, -v7, v98, v103
	v_fma_f32 v38, -v8, v32, v38
	v_fma_f32 v107, -v8, v98, v107
	v_fma_f32 v39, -v9, v32, v39
	v_fma_f32 v106, -v9, v98, v106
	v_fma_f32 v46, -v14, v32, v46
	v_fma_f32 v121, -v14, v98, v121
	ds_read_b128 v[2:5], v6 offset:8288
	ds_read_b128 v[6:9], v6 offset:8304
	v_fma_f32 v40, -v10, v32, v40
	v_fma_f32 v111, -v10, v98, v111
	v_fma_f32 v41, -v11, v32, v41
	v_fma_f32 v110, -v11, v98, v110
	v_fma_f32 v42, -v12, v32, v42
	s_nop 0
	v_add_u32_e32 v14, s51, v58
	v_fma_f32 v113, -v12, v98, v113
	v_fma_f32 v43, -v13, v32, v43
	v_fma_f32 v112, -v13, v98, v112
	v_fma_f32 v47, -v15, v32, v47
	v_fma_f32 v120, -v15, v98, v120
	v_fma_f32 v48, -v16, v32, v48
	v_fma_f32 v123, -v16, v98, v123
	v_fma_f32 v122, -v17, v98, v122
	s_waitcnt lgkmcnt(0)
	v_fma_f32 v44, -v2, v32, v44
	v_fma_f32 v74, -v2, v98, v74
	v_fma_f32 v45, -v3, v32, v45
	v_fma_f32 v75, -v3, v98, v75
	v_fma_f32 v50, -v4, v32, v50
	v_fma_f32 v76, -v4, v98, v76
	v_fma_f32 v51, -v5, v32, v51
	v_fma_f32 v77, -v5, v98, v77
	v_fma_f32 v52, -v6, v32, v52
	v_fma_f32 v78, -v6, v98, v78
	v_fma_f32 v53, -v7, v32, v53
	v_fma_f32 v79, -v7, v98, v79
	v_fma_f32 v54, -v8, v32, v54
	v_fma_f32 v105, -v8, v98, v105
	v_fma_f32 v55, -v9, v32, v55
	ds_read_b128 v[2:5], v14 offset:8224
	v_fma_f32 v114, -v9, v98, v114
	ds_read_b128 v[6:9], v14 offset:8240
	ds_read_b128 v[10:13], v14 offset:8256
	ds_read_b128 v[14:17], v14 offset:8272
	s_waitcnt lgkmcnt(0)
	v_fma_f32 v49, -v17, v33, v49
	s_nop 0
	v_fma_f32 v36, -v6, v33, v36
	v_fma_f32 v104, -v6, v97, v104
	v_fma_f32 v34, -v4, v33, v34
	v_fma_f32 v100, -v4, v97, v100
	v_fma_f32 v35, -v5, v33, v35
	s_nop 0
	v_add_u32_e32 v6, s51, v58
	v_mov_b32_e32 v58, 0x500
	v_fma_f32 v99, -v5, v97, v99
	v_fma_f32 v37, -v7, v33, v37
	v_fma_f32 v103, -v7, v97, v103
	v_fma_f32 v38, -v8, v33, v38
	v_fma_f32 v107, -v8, v97, v107
	v_fma_f32 v39, -v9, v33, v39
	v_fma_f32 v106, -v9, v97, v106
	v_fma_f32 v46, -v14, v33, v46
	v_fma_f32 v121, -v14, v97, v121
	ds_read_b128 v[2:5], v6 offset:8288
	ds_read_b128 v[6:9], v6 offset:8304
	v_fma_f32 v40, -v10, v33, v40
	v_fma_f32 v111, -v10, v97, v111
	v_fma_f32 v41, -v11, v33, v41
	v_fma_f32 v110, -v11, v97, v110
	v_fma_f32 v42, -v12, v33, v42
	s_nop 0
	v_add_u32_e32 v14, s51, v58
	v_fma_f32 v113, -v12, v97, v113
	v_fma_f32 v43, -v13, v33, v43
	v_fma_f32 v112, -v13, v97, v112
	v_fma_f32 v47, -v15, v33, v47
	v_fma_f32 v120, -v15, v97, v120
	v_fma_f32 v48, -v16, v33, v48
	v_fma_f32 v123, -v16, v97, v123
	v_fma_f32 v122, -v17, v97, v122
	s_waitcnt lgkmcnt(0)
	v_fma_f32 v44, -v2, v33, v44
	v_fma_f32 v74, -v2, v97, v74
	v_fma_f32 v45, -v3, v33, v45
	v_fma_f32 v75, -v3, v97, v75
	v_fma_f32 v50, -v4, v33, v50
	v_fma_f32 v76, -v4, v97, v76
	v_fma_f32 v51, -v5, v33, v51
	v_fma_f32 v77, -v5, v97, v77
	v_fma_f32 v52, -v6, v33, v52
	v_fma_f32 v78, -v6, v97, v78
	v_fma_f32 v53, -v7, v33, v53
	v_fma_f32 v79, -v7, v97, v79
	v_fma_f32 v54, -v8, v33, v54
	v_fma_f32 v105, -v8, v97, v105
	v_fma_f32 v55, -v9, v33, v55
	ds_read_b128 v[2:5], v14 offset:8224
	v_fma_f32 v114, -v9, v97, v114
	ds_read_b128 v[6:9], v14 offset:8240
	ds_read_b128 v[10:13], v14 offset:8256
	ds_read_b128 v[14:17], v14 offset:8272
	s_waitcnt lgkmcnt(0)
	v_fma_f32 v49, -v17, v34, v49
	s_nop 0
	v_fma_f32 v36, -v6, v34, v36
	v_fma_f32 v104, -v6, v100, v104
	v_fma_f32 v35, -v5, v34, v35
	v_fma_f32 v99, -v5, v100, v99
	v_fma_f32 v37, -v7, v34, v37
	s_nop 0
	v_add_u32_e32 v6, s51, v58
	v_mov_b32_e32 v58, 0x580
	v_fma_f32 v103, -v7, v100, v103
	v_fma_f32 v38, -v8, v34, v38
	v_fma_f32 v107, -v8, v100, v107
	v_fma_f32 v39, -v9, v34, v39
	v_fma_f32 v106, -v9, v100, v106
	v_fma_f32 v46, -v14, v34, v46
	v_fma_f32 v121, -v14, v100, v121
	ds_read_b128 v[2:5], v6 offset:8288
	ds_read_b128 v[6:9], v6 offset:8304
	v_fma_f32 v40, -v10, v34, v40
	v_fma_f32 v111, -v10, v100, v111
	v_fma_f32 v41, -v11, v34, v41
	v_fma_f32 v110, -v11, v100, v110
	v_fma_f32 v42, -v12, v34, v42
	s_nop 0
	v_add_u32_e32 v14, s51, v58
	v_fma_f32 v113, -v12, v100, v113
	v_fma_f32 v43, -v13, v34, v43
	v_fma_f32 v112, -v13, v100, v112
	v_fma_f32 v47, -v15, v34, v47
	v_fma_f32 v120, -v15, v100, v120
	v_fma_f32 v48, -v16, v34, v48
	v_fma_f32 v123, -v16, v100, v123
	v_fma_f32 v122, -v17, v100, v122
	s_waitcnt lgkmcnt(0)
	v_fma_f32 v44, -v2, v34, v44
	v_fma_f32 v74, -v2, v100, v74
	v_fma_f32 v45, -v3, v34, v45
	v_fma_f32 v75, -v3, v100, v75
	v_fma_f32 v50, -v4, v34, v50
	v_fma_f32 v76, -v4, v100, v76
	v_fma_f32 v51, -v5, v34, v51
	v_fma_f32 v77, -v5, v100, v77
	v_fma_f32 v52, -v6, v34, v52
	v_fma_f32 v78, -v6, v100, v78
	v_fma_f32 v53, -v7, v34, v53
	v_fma_f32 v79, -v7, v100, v79
	v_fma_f32 v54, -v8, v34, v54
	v_fma_f32 v105, -v8, v100, v105
	v_fma_f32 v55, -v9, v34, v55
	ds_read_b128 v[2:5], v14 offset:8240
	v_fma_f32 v114, -v9, v100, v114
	ds_read_b128 v[6:9], v14 offset:8256
	ds_read_b128 v[10:13], v14 offset:8272
	ds_read_b128 v[14:17], v14 offset:8288
	s_waitcnt lgkmcnt(0)
	v_fma_f32 v51, -v17, v35, v51
	s_nop 0
	v_fma_f32 v36, -v2, v35, v36
	v_fma_f32 v104, -v2, v99, v104
	v_fma_f32 v37, -v3, v35, v37
	v_fma_f32 v103, -v3, v99, v103
	v_fma_f32 v38, -v4, v35, v38
	s_nop 0
	v_add_u32_e32 v2, s51, v58
	v_mov_b32_e32 v58, 0x600
	v_fma_f32 v107, -v4, v99, v107
	v_fma_f32 v39, -v5, v35, v39
	v_fma_f32 v106, -v5, v99, v106
	v_fma_f32 v44, -v14, v35, v44
	v_fma_f32 v74, -v14, v99, v74
	ds_read_b128 v[2:5], v2 offset:8304
	v_fma_f32 v40, -v6, v35, v40
	v_fma_f32 v111, -v6, v99, v111
	v_fma_f32 v41, -v7, v35, v41
	v_fma_f32 v110, -v7, v99, v110
	v_fma_f32 v42, -v8, v35, v42
	s_nop 0
	v_add_u32_e32 v14, s51, v58
	v_fma_f32 v113, -v8, v99, v113
	v_fma_f32 v43, -v9, v35, v43
	v_fma_f32 v112, -v9, v99, v112
	v_fma_f32 v46, -v10, v35, v46
	v_fma_f32 v121, -v10, v99, v121
	v_fma_f32 v47, -v11, v35, v47
	v_fma_f32 v120, -v11, v99, v120
	v_fma_f32 v48, -v12, v35, v48
	v_fma_f32 v123, -v12, v99, v123
	v_fma_f32 v49, -v13, v35, v49
	v_fma_f32 v122, -v13, v99, v122
	v_fma_f32 v45, -v15, v35, v45
	v_fma_f32 v75, -v15, v99, v75
	v_fma_f32 v50, -v16, v35, v50
	v_fma_f32 v76, -v16, v99, v76
	v_fma_f32 v77, -v17, v99, v77
	s_waitcnt lgkmcnt(0)
	v_fma_f32 v52, -v2, v35, v52
	v_fma_f32 v78, -v2, v99, v78
	v_fma_f32 v53, -v3, v35, v53
	v_fma_f32 v79, -v3, v99, v79
	v_fma_f32 v54, -v4, v35, v54
	v_fma_f32 v105, -v4, v99, v105
	v_fma_f32 v55, -v5, v35, v55
	ds_read_b128 v[6:9], v14 offset:8240
	v_fma_f32 v114, -v5, v99, v114
	ds_read_b128 v[2:5], v14 offset:8256
	ds_read_b128 v[10:13], v14 offset:8272
	ds_read_b128 v[14:17], v14 offset:8288
	s_waitcnt lgkmcnt(0)
	v_fma_f32 v51, -v17, v36, v51
	s_nop 0
	v_fma_f32 v40, -v2, v36, v40
	v_fma_f32 v111, -v2, v104, v111
	v_fma_f32 v37, -v7, v36, v37
	v_fma_f32 v103, -v7, v104, v103
	v_fma_f32 v41, -v3, v36, v41
	s_nop 0
	v_add_u32_e32 v2, s51, v58
	v_mov_b32_e32 v58, 0x680
	v_fma_f32 v110, -v3, v104, v110
	v_fma_f32 v42, -v4, v36, v42
	v_fma_f32 v113, -v4, v104, v113
	v_fma_f32 v43, -v5, v36, v43
	v_fma_f32 v112, -v5, v104, v112
	v_fma_f32 v44, -v14, v36, v44
	v_fma_f32 v74, -v14, v104, v74
	ds_read_b128 v[2:5], v2 offset:8304
	v_fma_f32 v38, -v8, v36, v38
	v_fma_f32 v107, -v8, v104, v107
	v_fma_f32 v39, -v9, v36, v39
	v_fma_f32 v106, -v9, v104, v106
	v_fma_f32 v46, -v10, v36, v46
	s_nop 0
	v_add_u32_e32 v14, s51, v58
	v_fma_f32 v121, -v10, v104, v121
	v_fma_f32 v47, -v11, v36, v47
	v_fma_f32 v120, -v11, v104, v120
	v_fma_f32 v48, -v12, v36, v48
	v_fma_f32 v123, -v12, v104, v123
	v_fma_f32 v49, -v13, v36, v49
	v_fma_f32 v122, -v13, v104, v122
	v_fma_f32 v45, -v15, v36, v45
	v_fma_f32 v75, -v15, v104, v75
	v_fma_f32 v50, -v16, v36, v50
	v_fma_f32 v76, -v16, v104, v76
	v_fma_f32 v77, -v17, v104, v77
	s_waitcnt lgkmcnt(0)
	v_fma_f32 v52, -v2, v36, v52
	v_fma_f32 v78, -v2, v104, v78
	v_fma_f32 v53, -v3, v36, v53
	v_fma_f32 v79, -v3, v104, v79
	v_fma_f32 v54, -v4, v36, v54
	v_fma_f32 v105, -v4, v104, v105
	v_fma_f32 v55, -v5, v36, v55
	ds_read_b128 v[6:9], v14 offset:8240
	v_fma_f32 v114, -v5, v104, v114
	ds_read_b128 v[2:5], v14 offset:8256
	ds_read_b128 v[10:13], v14 offset:8272
	ds_read_b128 v[14:17], v14 offset:8288
	s_waitcnt lgkmcnt(0)
	v_fma_f32 v51, -v17, v37, v51
	s_nop 0
	v_fma_f32 v40, -v2, v37, v40
	v_fma_f32 v111, -v2, v103, v111
	v_fma_f32 v38, -v8, v37, v38
	v_fma_f32 v107, -v8, v103, v107
	v_fma_f32 v41, -v3, v37, v41
	s_nop 0
	v_add_u32_e32 v2, s51, v58
	v_mov_b32_e32 v58, 0x700
	v_fma_f32 v110, -v3, v103, v110
	v_fma_f32 v42, -v4, v37, v42
	v_fma_f32 v113, -v4, v103, v113
	v_fma_f32 v43, -v5, v37, v43
	v_fma_f32 v112, -v5, v103, v112
	v_fma_f32 v44, -v14, v37, v44
	v_fma_f32 v74, -v14, v103, v74
	ds_read_b128 v[2:5], v2 offset:8304
	v_fma_f32 v39, -v9, v37, v39
	v_fma_f32 v106, -v9, v103, v106
	v_fma_f32 v46, -v10, v37, v46
	v_fma_f32 v121, -v10, v103, v121
	v_fma_f32 v47, -v11, v37, v47
	s_nop 0
	v_add_u32_e32 v14, s51, v58
	v_fma_f32 v120, -v11, v103, v120
	v_fma_f32 v48, -v12, v37, v48
	v_fma_f32 v123, -v12, v103, v123
	v_fma_f32 v49, -v13, v37, v49
	v_fma_f32 v122, -v13, v103, v122
	v_fma_f32 v45, -v15, v37, v45
	v_fma_f32 v75, -v15, v103, v75
	v_fma_f32 v50, -v16, v37, v50
	v_fma_f32 v76, -v16, v103, v76
	v_fma_f32 v77, -v17, v103, v77
	s_waitcnt lgkmcnt(0)
	v_fma_f32 v52, -v2, v37, v52
	v_fma_f32 v78, -v2, v103, v78
	v_fma_f32 v53, -v3, v37, v53
	v_fma_f32 v79, -v3, v103, v79
	v_fma_f32 v54, -v4, v37, v54
	v_fma_f32 v105, -v4, v103, v105
	v_fma_f32 v55, -v5, v37, v55
	ds_read_b128 v[6:9], v14 offset:8240
	v_fma_f32 v114, -v5, v103, v114
	ds_read_b128 v[2:5], v14 offset:8256
	ds_read_b128 v[10:13], v14 offset:8272
	ds_read_b128 v[14:17], v14 offset:8288
	s_waitcnt lgkmcnt(0)
	v_fma_f32 v40, -v2, v38, v40
	v_fma_f32 v111, -v2, v107, v111
	v_fma_f32 v51, -v17, v38, v51
	v_fma_f32 v41, -v3, v38, v41
	v_fma_f32 v110, -v3, v107, v110
	v_fma_f32 v42, -v4, v38, v42
	v_fma_f32 v113, -v4, v107, v113
	v_fma_f32 v43, -v5, v38, v43
	s_nop 0
	v_fma_f32 v112, -v5, v107, v112
	v_fma_f32 v39, -v9, v38, v39
	v_fma_f32 v106, -v9, v107, v106
	v_fma_f32 v44, -v14, v38, v44
	v_fma_f32 v74, -v14, v107, v74
	s_nop 0
	v_add_u32_e32 v2, s51, v58
	ds_read_b128 v[2:5], v2 offset:8304
	s_waitcnt lgkmcnt(0)
	v_fma_f32 v52, -v2, v38, v52
	v_fma_f32 v78, -v2, v107, v78
	v_mov_b32_e32 v2, 0x780
	v_fma_f32 v46, -v10, v38, v46
	v_fma_f32 v121, -v10, v107, v121
	v_fma_f32 v47, -v11, v38, v47
	v_fma_f32 v120, -v11, v107, v120
	v_fma_f32 v48, -v12, v38, v48
	s_nop 0
	v_add_u32_e32 v14, s51, v2
	v_fma_f32 v123, -v12, v107, v123
	v_fma_f32 v49, -v13, v38, v49
	v_fma_f32 v122, -v13, v107, v122
	v_fma_f32 v45, -v15, v38, v45
	v_fma_f32 v75, -v15, v107, v75
	v_fma_f32 v50, -v16, v38, v50
	v_fma_f32 v76, -v16, v107, v76
	v_fma_f32 v77, -v17, v107, v77
	v_fma_f32 v53, -v3, v38, v53
	v_fma_f32 v79, -v3, v107, v79
	v_fma_f32 v54, -v4, v38, v54
	v_fma_f32 v105, -v4, v107, v105
	v_fma_f32 v55, -v5, v38, v55
	ds_read_b128 v[6:9], v14 offset:8256
	v_fma_f32 v114, -v5, v107, v114
	ds_read_b128 v[2:5], v14 offset:8272
	ds_read_b128 v[10:13], v14 offset:8288
	ds_read_b128 v[14:17], v14 offset:8304
	s_waitcnt lgkmcnt(0)
	v_fma_f32 v46, -v2, v39, v46
	v_fma_f32 v121, -v2, v106, v121
	v_mov_b32_e32 v2, 0x800
	v_fma_f32 v40, -v6, v39, v40
	v_fma_f32 v111, -v6, v106, v111
	v_fma_f32 v52, -v14, v39, v52
	v_fma_f32 v78, -v14, v106, v78
	v_fma_f32 v41, -v7, v39, v41
	v_fma_f32 v110, -v7, v106, v110
	v_fma_f32 v42, -v8, v39, v42
	s_nop 0
	v_fma_f32 v113, -v8, v106, v113
	v_fma_f32 v43, -v9, v39, v43
	v_fma_f32 v112, -v9, v106, v112
	v_fma_f32 v47, -v3, v39, v47
	v_fma_f32 v120, -v3, v106, v120
	s_nop 0
	v_add_u32_e32 v14, s51, v2
	v_fma_f32 v48, -v4, v39, v48
	v_fma_f32 v123, -v4, v106, v123
	v_fma_f32 v49, -v5, v39, v49
	v_fma_f32 v122, -v5, v106, v122
	v_fma_f32 v44, -v10, v39, v44
	v_fma_f32 v74, -v10, v106, v74
	v_fma_f32 v45, -v11, v39, v45
	v_fma_f32 v75, -v11, v106, v75
	v_fma_f32 v50, -v12, v39, v50
	v_fma_f32 v76, -v12, v106, v76
	v_fma_f32 v51, -v13, v39, v51
	v_fma_f32 v77, -v13, v106, v77
	v_fma_f32 v53, -v15, v39, v53
	v_fma_f32 v79, -v15, v106, v79
	v_fma_f32 v54, -v16, v39, v54
	v_fma_f32 v105, -v16, v106, v105
	v_fma_f32 v55, -v17, v39, v55
	ds_read_b128 v[2:5], v14 offset:8256
	v_fma_f32 v114, -v17, v106, v114
	ds_read_b128 v[6:9], v14 offset:8272
	ds_read_b128 v[10:13], v14 offset:8288
	ds_read_b128 v[14:17], v14 offset:8304
	s_waitcnt lgkmcnt(0)
	v_mov_b32_e32 v2, 0x880
	v_fma_f32 v41, -v3, v40, v41
	v_fma_f32 v110, -v3, v111, v110
	v_fma_f32 v52, -v14, v40, v52
	v_fma_f32 v78, -v14, v111, v78
	s_nop 0
	v_fma_f32 v42, -v4, v40, v42
	v_fma_f32 v113, -v4, v111, v113
	v_fma_f32 v43, -v5, v40, v43
	v_fma_f32 v112, -v5, v111, v112
	v_fma_f32 v46, -v6, v40, v46
	s_nop 0
	v_add_u32_e32 v14, s51, v2
	v_fma_f32 v121, -v6, v111, v121
	v_fma_f32 v47, -v7, v40, v47
	v_fma_f32 v120, -v7, v111, v120
	v_fma_f32 v48, -v8, v40, v48
	v_fma_f32 v123, -v8, v111, v123
	v_fma_f32 v49, -v9, v40, v49
	v_fma_f32 v122, -v9, v111, v122
	v_fma_f32 v44, -v10, v40, v44
	v_fma_f32 v74, -v10, v111, v74
	v_fma_f32 v45, -v11, v40, v45
	v_fma_f32 v75, -v11, v111, v75
	v_fma_f32 v50, -v12, v40, v50
	v_fma_f32 v76, -v12, v111, v76
	v_fma_f32 v51, -v13, v40, v51
	v_fma_f32 v77, -v13, v111, v77
	v_fma_f32 v53, -v15, v40, v53
	v_fma_f32 v79, -v15, v111, v79
	v_fma_f32 v54, -v16, v40, v54
	v_fma_f32 v105, -v16, v111, v105
	v_fma_f32 v55, -v17, v40, v55
	ds_read_b128 v[2:5], v14 offset:8256
	v_fma_f32 v114, -v17, v111, v114
	ds_read_b128 v[6:9], v14 offset:8272
	ds_read_b128 v[10:13], v14 offset:8288
	ds_read_b128 v[14:17], v14 offset:8304
	s_waitcnt lgkmcnt(0)
	v_mov_b32_e32 v2, 0x900
	v_fma_f32 v42, -v4, v41, v42
	v_fma_f32 v113, -v4, v110, v113
	v_fma_f32 v52, -v14, v41, v52
	v_fma_f32 v78, -v14, v110, v78
	s_nop 0
	v_fma_f32 v43, -v5, v41, v43
	v_fma_f32 v112, -v5, v110, v112
	v_fma_f32 v46, -v6, v41, v46
	v_fma_f32 v121, -v6, v110, v121
	v_fma_f32 v47, -v7, v41, v47
	s_nop 0
	v_add_u32_e32 v14, s51, v2
	v_fma_f32 v120, -v7, v110, v120
	v_fma_f32 v48, -v8, v41, v48
	v_fma_f32 v123, -v8, v110, v123
	v_fma_f32 v49, -v9, v41, v49
	v_fma_f32 v122, -v9, v110, v122
	v_fma_f32 v44, -v10, v41, v44
	v_fma_f32 v74, -v10, v110, v74
	v_fma_f32 v45, -v11, v41, v45
	v_fma_f32 v75, -v11, v110, v75
	v_fma_f32 v50, -v12, v41, v50
	v_fma_f32 v76, -v12, v110, v76
	v_fma_f32 v51, -v13, v41, v51
	v_fma_f32 v77, -v13, v110, v77
	v_fma_f32 v53, -v15, v41, v53
	v_fma_f32 v79, -v15, v110, v79
	v_fma_f32 v54, -v16, v41, v54
	v_fma_f32 v105, -v16, v110, v105
	v_fma_f32 v55, -v17, v41, v55
	ds_read_b128 v[2:5], v14 offset:8256
	v_fma_f32 v114, -v17, v110, v114
	ds_read_b128 v[6:9], v14 offset:8272
	ds_read_b128 v[10:13], v14 offset:8288
	ds_read_b128 v[14:17], v14 offset:8304
	s_waitcnt lgkmcnt(0)
	v_mov_b32_e32 v2, 0x980
	v_fma_f32 v43, -v5, v42, v43
	v_fma_f32 v112, -v5, v113, v112
	v_fma_f32 v44, -v10, v42, v44
	v_fma_f32 v74, -v10, v113, v74
	v_fma_f32 v46, -v6, v42, v46
	v_fma_f32 v121, -v6, v113, v121
	v_fma_f32 v47, -v7, v42, v47
	s_nop 0
	v_fma_f32 v120, -v7, v113, v120
	v_fma_f32 v48, -v8, v42, v48
	v_fma_f32 v123, -v8, v113, v123
	v_fma_f32 v49, -v9, v42, v49
	v_fma_f32 v122, -v9, v113, v122
	s_nop 0
	v_add_u32_e32 v10, s51, v2
	v_fma_f32 v45, -v11, v42, v45
	v_fma_f32 v75, -v11, v113, v75
	v_fma_f32 v50, -v12, v42, v50
	v_fma_f32 v76, -v12, v113, v76
	v_fma_f32 v51, -v13, v42, v51
	v_fma_f32 v77, -v13, v113, v77
	ds_read_b128 v[2:5], v10 offset:8272
	ds_read_b128 v[6:9], v10 offset:8288
	ds_read_b128 v[10:13], v10 offset:8304
	v_fma_f32 v52, -v14, v42, v52
	v_fma_f32 v78, -v14, v113, v78
	s_waitcnt lgkmcnt(0)
	v_fma_f32 v46, -v2, v43, v46
	v_fma_f32 v121, -v2, v112, v121
	v_mov_b32_e32 v2, 0xa00
	v_fma_f32 v53, -v15, v42, v53
	v_fma_f32 v79, -v15, v113, v79
	v_fma_f32 v54, -v16, v42, v54
	v_fma_f32 v105, -v16, v113, v105
	v_fma_f32 v55, -v17, v42, v55
	v_fma_f32 v114, -v17, v113, v114
	v_fma_f32 v52, -v10, v43, v52
	v_fma_f32 v78, -v10, v112, v78
	v_fma_f32 v47, -v3, v43, v47
	v_fma_f32 v120, -v3, v112, v120
	v_fma_f32 v48, -v4, v43, v48
	v_fma_f32 v123, -v4, v112, v123
	v_fma_f32 v49, -v5, v43, v49
	s_nop 0
	v_add_u32_e32 v10, s51, v2
	v_fma_f32 v122, -v5, v112, v122
	v_fma_f32 v44, -v6, v43, v44
	v_fma_f32 v74, -v6, v112, v74
	v_fma_f32 v45, -v7, v43, v45
	v_fma_f32 v75, -v7, v112, v75
	v_fma_f32 v50, -v8, v43, v50
	v_fma_f32 v76, -v8, v112, v76
	v_fma_f32 v51, -v9, v43, v51
	v_fma_f32 v77, -v9, v112, v77
	v_fma_f32 v53, -v11, v43, v53
	v_fma_f32 v79, -v11, v112, v79
	v_fma_f32 v54, -v12, v43, v54
	v_fma_f32 v105, -v12, v112, v105
	ds_read_b128 v[2:5], v10 offset:8272
	v_fma_f32 v55, -v13, v43, v55
	v_fma_f32 v114, -v13, v112, v114
	ds_read_b128 v[6:9], v10 offset:8288
	ds_read_b128 v[10:13], v10 offset:8304
	s_waitcnt lgkmcnt(0)
	v_mov_b32_e32 v2, 0xa80
	v_fma_f32 v47, -v3, v46, v47
	v_fma_f32 v120, -v3, v121, v120
	v_fma_f32 v52, -v10, v46, v52
	v_fma_f32 v78, -v10, v121, v78
	s_nop 0
	v_fma_f32 v48, -v4, v46, v48
	v_fma_f32 v123, -v4, v121, v123
	v_fma_f32 v49, -v5, v46, v49
	v_fma_f32 v122, -v5, v121, v122
	v_fma_f32 v44, -v6, v46, v44
	s_nop 0
	v_add_u32_e32 v10, s51, v2
	v_fma_f32 v74, -v6, v121, v74
	v_fma_f32 v45, -v7, v46, v45
	v_fma_f32 v75, -v7, v121, v75
	v_fma_f32 v50, -v8, v46, v50
	v_fma_f32 v76, -v8, v121, v76
	v_fma_f32 v51, -v9, v46, v51
	v_fma_f32 v77, -v9, v121, v77
	v_fma_f32 v53, -v11, v46, v53
	v_fma_f32 v79, -v11, v121, v79
	v_fma_f32 v54, -v12, v46, v54
	v_fma_f32 v105, -v12, v121, v105
	ds_read_b128 v[2:5], v10 offset:8272
	v_fma_f32 v55, -v13, v46, v55
	v_fma_f32 v114, -v13, v121, v114
	ds_read_b128 v[6:9], v10 offset:8288
	ds_read_b128 v[10:13], v10 offset:8304
	s_waitcnt lgkmcnt(0)
	v_mov_b32_e32 v2, 0xb00
	v_fma_f32 v48, -v4, v47, v48
	v_fma_f32 v123, -v4, v120, v123
	v_fma_f32 v52, -v10, v47, v52
	v_fma_f32 v78, -v10, v120, v78
	s_nop 0
	v_fma_f32 v49, -v5, v47, v49
	v_fma_f32 v122, -v5, v120, v122
	v_fma_f32 v44, -v6, v47, v44
	v_fma_f32 v74, -v6, v120, v74
	v_fma_f32 v45, -v7, v47, v45
	s_nop 0
	v_add_u32_e32 v10, s51, v2
	ds_read_b128 v[2:5], v10 offset:8272
	v_fma_f32 v75, -v7, v120, v75
	v_fma_f32 v50, -v8, v47, v50
	v_fma_f32 v76, -v8, v120, v76
	v_fma_f32 v51, -v9, v47, v51
	v_fma_f32 v77, -v9, v120, v77
	ds_read_b128 v[6:9], v10 offset:8288
	s_waitcnt lgkmcnt(0)
	v_mov_b32_e32 v2, 0xb80
	v_fma_f32 v53, -v11, v47, v53
	v_fma_f32 v79, -v11, v120, v79
	v_fma_f32 v54, -v12, v47, v54
	v_fma_f32 v105, -v12, v120, v105
	v_fma_f32 v55, -v13, v47, v55
	v_fma_f32 v114, -v13, v120, v114
	ds_read_b128 v[10:13], v10 offset:8304
	v_fma_f32 v49, -v5, v48, v49
	v_fma_f32 v122, -v5, v123, v122
	v_fma_f32 v44, -v6, v48, v44
	v_fma_f32 v74, -v6, v123, v74
	v_fma_f32 v45, -v7, v48, v45
	v_fma_f32 v75, -v7, v123, v75
	v_fma_f32 v50, -v8, v48, v50
	s_nop 0
	v_fma_f32 v76, -v8, v123, v76
	v_fma_f32 v51, -v9, v48, v51
	v_fma_f32 v77, -v9, v123, v77
	s_waitcnt lgkmcnt(0)
	v_fma_f32 v52, -v10, v48, v52
	v_fma_f32 v78, -v10, v123, v78
	v_add_u32_e32 v6, s51, v2
	ds_read_b128 v[2:5], v6 offset:8288
	ds_read_b128 v[6:9], v6 offset:8304
	s_waitcnt lgkmcnt(0)
	v_fma_f32 v44, -v2, v49, v44
	v_fma_f32 v74, -v2, v122, v74
	v_mov_b32_e32 v2, 0xc00
	v_fma_f32 v52, -v6, v49, v52
	v_fma_f32 v78, -v6, v122, v78
	v_fma_f32 v53, -v11, v48, v53
	v_fma_f32 v79, -v11, v123, v79
	v_fma_f32 v54, -v12, v48, v54
	v_fma_f32 v105, -v12, v123, v105
	v_fma_f32 v55, -v13, v48, v55
	s_nop 0
	v_add_u32_e32 v6, s51, v2
	v_fma_f32 v114, -v13, v123, v114
	v_fma_f32 v45, -v3, v49, v45
	v_fma_f32 v75, -v3, v122, v75
	v_fma_f32 v50, -v4, v49, v50
	v_fma_f32 v76, -v4, v122, v76
	v_fma_f32 v51, -v5, v49, v51
	v_fma_f32 v77, -v5, v122, v77
	ds_read_b128 v[2:5], v6 offset:8288
	v_fma_f32 v53, -v7, v49, v53
	v_fma_f32 v79, -v7, v122, v79
	v_fma_f32 v54, -v8, v49, v54
	v_fma_f32 v105, -v8, v122, v105
	v_fma_f32 v55, -v9, v49, v55
	v_fma_f32 v114, -v9, v122, v114
	ds_read_b128 v[6:9], v6 offset:8304
	s_waitcnt lgkmcnt(0)
	v_mov_b32_e32 v2, 0xc80
	v_fma_f32 v45, -v3, v44, v45
	v_fma_f32 v75, -v3, v74, v75
	v_fma_f32 v52, -v6, v44, v52
	v_fma_f32 v78, -v6, v74, v78
	v_fma_f32 v50, -v4, v44, v50
	v_fma_f32 v76, -v4, v74, v76
	v_fma_f32 v51, -v5, v44, v51
	s_nop 0
	v_fma_f32 v77, -v5, v74, v77
	v_fma_f32 v53, -v7, v44, v53
	v_fma_f32 v79, -v7, v74, v79
	v_fma_f32 v54, -v8, v44, v54
	v_fma_f32 v105, -v8, v74, v105
	s_nop 0
	v_add_u32_e32 v6, s51, v2
	ds_read_b128 v[2:5], v6 offset:8288
	v_fma_f32 v55, -v9, v44, v55
	v_fma_f32 v114, -v9, v74, v114
	ds_read_b128 v[6:9], v6 offset:8304
	s_waitcnt lgkmcnt(0)
	v_mov_b32_e32 v2, 0xd00
	v_fma_f32 v50, -v4, v45, v50
	v_fma_f32 v76, -v4, v75, v76
	v_fma_f32 v52, -v6, v45, v52
	v_fma_f32 v78, -v6, v75, v78
	v_fma_f32 v51, -v5, v45, v51
	v_fma_f32 v77, -v5, v75, v77
	v_fma_f32 v53, -v7, v45, v53
	s_nop 0
	v_fma_f32 v79, -v7, v75, v79
	v_fma_f32 v54, -v8, v45, v54
	v_fma_f32 v105, -v8, v75, v105
	v_fma_f32 v55, -v9, v45, v55
	v_fma_f32 v114, -v9, v75, v114
	s_nop 0
	v_add_u32_e32 v6, s51, v2
	ds_read_b128 v[2:5], v6 offset:8288
	ds_read_b128 v[10:13], v6 offset:8304
	s_waitcnt lgkmcnt(0)
	v_mov_b32_e32 v2, 0xd80
	v_fma_f32 v51, -v5, v50, v51
	v_fma_f32 v77, -v5, v76, v77
	v_fma_f32 v52, -v10, v50, v52
	v_fma_f32 v78, -v10, v76, v78
	v_fma_f32 v53, -v11, v50, v53
	v_fma_f32 v79, -v11, v76, v79
	v_fma_f32 v54, -v12, v50, v54
	s_nop 0
	v_fma_f32 v105, -v12, v76, v105
	v_fma_f32 v55, -v13, v50, v55
	v_fma_f32 v114, -v13, v76, v114
	s_nop 0
	v_add_u32_e32 v2, s51, v2
	ds_read_b128 v[2:5], v2 offset:8304
	s_waitcnt lgkmcnt(0)
	v_fma_f32 v52, -v2, v51, v52
	v_fma_f32 v78, -v2, v77, v78
	v_mov_b32_e32 v2, 0xe00
	v_fma_f32 v53, -v3, v51, v53
	v_fma_f32 v79, -v3, v77, v79
	v_fma_f32 v54, -v4, v51, v54
	v_fma_f32 v105, -v4, v77, v105
	v_fma_f32 v55, -v5, v51, v55
	s_nop 0
	v_add_u32_e32 v2, s51, v2
	ds_read_b128 v[6:9], v2 offset:8304
	v_mov_b32_e32 v2, 0xe80
	s_waitcnt lgkmcnt(0)
; __global__ void __launch_bounds__(NWAVES * 64, 2) mega_fwd(Args args) {
;     ...
;     for (int unit = gw; unit < NB * NH * gdn::NCH; unit += NGW) gdn::pre_unit(unit, P, (const unsigned short*)(ws + WS_PB), in[14], in[15], in[16], REC, L + RING_OFF + wave * 16384, lane);
	v_fma_f32 v53, -v7, v52, v53
	v_fma_f32 v79, -v7, v78, v79
	v_fma_f32 v54, -v8, v52, v54
	v_fma_f32 v105, -v8, v78, v105
	v_fma_f32 v114, -v5, v77, v114
	v_fma_f32 v55, -v9, v52, v55
	v_add_u32_e32 v8, s51, v56
	v_fma_f32 v114, -v9, v78, v114
	s_nop 0
	v_add_u32_e32 v2, s51, v2
	ds_read_b128 v[10:13], v2 offset:8304
	v_mov_b32_e32 v2, 0xf00
	s_waitcnt lgkmcnt(0)
	v_fma_f32 v54, -v12, v53, v54
	v_fma_f32 v105, -v12, v79, v105
	v_fma_f32 v55, -v13, v53, v55
	v_fma_f32 v114, -v13, v79, v114
	s_nop 0
	s_nop 0
	v_add_u32_e32 v2, s51, v2
	ds_read_b128 v[2:5], v2 offset:8304
	s_waitcnt lgkmcnt(0)
	v_lshlrev_b64 v[2:3], 2, v[22:23]
	v_fma_f32 v55, -v5, v54, v55
	v_fma_f32 v114, -v5, v105, v114
	v_lshl_add_u64 v[4:5], s[2:3], 0, v[2:3]
	flat_store_dword v[4:5], v24
	v_lshlrev_b64 v[4:5], 2, v[22:23]
	v_lshl_add_u64 v[6:7], s[2:3], 0, v[4:5]
	s_add_u32 s2, s0, 0x4800
	s_addc_u32 s3, s1, 0
	v_lshl_add_u64 v[2:3], s[2:3], 0, v[2:3]
	flat_store_dword v[6:7], v25 offset:256
	flat_store_dword v[6:7], v26 offset:512
	flat_store_dword v[6:7], v27 offset:768
	flat_store_dword v[6:7], v28 offset:1024
	flat_store_dword v[6:7], v29 offset:1280
	flat_store_dword v[6:7], v30 offset:1536
	flat_store_dword v[6:7], v31 offset:1792
	flat_store_dword v[6:7], v32 offset:2048
	flat_store_dword v[6:7], v33 offset:2304
	flat_store_dword v[6:7], v34 offset:2560
	flat_store_dword v[6:7], v35 offset:2816
	flat_store_dword v[6:7], v36 offset:3072
	flat_store_dword v[6:7], v37 offset:3328
	flat_store_dword v[6:7], v38 offset:3584
	flat_store_dword v[6:7], v39 offset:3840
	flat_store_dword v[2:3], v40
	v_lshl_add_u64 v[2:3], s[2:3], 0, v[4:5]
	flat_store_dword v[2:3], v41 offset:256
	flat_store_dword v[2:3], v42 offset:512
	flat_store_dword v[2:3], v43 offset:768
	flat_store_dword v[2:3], v46 offset:1024
	flat_store_dword v[2:3], v47 offset:1280
	flat_store_dword v[2:3], v48 offset:1536
	flat_store_dword v[2:3], v49 offset:1792
	flat_store_dword v[2:3], v44 offset:2048
	flat_store_dword v[2:3], v45 offset:2304
	flat_store_dword v[2:3], v50 offset:2560
	flat_store_dword v[2:3], v51 offset:2816
	flat_store_dword v[2:3], v52 offset:3072
	flat_store_dword v[2:3], v53 offset:3328
	flat_store_dword v[2:3], v54 offset:3584
	flat_store_dword v[2:3], v55 offset:3840
	v_bfe_u32 v2, v22, 2, 1
	s_mov_b32 s2, 0x7ffffe
	v_and_or_b32 v2, v21, s2, v2
	v_and_b32_e32 v3, 6, v87
	v_and_b32_e32 v4, 8, v22
	v_lshl_add_u32 v2, v2, 9, s51
	v_add3_u32 v2, v2, v4, v3
	v_cvt_pk_bf16_f32 v3, -v88, s0
	s_waitcnt lgkmcnt(0)
	ds_write_b16 v2, v3
	v_cvt_pk_bf16_f32 v3, -v90, s0
	ds_write_b16 v2, v3 offset:16
	v_cvt_pk_bf16_f32 v3, -v89, s0
	ds_write_b16 v2, v3 offset:32
	v_cvt_pk_bf16_f32 v3, -v91, s0
	ds_write_b16 v2, v3 offset:48
	v_cvt_pk_bf16_f32 v3, -v92, s0
	ds_write_b16 v2, v3 offset:64
	v_cvt_pk_bf16_f32 v3, -v93, s0
	ds_write_b16 v2, v3 offset:80
	v_cvt_pk_bf16_f32 v3, -v94, s0
	ds_write_b16 v2, v3 offset:96
	v_cvt_pk_bf16_f32 v3, -v95, s0
	ds_write_b16 v2, v3 offset:112
	v_cvt_pk_bf16_f32 v3, -v98, s0
	ds_write_b16 v2, v3 offset:128
	v_cvt_pk_bf16_f32 v3, -v97, s0
	ds_write_b16 v2, v3 offset:144
	v_cvt_pk_bf16_f32 v3, -v100, s0
	ds_write_b16 v2, v3 offset:160
	v_cvt_pk_bf16_f32 v3, -v99, s0
	ds_write_b16 v2, v3 offset:176
	v_cvt_pk_bf16_f32 v3, -v104, s0
	ds_write_b16 v2, v3 offset:192
	v_cvt_pk_bf16_f32 v3, -v103, s0
	ds_write_b16 v2, v3 offset:208
	v_cvt_pk_bf16_f32 v3, -v107, s0
	ds_write_b16 v2, v3 offset:224
	v_cvt_pk_bf16_f32 v3, -v106, s0
	ds_write_b16 v2, v3 offset:240
	v_cvt_pk_bf16_f32 v3, -v111, s0
	ds_write_b16 v2, v3 offset:256
	v_cvt_pk_bf16_f32 v3, -v110, s0
	ds_write_b16 v2, v3 offset:272
	v_cvt_pk_bf16_f32 v3, -v113, s0
	ds_write_b16 v2, v3 offset:288
	v_cvt_pk_bf16_f32 v3, -v112, s0
	ds_write_b16 v2, v3 offset:304
	v_cvt_pk_bf16_f32 v3, -v121, s0
	ds_write_b16 v2, v3 offset:320
	v_cvt_pk_bf16_f32 v3, -v120, s0
	ds_write_b16 v2, v3 offset:336
	v_cvt_pk_bf16_f32 v3, -v123, s0
	ds_write_b16 v2, v3 offset:352
	v_cvt_pk_bf16_f32 v3, -v122, s0
	ds_write_b16 v2, v3 offset:368
	v_cvt_pk_bf16_f32 v3, -v74, s0
	ds_write_b16 v2, v3 offset:384
	v_cvt_pk_bf16_f32 v3, -v75, s0
	ds_write_b16 v2, v3 offset:400
	v_cvt_pk_bf16_f32 v3, -v76, s0
	ds_write_b16 v2, v3 offset:416
	v_cvt_pk_bf16_f32 v3, -v77, s0
	ds_write_b16 v2, v3 offset:432
	v_cvt_pk_bf16_f32 v3, -v78, s0
	ds_write_b16 v2, v3 offset:448
	v_cvt_pk_bf16_f32 v3, -v79, s0
	ds_write_b16 v2, v3 offset:464
	v_cvt_pk_bf16_f32 v3, -v105, s0
	ds_write_b16 v2, v3 offset:480
	v_cvt_pk_bf16_f32 v3, -v114, s0
	ds_write_b16 v2, v3 offset:496
	s_waitcnt lgkmcnt(0)
	ds_read_b128 v[2:5], v8
	v_lshl_add_u64 v[6:7], s[0:1], 0, v[56:57]
	v_readlane_b32 s3, v245, 63
	s_add_i32 s76, s76, s3
	s_add_i32 s10, s10, s11
	s_waitcnt lgkmcnt(0)
	flat_store_dwordx4 v[6:7], v[2:5]
	ds_read_b128 v[2:5], v8 offset:1024
	s_mul_i32 s2, s3, 0x5a00
	s_add_u32 s0, s0, s2
	s_mul_hi_i32 s2, s3, 0x5a00
	s_addc_u32 s1, s1, s2
	s_waitcnt lgkmcnt(0)
	flat_store_dwordx4 v[6:7], v[2:5] offset:1024
	ds_read_b128 v[2:5], v8 offset:2048
	s_cmpk_gt_i32 s76, 0xfff
	s_waitcnt lgkmcnt(0)
	flat_store_dwordx4 v[6:7], v[2:5] offset:2048
	ds_read_b128 v[2:5], v8 offset:3072
	s_waitcnt lgkmcnt(0)
	flat_store_dwordx4 v[6:7], v[2:5] offset:3072
	s_waitcnt lgkmcnt(0)
	s_cbranch_scc1 .LBB0_1077
